# attention loops: s_setprio 1/0 bracketing every run of 32x32x16 MFMAs (on top of the trimmed GEMM loop)
# speedup vs baseline: 1.0062x; 1.0048x over previous
.LBB0_397:
	s_or_b64 exec, exec, s[0:1]
	v_ashrrev_i32_e32 v19, 4, v18
	v_and_b32_e32 v4, 0xfffff0, v19
	v_lshlrev_b32_e32 v5, 1, v19
	v_and_or_b32 v4, v5, 8, v4
	v_lshrrev_b32_e32 v5, 1, v19
	v_and_b32_e32 v6, 3, v19
	v_bfe_u32 v2, v18, 5, 1
	s_ashr_i32 s51, s52, 1
	v_and_or_b32 v5, v5, 4, v6
	v_add_u32_e32 v6, 32, v19
	v_and_b32_e32 v205, 31, v18
	s_andn2_b32 s51, s51, 31
	v_lshlrev_b32_e32 v206, 2, v2
	v_and_b32_e32 v7, 0xfffff0, v6
	v_lshlrev_b32_e32 v8, 1, v6
	s_add_i32 s0, s51, 0x100000
	v_sub_u32_e32 v3, v205, v206
	v_lshlrev_b32_e32 v200, 4, v2
	v_lshlrev_b32_e32 v2, 3, v18
	v_and_or_b32 v7, v8, 8, v7
	v_add_u32_e32 v207, s0, v3
	v_and_b32_e32 v3, 0x78, v2
	v_lshrrev_b32_e32 v4, 1, v4
	v_bfe_u32 v2, v2, 5, 2
	v_lshrrev_b32_e32 v7, 1, v7
	v_or_b32_e32 v4, v4, v2
	v_lshlrev_b32_e32 v20, 1, v3
	v_or_b32_e32 v2, v7, v2
	v_lshlrev_b32_e32 v4, 9, v4
	v_lshlrev_b32_e32 v5, 6, v5
	v_and_b32_e32 v3, 48, v20
	v_lshlrev_b32_e32 v2, 9, v2
	v_or3_b32 v4, v4, v5, v3
	v_or3_b32 v2, v2, v5, v3
	v_add_u32_e32 v201, 0, v4
	v_add_u32_e32 v213, 0, v2
	s_waitcnt lgkmcnt(0)
	s_barrier
	s_barrier
	ds_write_b128 v201, v[166:169]
	ds_write_b128 v213, v[170:173]
	s_add_u32 s0, s48, 0x20000
	s_addc_u32 s1, s49, 0
	v_lshl_or_b32 v198, v19, 10, v20
	v_lshl_or_b32 v202, v6, 10, v20
	global_load_dwordx4 v[2:5], v198, s[0:1]
	global_load_dwordx4 v[6:9], v202, s[0:1]
	s_add_u32 s0, s46, 0x20000
	s_addc_u32 s1, s47, 0
	global_load_dwordx4 v[10:13], v198, s[0:1]
	global_load_dwordx4 v[14:17], v202, s[0:1]
	s_cmp_gt_i32 s51, 0xfff000a0
	v_lshlrev_b32_e32 v29, 4, v205
	s_mov_b64 s[0:1], -1
	v_add_u32_e32 v222, s13, v200
	v_lshlrev_b32_e32 v21, 8, v205
	v_and_b32_e32 v24, 0x70, v29
	v_bitop3_b32 v22, v200, v29, s12 bitop3:0x78
	s_cbranch_scc0 .LBB0_402
	v_lshlrev_b32_e32 v23, 8, v205
	v_bitop3_b32 v25, v200, v29, s12 bitop3:0x78
	v_add3_u32 v34, 0, v25, v23
	ds_read_b128 v[26:29], v34 offset:32768
	ds_read_b128 v[114:117], v222 offset:768
	ds_read_b128 v[118:121], v222 offset:800
	ds_read_b128 v[122:125], v222 offset:832
	ds_read_b128 v[126:129], v222 offset:864
	ds_read_b128 v[98:101], v222 offset:896
	ds_read_b128 v[30:33], v34 offset:40960
	ds_read_b128 v[102:105], v222 offset:928
	ds_read_b128 v[106:109], v222 offset:960
	ds_read_b128 v[110:113], v222 offset:992
	s_waitcnt vmcnt(11) lgkmcnt(5)
	s_setprio 1
	v_mfma_f32_32x32x16_bf16 v[114:129], v[26:29], v[162:165], v[114:129]
	v_bitop3_b32 v26, v200, v24, 32 bitop3:0x36
	v_add3_u32 v35, 0, v26, v23
	v_bitop3_b32 v27, v200, v24, 64 bitop3:0x36
	v_add3_u32 v36, 0, v27, v23
	s_cmp_gt_i32 s51, 0xfff000fe
	s_waitcnt lgkmcnt(0)
	v_mfma_f32_32x32x16_bf16 v[98:113], v[30:33], v[162:165], v[98:113]
	ds_read_b128 v[28:31], v35 offset:32768
	s_waitcnt vmcnt(10) lgkmcnt(0)
	v_mfma_f32_32x32x16_bf16 v[114:129], v[28:31], v[158:161], v[114:129]
	ds_read_b128 v[28:31], v35 offset:40960
	s_waitcnt lgkmcnt(0)
	v_mfma_f32_32x32x16_bf16 v[98:113], v[28:31], v[158:161], v[98:113]
	ds_read_b128 v[28:31], v36 offset:32768
	s_waitcnt vmcnt(9) lgkmcnt(0)
	v_mfma_f32_32x32x16_bf16 v[114:129], v[28:31], v[154:157], v[114:129]
	ds_read_b128 v[30:33], v36 offset:40960
	v_bitop3_b32 v28, v200, v24, s14 bitop3:0x36
	v_add3_u32 v29, 0, v28, v23
	s_waitcnt lgkmcnt(0)
	v_mfma_f32_32x32x16_bf16 v[98:113], v[30:33], v[154:157], v[98:113]
	ds_read_b128 v[30:33], v29 offset:32768
	s_waitcnt vmcnt(8) lgkmcnt(0)
	v_mfma_f32_32x32x16_bf16 v[114:129], v[30:33], v[150:153], v[114:129]
	ds_read_b128 v[30:33], v29 offset:40960
	s_waitcnt lgkmcnt(0)
	v_mfma_f32_32x32x16_bf16 v[98:113], v[30:33], v[150:153], v[98:113]
	ds_read_b128 v[30:33], v34 offset:32896
	s_waitcnt vmcnt(7) lgkmcnt(0)
	v_mfma_f32_32x32x16_bf16 v[114:129], v[30:33], v[142:145], v[114:129]
	ds_read_b128 v[30:33], v34 offset:41088
	s_waitcnt lgkmcnt(0)
	v_mfma_f32_32x32x16_bf16 v[98:113], v[30:33], v[142:145], v[98:113]
	ds_read_b128 v[30:33], v35 offset:32896
	s_waitcnt vmcnt(6) lgkmcnt(0)
	v_mfma_f32_32x32x16_bf16 v[114:129], v[30:33], v[138:141], v[114:129]
	ds_read_b128 v[30:33], v35 offset:41088
	s_waitcnt lgkmcnt(0)
	v_mfma_f32_32x32x16_bf16 v[98:113], v[30:33], v[138:141], v[98:113]
	ds_read_b128 v[30:33], v36 offset:32896
	s_waitcnt vmcnt(5) lgkmcnt(0)
	v_mfma_f32_32x32x16_bf16 v[114:129], v[30:33], v[134:137], v[114:129]
	ds_read_b128 v[30:33], v36 offset:41088
	s_waitcnt lgkmcnt(0)
	v_mfma_f32_32x32x16_bf16 v[98:113], v[30:33], v[134:137], v[98:113]
	ds_read_b128 v[30:33], v29 offset:32896
	s_waitcnt vmcnt(4) lgkmcnt(0)
	v_mfma_f32_32x32x16_bf16 v[114:129], v[30:33], v[130:133], v[114:129]
	ds_read_b128 v[30:33], v29 offset:41088
	s_waitcnt lgkmcnt(0)
	v_mfma_f32_32x32x16_bf16 v[98:113], v[30:33], v[130:133], v[98:113]
	s_setprio 0
	s_cbranch_scc1 .LBB0_400
	v_add_u32_e32 v29, 0xbfffff40, v207
	v_cmp_lt_u32_e32 vcc, s15, v29
	v_add_u32_e32 v29, 0xbfffff20, v207
	s_nop 4
	v_cndmask_b32_e32 v114, v1, v114, vcc
	v_cmp_lt_u32_e32 vcc, s15, v29
	v_add_u32_e32 v29, 0xbfffff3f, v207
	s_nop 0
	v_cndmask_b32_e32 v98, v1, v98, vcc
	v_cmp_lt_u32_e32 vcc, s15, v29
	v_add_u32_e32 v29, 0xbfffff1f, v207
	s_nop 0
	v_cndmask_b32_e32 v115, v1, v115, vcc
	v_cmp_lt_u32_e32 vcc, s15, v29
	v_add_u32_e32 v29, 0xbfffff3e, v207
	s_nop 0
	v_cndmask_b32_e32 v99, v1, v99, vcc
	v_cmp_lt_u32_e32 vcc, s15, v29
	v_add_u32_e32 v29, 0xbfffff1e, v207
	s_nop 0
	v_cndmask_b32_e32 v116, v1, v116, vcc
	v_cmp_lt_u32_e32 vcc, s15, v29
	v_add_u32_e32 v29, 0xbfffff3d, v207
	s_nop 0
	v_cndmask_b32_e32 v100, v1, v100, vcc
	v_cmp_lt_u32_e32 vcc, s15, v29
	v_add_u32_e32 v29, 0xbfffff1d, v207
	s_nop 0
	v_cndmask_b32_e32 v117, v1, v117, vcc
	v_cmp_lt_u32_e32 vcc, s15, v29
	v_add_u32_e32 v29, 0xbfffff38, v207
	s_nop 0
	v_cndmask_b32_e32 v101, v1, v101, vcc
	v_cmp_lt_u32_e32 vcc, s15, v29
	v_add_u32_e32 v29, 0xbfffff18, v207
	s_nop 0
	v_cndmask_b32_e32 v118, v1, v118, vcc
	v_cmp_lt_u32_e32 vcc, s15, v29
	v_add_u32_e32 v29, 0xbfffff37, v207
	s_nop 0
	v_cndmask_b32_e32 v102, v1, v102, vcc
	v_cmp_lt_u32_e32 vcc, s15, v29
	v_add_u32_e32 v29, 0xbfffff17, v207
	s_nop 0
	v_cndmask_b32_e32 v119, v1, v119, vcc
	v_cmp_lt_u32_e32 vcc, s15, v29
	v_add_u32_e32 v29, 0xbfffff36, v207
	s_nop 0
	v_cndmask_b32_e32 v103, v1, v103, vcc
	v_cmp_lt_u32_e32 vcc, s15, v29
	v_add_u32_e32 v29, 0xbfffff16, v207
	s_nop 0
	v_cndmask_b32_e32 v120, v1, v120, vcc
	v_cmp_lt_u32_e32 vcc, s15, v29
	v_add_u32_e32 v29, 0xbfffff35, v207
	s_nop 0
	v_cndmask_b32_e32 v104, v1, v104, vcc
	v_cmp_lt_u32_e32 vcc, s15, v29
	v_add_u32_e32 v29, 0xbfffff15, v207
	s_nop 0
	v_cndmask_b32_e32 v121, v1, v121, vcc
	v_cmp_lt_u32_e32 vcc, s15, v29
	v_add_u32_e32 v29, 0xbfffff30, v207
	s_nop 0
	v_cndmask_b32_e32 v105, v1, v105, vcc
	v_cmp_lt_u32_e32 vcc, s15, v29
	v_add_u32_e32 v29, 0xbfffff10, v207
	s_nop 0
	v_cndmask_b32_e32 v122, v1, v122, vcc
	v_cmp_lt_u32_e32 vcc, s15, v29
	v_add_u32_e32 v29, 0xbfffff2f, v207
	s_nop 0
	v_cndmask_b32_e32 v106, v1, v106, vcc
	v_cmp_lt_u32_e32 vcc, s15, v29
	v_add_u32_e32 v29, 0xbfffff0f, v207
	s_nop 0
	v_cndmask_b32_e32 v123, v1, v123, vcc
	v_cmp_lt_u32_e32 vcc, s15, v29
	v_add_u32_e32 v29, 0xbfffff2e, v207
	s_nop 0
	v_cndmask_b32_e32 v107, v1, v107, vcc
	v_cmp_lt_u32_e32 vcc, s15, v29
	v_add_u32_e32 v29, 0xbfffff0e, v207
	s_nop 0
	v_cndmask_b32_e32 v124, v1, v124, vcc
	v_cmp_lt_u32_e32 vcc, s15, v29
	v_add_u32_e32 v29, 0xbfffff2d, v207
	s_nop 0
	v_cndmask_b32_e32 v108, v1, v108, vcc
	v_cmp_lt_u32_e32 vcc, s15, v29
	v_add_u32_e32 v29, 0xbfffff0d, v207
	s_nop 0
	v_cndmask_b32_e32 v125, v1, v125, vcc
	v_cmp_lt_u32_e32 vcc, s15, v29
	v_add_u32_e32 v29, 0xbfffff28, v207
	s_nop 0
	v_cndmask_b32_e32 v109, v1, v109, vcc
	v_cmp_lt_u32_e32 vcc, s15, v29
	v_add_u32_e32 v29, 0xbfffff08, v207
	s_nop 0
	v_cndmask_b32_e32 v126, v1, v126, vcc
	v_cmp_lt_u32_e32 vcc, s15, v29
	v_add_u32_e32 v29, 0xbfffff27, v207
	s_nop 0
	v_cndmask_b32_e32 v110, v1, v110, vcc
	v_cmp_lt_u32_e32 vcc, s15, v29
	v_add_u32_e32 v29, 0xbfffff07, v207
	s_nop 0
	v_cndmask_b32_e32 v127, v1, v127, vcc
	v_cmp_lt_u32_e32 vcc, s15, v29
	v_add_u32_e32 v29, 0xbfffff26, v207
	s_nop 0
	v_cndmask_b32_e32 v111, v1, v111, vcc
	v_cmp_lt_u32_e32 vcc, s15, v29
	v_add_u32_e32 v29, 0xbfffff06, v207
	s_nop 0
	v_cndmask_b32_e32 v128, v1, v128, vcc
	v_cmp_lt_u32_e32 vcc, s15, v29
	v_add_u32_e32 v29, 0xbfffff25, v207
	s_nop 0
	v_cndmask_b32_e32 v112, v1, v112, vcc
	v_cmp_lt_u32_e32 vcc, s15, v29
	v_add_u32_e32 v29, 0xbfffff05, v207
	s_nop 0
	v_cndmask_b32_e32 v129, v1, v129, vcc
	v_cmp_lt_u32_e32 vcc, s15, v29
	s_nop 1
	v_cndmask_b32_e32 v113, v1, v113, vcc

.LBB0_404:
	v_lshlrev_b32_e32 v19, 8, v19
	v_and_b32_e32 v21, 0x70, v18
	s_waitcnt vmcnt(0)
	v_bitop3_b32 v19, v20, v19, v21 bitop3:0xde
	v_mov_b32_e32 v203, v199
	v_add_u32_e32 v208, 0, v19
	s_waitcnt vmcnt(3)
	ds_write_b128 v201, v[2:5] offset:16384
	s_waitcnt vmcnt(2)
	ds_write_b128 v213, v[6:9] offset:16384
	s_waitcnt vmcnt(1)
	ds_write_b128 v208, v[10:13] offset:49152
	s_waitcnt vmcnt(0)
	ds_write_b128 v208, v[14:17] offset:57344
	s_waitcnt lgkmcnt(0)
	s_barrier
	v_add_u32_e32 v6, 0, v25
	v_add_u32_e32 v7, 0, v26
	v_add_u32_e32 v8, 0, v27
	v_add_u32_e32 v9, 0, v28
	s_add_u32 s0, s48, 0x10000
	s_addc_u32 s1, s49, 0
	v_lshl_add_u64 v[2:3], s[0:1], 0, v[198:199]
	v_lshl_add_u64 v[4:5], s[0:1], 0, v[202:203]
	s_add_u32 s0, s46, 0x10000
	s_addc_u32 s1, s47, 0
	global_load_dwordx4 v[182:185], v[2:3], off
	global_load_dwordx4 v[186:189], v[4:5], off
	v_lshl_add_u64 v[2:3], s[0:1], 0, v[198:199]
	v_lshl_add_u64 v[4:5], s[0:1], 0, v[202:203]
	global_load_dwordx4 v[194:197], v[2:3], off
	global_load_dwordx4 v[190:193], v[4:5], off
	s_cmp_gt_i32 s51, 0xfff00060
	s_cselect_b64 s[0:1], -1, 0
	s_cmp_lt_i32 s51, 0xfff00061
	v_add_u32_e32 v220, v6, v23
	v_add_u32_e32 v219, v7, v23
	v_add_u32_e32 v218, v8, v23
	v_add_u32_e32 v217, v9, v23
	s_cbranch_scc1 .LBB0_406
	ds_read_b128 v[2:5], v220 offset:49152
	ds_read_b128 v[82:85], v222 offset:512
	ds_read_b128 v[86:89], v222 offset:544
	ds_read_b128 v[90:93], v222 offset:576
	ds_read_b128 v[94:97], v222 offset:608
	ds_read_b128 v[66:69], v222 offset:640
	ds_read_b128 v[6:9], v220 offset:57344
	ds_read_b128 v[70:73], v222 offset:672
	ds_read_b128 v[74:77], v222 offset:704
	ds_read_b128 v[78:81], v222 offset:736
	s_waitcnt lgkmcnt(5)
	s_setprio 1
	v_mfma_f32_32x32x16_bf16 v[82:97], v[2:5], v[162:165], v[82:97]
	ds_read_b128 v[2:5], v219 offset:49152
	s_waitcnt lgkmcnt(1)
	v_mfma_f32_32x32x16_bf16 v[66:81], v[6:9], v[162:165], v[66:81]
	s_waitcnt lgkmcnt(0)
	v_mfma_f32_32x32x16_bf16 v[82:97], v[2:5], v[158:161], v[82:97]
	ds_read_b128 v[2:5], v219 offset:57344
	s_waitcnt lgkmcnt(0)
	v_mfma_f32_32x32x16_bf16 v[66:81], v[2:5], v[158:161], v[66:81]
	ds_read_b128 v[2:5], v218 offset:49152
	s_waitcnt lgkmcnt(0)
	v_mfma_f32_32x32x16_bf16 v[82:97], v[2:5], v[154:157], v[82:97]
	ds_read_b128 v[2:5], v218 offset:57344
	s_waitcnt lgkmcnt(0)
	v_mfma_f32_32x32x16_bf16 v[66:81], v[2:5], v[154:157], v[66:81]
	ds_read_b128 v[2:5], v217 offset:49152
	s_waitcnt lgkmcnt(0)
	v_mfma_f32_32x32x16_bf16 v[82:97], v[2:5], v[150:153], v[82:97]
	ds_read_b128 v[2:5], v217 offset:57344
	s_waitcnt lgkmcnt(0)
	v_mfma_f32_32x32x16_bf16 v[66:81], v[2:5], v[150:153], v[66:81]
	ds_read_b128 v[2:5], v220 offset:49280
	s_waitcnt lgkmcnt(0)
	v_mfma_f32_32x32x16_bf16 v[82:97], v[2:5], v[142:145], v[82:97]
	ds_read_b128 v[2:5], v220 offset:57472
	s_waitcnt lgkmcnt(0)
	v_mfma_f32_32x32x16_bf16 v[66:81], v[2:5], v[142:145], v[66:81]
	ds_read_b128 v[2:5], v219 offset:49280
	s_waitcnt lgkmcnt(0)
	v_mfma_f32_32x32x16_bf16 v[82:97], v[2:5], v[138:141], v[82:97]
	ds_read_b128 v[2:5], v219 offset:57472
	s_waitcnt lgkmcnt(0)
	v_mfma_f32_32x32x16_bf16 v[66:81], v[2:5], v[138:141], v[66:81]
	ds_read_b128 v[2:5], v218 offset:49280
	s_waitcnt lgkmcnt(0)
	v_mfma_f32_32x32x16_bf16 v[82:97], v[2:5], v[134:137], v[82:97]
	ds_read_b128 v[2:5], v218 offset:57472
	s_waitcnt lgkmcnt(0)
	v_mfma_f32_32x32x16_bf16 v[66:81], v[2:5], v[134:137], v[66:81]
	ds_read_b128 v[2:5], v217 offset:49280
	s_waitcnt lgkmcnt(0)
	v_mfma_f32_32x32x16_bf16 v[82:97], v[2:5], v[130:133], v[82:97]
	ds_read_b128 v[2:5], v217 offset:57472
	s_waitcnt lgkmcnt(0)
	v_mfma_f32_32x32x16_bf16 v[66:81], v[2:5], v[130:133], v[66:81]
	s_setprio 0
	s_branch .LBB0_407

.LBB0_409:
.LBB0_410:
	v_and_b32_e32 v214, 63, v18
	v_lshlrev_b32_e32 v3, 4, v214
	v_lshlrev_b32_e32 v2, 3, v214
	v_and_b32_e32 v3, 0xc0, v3
	v_lshlrev_b32_e32 v4, 1, v214
	v_and_or_b32 v3, v2, 24, v3
	v_and_b32_e32 v4, 32, v4
	v_and_b32_e32 v2, 0x100, v2
	s_cmp_lg_u32 0, -1
	v_or3_b32 v2, v3, v4, v2
	s_cselect_b32 s40, 0, 0
	v_add_u32_e32 v211, s40, v2
	s_and_b64 vcc, exec, s[38:39]
	s_cbranch_vccnz .LBB0_413
	ds_read_b64_tr_b16 v[2:3], v211 offset:0
	ds_read_b64_tr_b16 v[4:5], v211 offset:0x800
	ds_read_b64_tr_b16 v[18:19], v211 offset:0x1000
	ds_read_b64_tr_b16 v[20:21], v211 offset:0x1800
	ds_read_b64_tr_b16 v[22:23], v211 offset:0x2000
	ds_read_b64_tr_b16 v[24:25], v211 offset:0x2800
	ds_read_b64_tr_b16 v[26:27], v211 offset:0x3000
	ds_read_b64_tr_b16 v[28:29], v211 offset:0x3800
	s_waitcnt lgkmcnt(0)
	s_nop 0
	s_setprio 1
	v_mfma_f32_32x32x16_bf16 v[2:17], v[166:169], v[2:5], 0
	v_mfma_f32_32x32x16_bf16 v[2:17], v[170:173], v[18:21], v[2:17]
	s_setprio 0
	ds_read_b64_tr_b16 v[18:19], v211 offset:0x200
	ds_read_b64_tr_b16 v[20:21], v211 offset:0xa00
	ds_read_b64_tr_b16 v[34:35], v211 offset:0x1200
	ds_read_b64_tr_b16 v[36:37], v211 offset:0x1a00
	ds_read_b64_tr_b16 v[38:39], v211 offset:0x2200
	ds_read_b64_tr_b16 v[40:41], v211 offset:0x2a00
	ds_read_b64_tr_b16 v[42:43], v211 offset:0x3200
	s_setprio 1
	v_mfma_f32_32x32x16_bf16 v[2:17], v[174:177], v[22:25], v[2:17]
	ds_read_b64_tr_b16 v[44:45], v211 offset:0x3a00
	s_waitcnt lgkmcnt(0)
	v_mfma_f32_32x32x16_bf16 v[2:17], v[178:181], v[26:29], v[2:17]
	v_mfma_f32_32x32x16_bf16 v[18:33], v[166:169], v[18:21], 0
	v_mfma_f32_32x32x16_bf16 v[18:33], v[170:173], v[34:37], v[18:33]
	s_setprio 0
	ds_read_b64_tr_b16 v[34:35], v211 offset:0x400
	ds_read_b64_tr_b16 v[36:37], v211 offset:0xc00
	ds_read_b64_tr_b16 v[50:51], v211 offset:0x1400
	ds_read_b64_tr_b16 v[52:53], v211 offset:0x1c00
	ds_read_b64_tr_b16 v[54:55], v211 offset:0x2400
	ds_read_b64_tr_b16 v[56:57], v211 offset:0x2c00
	ds_read_b64_tr_b16 v[58:59], v211 offset:0x3400
	s_setprio 1
	v_mfma_f32_32x32x16_bf16 v[18:33], v[174:177], v[38:41], v[18:33]
	ds_read_b64_tr_b16 v[60:61], v211 offset:0x3c00
	s_waitcnt lgkmcnt(0)
	v_mfma_f32_32x32x16_bf16 v[18:33], v[178:181], v[42:45], v[18:33]
	v_mfma_f32_32x32x16_bf16 v[34:49], v[166:169], v[34:37], 0
	v_mfma_f32_32x32x16_bf16 v[34:49], v[170:173], v[50:53], v[34:49]
	s_setprio 0
	ds_read_b64_tr_b16 v[50:51], v211 offset:0x600
	ds_read_b64_tr_b16 v[52:53], v211 offset:0xe00
	ds_read_b64_tr_b16 v[224:225], v211 offset:0x1600
	ds_read_b64_tr_b16 v[226:227], v211 offset:0x1e00
	ds_read_b64_tr_b16 v[228:229], v211 offset:0x2600
	ds_read_b64_tr_b16 v[230:231], v211 offset:0x2e00
	ds_read_b64_tr_b16 v[232:233], v211 offset:0x3600
	s_setprio 1
	v_mfma_f32_32x32x16_bf16 v[34:49], v[174:177], v[54:57], v[34:49]
	ds_read_b64_tr_b16 v[234:235], v211 offset:0x3e00
	s_waitcnt lgkmcnt(0)
	v_mfma_f32_32x32x16_bf16 v[34:49], v[178:181], v[58:61], v[34:49]
	v_mfma_f32_32x32x16_bf16 v[50:65], v[166:169], v[50:53], 0
	v_mfma_f32_32x32x16_bf16 v[50:65], v[170:173], v[224:227], v[50:65]
	v_mfma_f32_32x32x16_bf16 v[50:65], v[174:177], v[228:231], v[50:65]
	v_mfma_f32_32x32x16_bf16 v[50:65], v[178:181], v[232:235], v[50:65]
	s_setprio 0
	s_andn2_b64 vcc, exec, s[0:1]
	s_mov_b64 s[0:1], 0
	s_cbranch_vccz .LBB0_414

.LBB0_425:
	s_waitcnt lgkmcnt(0)
	s_barrier
	v_lshl_add_u64 v[182:183], s[48:49], 0, v[198:199]
	v_lshl_add_u64 v[184:185], s[48:49], 0, v[202:203]
	global_load_dwordx4 v[186:189], v[182:183], off
	global_load_dwordx4 v[190:193], v[184:185], off
	v_lshl_add_u64 v[182:183], s[46:47], 0, v[198:199]
	v_lshl_add_u64 v[184:185], s[46:47], 0, v[202:203]
	global_load_dwordx4 v[194:197], v[182:183], off
	s_nop 0
	global_load_dwordx4 v[182:185], v[184:185], off
	s_cmp_gt_i32 s51, 0xfff00020
	s_cselect_b64 s[0:1], -1, 0
	s_cmp_lt_i32 s51, 0xfff00021
	s_cbranch_scc1 .LBB0_427
	ds_read_b128 v[102:105], v220 offset:32768
	ds_read_b128 v[114:117], v222 offset:256
	ds_read_b128 v[118:121], v222 offset:288
	ds_read_b128 v[122:125], v222 offset:320
	ds_read_b128 v[126:129], v222 offset:352
	ds_read_b128 v[98:101], v222 offset:384
	ds_read_b128 v[224:227], v220 offset:40960
	s_waitcnt lgkmcnt(2)
	s_setprio 1
	v_mfma_f32_32x32x16_bf16 v[114:129], v[102:105], v[162:165], v[114:129]
	ds_read_b128 v[102:105], v222 offset:416
	ds_read_b128 v[106:109], v222 offset:448
	ds_read_b128 v[110:113], v222 offset:480
	s_waitcnt lgkmcnt(0)
	v_mfma_f32_32x32x16_bf16 v[98:113], v[224:227], v[162:165], v[98:113]
	ds_read_b128 v[222:225], v219 offset:32768
	s_waitcnt lgkmcnt(0)
	v_mfma_f32_32x32x16_bf16 v[114:129], v[222:225], v[158:161], v[114:129]
	ds_read_b128 v[222:225], v219 offset:40960
	s_waitcnt lgkmcnt(0)
	v_mfma_f32_32x32x16_bf16 v[98:113], v[222:225], v[158:161], v[98:113]
	ds_read_b128 v[222:225], v218 offset:32768
	s_waitcnt lgkmcnt(0)
	v_mfma_f32_32x32x16_bf16 v[114:129], v[222:225], v[154:157], v[114:129]
	ds_read_b128 v[222:225], v218 offset:40960
	s_waitcnt lgkmcnt(0)
	v_mfma_f32_32x32x16_bf16 v[98:113], v[222:225], v[154:157], v[98:113]
	ds_read_b128 v[222:225], v217 offset:32768
	s_waitcnt lgkmcnt(0)
	v_mfma_f32_32x32x16_bf16 v[114:129], v[222:225], v[150:153], v[114:129]
	ds_read_b128 v[222:225], v217 offset:40960
	s_waitcnt lgkmcnt(0)
	v_mfma_f32_32x32x16_bf16 v[98:113], v[222:225], v[150:153], v[98:113]
	ds_read_b128 v[222:225], v220 offset:32896
	s_waitcnt lgkmcnt(0)
	v_mfma_f32_32x32x16_bf16 v[114:129], v[222:225], v[142:145], v[114:129]
	ds_read_b128 v[222:225], v220 offset:41088
	s_waitcnt lgkmcnt(0)
	v_mfma_f32_32x32x16_bf16 v[98:113], v[222:225], v[142:145], v[98:113]
	ds_read_b128 v[222:225], v219 offset:32896
	s_waitcnt lgkmcnt(0)
	v_mfma_f32_32x32x16_bf16 v[114:129], v[222:225], v[138:141], v[114:129]
	ds_read_b128 v[222:225], v219 offset:41088
	s_waitcnt lgkmcnt(0)
	v_mfma_f32_32x32x16_bf16 v[98:113], v[222:225], v[138:141], v[98:113]
	ds_read_b128 v[222:225], v218 offset:32896
	s_waitcnt lgkmcnt(0)
	v_mfma_f32_32x32x16_bf16 v[114:129], v[222:225], v[134:137], v[114:129]
	ds_read_b128 v[222:225], v218 offset:41088
	s_waitcnt lgkmcnt(0)
	v_mfma_f32_32x32x16_bf16 v[98:113], v[222:225], v[134:137], v[98:113]
	ds_read_b128 v[222:225], v217 offset:32896
	s_waitcnt lgkmcnt(0)
	v_mfma_f32_32x32x16_bf16 v[114:129], v[222:225], v[130:133], v[114:129]
	ds_read_b128 v[222:225], v217 offset:41088
	s_waitcnt lgkmcnt(0)
	v_mfma_f32_32x32x16_bf16 v[98:113], v[222:225], v[130:133], v[98:113]
	s_setprio 0

.LBB0_429:
	s_and_b64 vcc, exec, s[40:41]
	s_cbranch_vccnz .LBB0_431
	ds_read_b64_tr_b16 v[222:223], v211 offset:0x4000
	ds_read_b64_tr_b16 v[224:225], v211 offset:0x4800
	ds_read_b64_tr_b16 v[226:227], v211 offset:0x5000
	ds_read_b64_tr_b16 v[228:229], v211 offset:0x5800
	ds_read_b64_tr_b16 v[230:231], v211 offset:0x6000
	ds_read_b64_tr_b16 v[232:233], v211 offset:0x6800
	ds_read_b64_tr_b16 v[234:235], v211 offset:0x7000
	ds_read_b64_tr_b16 v[236:237], v211 offset:0x7800
	s_waitcnt lgkmcnt(0)
	s_nop 0
	s_setprio 1
	v_mfma_f32_32x32x16_bf16 v[2:17], v[166:169], v[222:225], v[2:17]
	ds_read_b64_tr_b16 v[222:223], v211 offset:0x4200
	ds_read_b64_tr_b16 v[224:225], v211 offset:0x4a00
	v_mfma_f32_32x32x16_bf16 v[2:17], v[170:173], v[226:229], v[2:17]
	ds_read_b64_tr_b16 v[226:227], v211 offset:0x5200
	ds_read_b64_tr_b16 v[228:229], v211 offset:0x5a00
	v_mfma_f32_32x32x16_bf16 v[2:17], v[174:177], v[230:233], v[2:17]
	ds_read_b64_tr_b16 v[230:231], v211 offset:0x6200
	ds_read_b64_tr_b16 v[232:233], v211 offset:0x6a00
	v_mfma_f32_32x32x16_bf16 v[2:17], v[178:181], v[234:237], v[2:17]
	ds_read_b64_tr_b16 v[234:235], v211 offset:0x7200
	ds_read_b64_tr_b16 v[236:237], v211 offset:0x7a00
	s_waitcnt lgkmcnt(0)
	v_mfma_f32_32x32x16_bf16 v[18:33], v[166:169], v[222:225], v[18:33]
	ds_read_b64_tr_b16 v[222:223], v211 offset:0x4400
	ds_read_b64_tr_b16 v[224:225], v211 offset:0x4c00
	v_mfma_f32_32x32x16_bf16 v[18:33], v[170:173], v[226:229], v[18:33]
	ds_read_b64_tr_b16 v[226:227], v211 offset:0x5400
	ds_read_b64_tr_b16 v[228:229], v211 offset:0x5c00
	v_mfma_f32_32x32x16_bf16 v[18:33], v[174:177], v[230:233], v[18:33]
	ds_read_b64_tr_b16 v[230:231], v211 offset:0x6400
	ds_read_b64_tr_b16 v[232:233], v211 offset:0x6c00
	v_mfma_f32_32x32x16_bf16 v[18:33], v[178:181], v[234:237], v[18:33]
	ds_read_b64_tr_b16 v[234:235], v211 offset:0x7400
	ds_read_b64_tr_b16 v[236:237], v211 offset:0x7c00
	s_waitcnt lgkmcnt(0)
	v_mfma_f32_32x32x16_bf16 v[34:49], v[166:169], v[222:225], v[34:49]
	ds_read_b64_tr_b16 v[222:223], v211 offset:0x4600
	ds_read_b64_tr_b16 v[224:225], v211 offset:0x4e00
	v_mfma_f32_32x32x16_bf16 v[34:49], v[170:173], v[226:229], v[34:49]
	ds_read_b64_tr_b16 v[226:227], v211 offset:0x5600
	ds_read_b64_tr_b16 v[228:229], v211 offset:0x5e00
	v_mfma_f32_32x32x16_bf16 v[34:49], v[174:177], v[230:233], v[34:49]
	ds_read_b64_tr_b16 v[230:231], v211 offset:0x6600
	ds_read_b64_tr_b16 v[232:233], v211 offset:0x6e00
	v_mfma_f32_32x32x16_bf16 v[34:49], v[178:181], v[234:237], v[34:49]
	ds_read_b64_tr_b16 v[234:235], v211 offset:0x7600
	ds_read_b64_tr_b16 v[236:237], v211 offset:0x7e00
	s_waitcnt lgkmcnt(0)
	v_mfma_f32_32x32x16_bf16 v[50:65], v[166:169], v[222:225], v[50:65]
	v_mfma_f32_32x32x16_bf16 v[50:65], v[170:173], v[226:229], v[50:65]
	v_mfma_f32_32x32x16_bf16 v[50:65], v[174:177], v[230:233], v[50:65]
	v_mfma_f32_32x32x16_bf16 v[50:65], v[178:181], v[234:237], v[50:65]
	s_setprio 0

.LBB0_442:
	s_waitcnt lgkmcnt(0)
	s_barrier
	s_cmp_gt_i32 s51, 0xffefffe0
	s_cselect_b64 s[0:1], -1, 0
	s_cmp_lt_i32 s51, 0xffefffe1
	s_cbranch_scc1 .LBB0_444
	v_add_u32_e32 v66, 0, v200
	v_add_u32_e32 v78, 0x10800, v66
	ds_read_b128 v[70:73], v220 offset:49152
	ds_read_b128 v[82:85], v78
	ds_read_b128 v[86:89], v78 offset:32
	ds_read_b128 v[90:93], v78 offset:64
	ds_read_b128 v[94:97], v78 offset:96
	ds_read_b128 v[166:169], v220 offset:57344
	ds_read_b128 v[66:69], v78 offset:128
	s_waitcnt lgkmcnt(2)
	s_setprio 1
	v_mfma_f32_32x32x16_bf16 v[82:97], v[70:73], v[162:165], v[82:97]
	ds_read_b128 v[70:73], v78 offset:160
	ds_read_b128 v[74:77], v78 offset:192
	ds_read_b128 v[78:81], v78 offset:224
	s_waitcnt lgkmcnt(0)
	v_mfma_f32_32x32x16_bf16 v[66:81], v[166:169], v[162:165], v[66:81]
	ds_read_b128 v[162:165], v219 offset:49152
	s_waitcnt lgkmcnt(0)
	v_mfma_f32_32x32x16_bf16 v[82:97], v[162:165], v[158:161], v[82:97]
	ds_read_b128 v[162:165], v219 offset:57344
	s_waitcnt lgkmcnt(0)
	v_mfma_f32_32x32x16_bf16 v[66:81], v[162:165], v[158:161], v[66:81]
	ds_read_b128 v[158:161], v218 offset:49152
	s_waitcnt lgkmcnt(0)
	v_mfma_f32_32x32x16_bf16 v[82:97], v[158:161], v[154:157], v[82:97]
	ds_read_b128 v[158:161], v218 offset:57344
	s_waitcnt lgkmcnt(0)
	v_mfma_f32_32x32x16_bf16 v[66:81], v[158:161], v[154:157], v[66:81]
	ds_read_b128 v[154:157], v217 offset:49152
	s_waitcnt lgkmcnt(0)
	v_mfma_f32_32x32x16_bf16 v[82:97], v[154:157], v[150:153], v[82:97]
	ds_read_b128 v[154:157], v217 offset:57344
	s_waitcnt lgkmcnt(0)
	v_mfma_f32_32x32x16_bf16 v[66:81], v[154:157], v[150:153], v[66:81]
	ds_read_b128 v[150:153], v220 offset:49280
	s_waitcnt lgkmcnt(0)
	v_mfma_f32_32x32x16_bf16 v[82:97], v[150:153], v[142:145], v[82:97]
	ds_read_b128 v[150:153], v220 offset:57472
	s_waitcnt lgkmcnt(0)
	v_mfma_f32_32x32x16_bf16 v[66:81], v[150:153], v[142:145], v[66:81]
	ds_read_b128 v[142:145], v219 offset:49280
	s_waitcnt lgkmcnt(0)
	v_mfma_f32_32x32x16_bf16 v[82:97], v[142:145], v[138:141], v[82:97]
	ds_read_b128 v[142:145], v219 offset:57472
	s_waitcnt lgkmcnt(0)
	v_mfma_f32_32x32x16_bf16 v[66:81], v[142:145], v[138:141], v[66:81]
	ds_read_b128 v[138:141], v218 offset:49280
	s_waitcnt lgkmcnt(0)
	v_mfma_f32_32x32x16_bf16 v[82:97], v[138:141], v[134:137], v[82:97]
	ds_read_b128 v[138:141], v218 offset:57472
	s_waitcnt lgkmcnt(0)
	v_mfma_f32_32x32x16_bf16 v[66:81], v[138:141], v[134:137], v[66:81]
	ds_read_b128 v[134:137], v217 offset:49280
	s_waitcnt lgkmcnt(0)
	v_mfma_f32_32x32x16_bf16 v[82:97], v[134:137], v[130:133], v[82:97]
	ds_read_b128 v[134:137], v217 offset:57472
	s_waitcnt lgkmcnt(0)
	v_mfma_f32_32x32x16_bf16 v[66:81], v[134:137], v[130:133], v[66:81]
	s_setprio 0
.LBB0_444:
	s_add_u32 s46, s28, 0x30000
	s_addc_u32 s47, s29, 0
	v_lshl_add_u64 v[130:131], s[46:47], 0, v[198:199]
	v_lshl_add_u64 v[132:133], s[46:47], 0, v[202:203]
	s_add_u32 s46, s26, 0x30000
	s_addc_u32 s47, s27, 0
	global_load_dwordx4 v[166:169], v[130:131], off
	global_load_dwordx4 v[170:173], v[132:133], off
	v_lshl_add_u64 v[130:131], s[46:47], 0, v[198:199]
	v_lshl_add_u64 v[132:133], s[46:47], 0, v[202:203]
	global_load_dwordx4 v[174:177], v[130:131], off
	global_load_dwordx4 v[178:181], v[132:133], off
	s_add_i32 s46, s25, -1
	v_mov_b32_e32 v130, s46
	v_bitop3_b32 v198, s51, v130, v205 bitop3:0xc8
	v_lshlrev_b64 v[130:131], 10, v[198:199]
	v_lshl_add_u64 v[130:131], s[22:23], 0, v[130:131]
	v_mov_b32_e32 v201, v199
	v_lshl_add_u64 v[130:131], v[130:131], 0, v[200:201]
	global_load_dwordx4 v[162:165], v[130:131], off
	global_load_dwordx4 v[158:161], v[130:131], off offset:32
	global_load_dwordx4 v[154:157], v[130:131], off offset:64
	global_load_dwordx4 v[150:153], v[130:131], off offset:96
	global_load_dwordx4 v[142:145], v[130:131], off offset:128
	global_load_dwordx4 v[138:141], v[130:131], off offset:160
	global_load_dwordx4 v[134:137], v[130:131], off offset:192
	s_nop 0
	global_load_dwordx4 v[130:133], v[130:131], off offset:224
	s_and_b64 vcc, exec, s[40:41]
	s_cbranch_vccnz .LBB0_446
	v_exp_f32_e32 v182, v98
	v_add_f32_e32 v98, 0, v114
	v_add_f32_e32 v98, v115, v98
	v_add_f32_e32 v98, v116, v98
	v_add_f32_e32 v98, v117, v98
	v_add_f32_e32 v98, v118, v98
	v_add_f32_e32 v98, v119, v98
	v_add_f32_e32 v98, v120, v98
	v_add_f32_e32 v98, v121, v98
	v_add_f32_e32 v98, v122, v98
	v_add_f32_e32 v98, v123, v98
	v_add_f32_e32 v98, v124, v98
	v_add_f32_e32 v98, v125, v98
	v_add_f32_e32 v98, v126, v98
	v_exp_f32_e32 v183, v99
	v_add_f32_e32 v98, v127, v98
	v_exp_f32_e32 v184, v100
	v_add_f32_e32 v98, v128, v98
	v_exp_f32_e32 v185, v101
	v_add_f32_e32 v98, v129, v98
	v_exp_f32_e32 v186, v102
	v_add_f32_e32 v98, v182, v98
	v_exp_f32_e32 v187, v103
	v_add_f32_e32 v98, v183, v98
	v_exp_f32_e32 v188, v104
	v_add_f32_e32 v98, v184, v98
	v_exp_f32_e32 v189, v105
	v_add_f32_e32 v98, v185, v98
	v_exp_f32_e32 v190, v106
	v_add_f32_e32 v98, v186, v98
	v_exp_f32_e32 v191, v107
	v_add_f32_e32 v98, v187, v98
	v_exp_f32_e32 v192, v108
	v_add_f32_e32 v98, v188, v98
	v_exp_f32_e32 v193, v109
	v_add_f32_e32 v98, v189, v98
	v_exp_f32_e32 v194, v110
	v_add_f32_e32 v98, v190, v98
	v_exp_f32_e32 v195, v111
	v_add_f32_e32 v98, v191, v98
	v_exp_f32_e32 v196, v112
	v_add_f32_e32 v98, v192, v98
	v_exp_f32_e32 v113, v113
	v_add_f32_e32 v98, v193, v98
	v_add_f32_e32 v98, v194, v98
	v_add_f32_e32 v98, v195, v98
	v_add_f32_e32 v98, v196, v98
	v_add_f32_e32 v98, v113, v98
	v_mov_b32_e32 v99, v98
	s_nop 1
	v_permlane32_swap_b32_e32 v98, v99
	v_add_f32_e32 v197, v98, v99
	v_cvt_pk_bf16_f32 v98, v114, v115
	v_cvt_pk_bf16_f32 v99, v116, v117
	v_cvt_pk_bf16_f32 v100, v118, v119
	v_cvt_pk_bf16_f32 v101, v120, v121
	v_cvt_pk_bf16_f32 v102, v122, v123
	v_cvt_pk_bf16_f32 v103, v124, v125
	v_cvt_pk_bf16_f32 v104, v126, v127
	v_cvt_pk_bf16_f32 v105, v128, v129
	v_cvt_pk_bf16_f32 v106, v182, v183
	v_cvt_pk_bf16_f32 v107, v184, v185
	v_cvt_pk_bf16_f32 v108, v186, v187
	v_cvt_pk_bf16_f32 v109, v188, v189
	v_cvt_pk_bf16_f32 v110, v190, v191
	v_cvt_pk_bf16_f32 v111, v192, v193
	v_cvt_pk_bf16_f32 v112, v194, v195
	v_cvt_pk_bf16_f32 v113, v196, v113
	v_fmac_f32_e32 v197, v212, v216
	v_permlane32_swap_b32_e32 v98, v100
	v_permlane32_swap_b32_e32 v99, v101
	v_permlane32_swap_b32_e32 v102, v104
	v_permlane32_swap_b32_e32 v103, v105
	v_permlane32_swap_b32_e32 v106, v108
	v_permlane32_swap_b32_e32 v107, v109
	v_permlane32_swap_b32_e32 v110, v112
	v_permlane32_swap_b32_e32 v111, v113
	ds_read_b64_tr_b16 v[114:115], v211 offset:0
	ds_read_b64_tr_b16 v[116:117], v211 offset:0x800
	ds_read_b64_tr_b16 v[118:119], v211 offset:0x1000
	ds_read_b64_tr_b16 v[120:121], v211 offset:0x1800
	ds_read_b64_tr_b16 v[122:123], v211 offset:0x2000
	ds_read_b64_tr_b16 v[124:125], v211 offset:0x2800
	ds_read_b64_tr_b16 v[126:127], v211 offset:0x3000
	ds_read_b64_tr_b16 v[128:129], v211 offset:0x3800
	s_waitcnt lgkmcnt(0)
	s_nop 0
	s_setprio 1
	v_mfma_f32_32x32x16_bf16 v[2:17], v[98:101], v[114:117], v[2:17]
	ds_read_b64_tr_b16 v[114:115], v211 offset:0x200
	ds_read_b64_tr_b16 v[116:117], v211 offset:0xa00
	v_mfma_f32_32x32x16_bf16 v[2:17], v[102:105], v[118:121], v[2:17]
	ds_read_b64_tr_b16 v[118:119], v211 offset:0x1200
	ds_read_b64_tr_b16 v[120:121], v211 offset:0x1a00
	v_mfma_f32_32x32x16_bf16 v[2:17], v[106:109], v[122:125], v[2:17]
	ds_read_b64_tr_b16 v[122:123], v211 offset:0x2200
	ds_read_b64_tr_b16 v[124:125], v211 offset:0x2a00
	v_mfma_f32_32x32x16_bf16 v[2:17], v[110:113], v[126:129], v[2:17]
	ds_read_b64_tr_b16 v[126:127], v211 offset:0x3200
	ds_read_b64_tr_b16 v[128:129], v211 offset:0x3a00
	s_waitcnt lgkmcnt(0)
	v_mfma_f32_32x32x16_bf16 v[18:33], v[98:101], v[114:117], v[18:33]
	ds_read_b64_tr_b16 v[114:115], v211 offset:0x400
	ds_read_b64_tr_b16 v[116:117], v211 offset:0xc00
	v_mfma_f32_32x32x16_bf16 v[18:33], v[102:105], v[118:121], v[18:33]
	ds_read_b64_tr_b16 v[118:119], v211 offset:0x1400
	ds_read_b64_tr_b16 v[120:121], v211 offset:0x1c00
	v_mfma_f32_32x32x16_bf16 v[18:33], v[106:109], v[122:125], v[18:33]
	ds_read_b64_tr_b16 v[122:123], v211 offset:0x2400
	ds_read_b64_tr_b16 v[124:125], v211 offset:0x2c00
	v_mfma_f32_32x32x16_bf16 v[18:33], v[110:113], v[126:129], v[18:33]
	ds_read_b64_tr_b16 v[126:127], v211 offset:0x3400
	ds_read_b64_tr_b16 v[128:129], v211 offset:0x3c00
	s_waitcnt lgkmcnt(0)
	v_mfma_f32_32x32x16_bf16 v[34:49], v[98:101], v[114:117], v[34:49]
	ds_read_b64_tr_b16 v[114:115], v211 offset:0x600
	ds_read_b64_tr_b16 v[116:117], v211 offset:0xe00
	v_mfma_f32_32x32x16_bf16 v[34:49], v[102:105], v[118:121], v[34:49]
	ds_read_b64_tr_b16 v[118:119], v211 offset:0x1600
	ds_read_b64_tr_b16 v[120:121], v211 offset:0x1e00
	v_mfma_f32_32x32x16_bf16 v[34:49], v[106:109], v[122:125], v[34:49]
	ds_read_b64_tr_b16 v[122:123], v211 offset:0x2600
	ds_read_b64_tr_b16 v[124:125], v211 offset:0x2e00
	v_mfma_f32_32x32x16_bf16 v[34:49], v[110:113], v[126:129], v[34:49]
	ds_read_b64_tr_b16 v[126:127], v211 offset:0x3600
	ds_read_b64_tr_b16 v[128:129], v211 offset:0x3e00
	s_waitcnt lgkmcnt(0)
	v_mfma_f32_32x32x16_bf16 v[50:65], v[98:101], v[114:117], v[50:65]
	v_mov_b32_e32 v212, v197
	v_mfma_f32_32x32x16_bf16 v[50:65], v[102:105], v[118:121], v[50:65]
	v_mfma_f32_32x32x16_bf16 v[50:65], v[106:109], v[122:125], v[50:65]
	v_mfma_f32_32x32x16_bf16 v[50:65], v[110:113], v[126:129], v[50:65]
	s_setprio 0

.LBB0_457:
	v_exp_f32_e32 v98, v66
	v_add_f32_e32 v66, 0, v82
	v_add_f32_e32 v66, v83, v66
	v_add_f32_e32 v66, v84, v66
	v_add_f32_e32 v66, v85, v66
	v_add_f32_e32 v66, v86, v66
	v_add_f32_e32 v66, v87, v66
	v_add_f32_e32 v66, v88, v66
	v_add_f32_e32 v66, v89, v66
	v_add_f32_e32 v66, v90, v66
	v_add_f32_e32 v66, v91, v66
	v_add_f32_e32 v66, v92, v66
	v_add_f32_e32 v66, v93, v66
	v_add_f32_e32 v66, v94, v66
	v_exp_f32_e32 v99, v67
	v_add_f32_e32 v66, v95, v66
	v_exp_f32_e32 v100, v68
	v_add_f32_e32 v66, v96, v66
	v_exp_f32_e32 v101, v69
	v_add_f32_e32 v66, v97, v66
	v_exp_f32_e32 v102, v70
	v_add_f32_e32 v66, v98, v66
	v_exp_f32_e32 v103, v71
	v_add_f32_e32 v66, v99, v66
	v_exp_f32_e32 v104, v72
	v_add_f32_e32 v66, v100, v66
	v_exp_f32_e32 v105, v73
	v_add_f32_e32 v66, v101, v66
	v_exp_f32_e32 v106, v74
	v_add_f32_e32 v66, v102, v66
	v_exp_f32_e32 v107, v75
	v_add_f32_e32 v66, v103, v66
	v_exp_f32_e32 v108, v76
	v_add_f32_e32 v66, v104, v66
	v_exp_f32_e32 v109, v77
	v_add_f32_e32 v66, v105, v66
	v_exp_f32_e32 v110, v78
	v_add_f32_e32 v66, v106, v66
	v_exp_f32_e32 v111, v79
	v_add_f32_e32 v66, v107, v66
	v_exp_f32_e32 v112, v80
	v_add_f32_e32 v66, v108, v66
	v_exp_f32_e32 v81, v81
	v_add_f32_e32 v66, v109, v66
	v_add_f32_e32 v66, v110, v66
	v_add_f32_e32 v66, v111, v66
	v_add_f32_e32 v66, v112, v66
	v_add_f32_e32 v66, v81, v66
	v_mov_b32_e32 v67, v66
	s_nop 1
	v_permlane32_swap_b32_e32 v66, v67
	v_add_f32_e32 v113, v66, v67
	v_cvt_pk_bf16_f32 v66, v82, v83
	v_cvt_pk_bf16_f32 v67, v84, v85
	v_cvt_pk_bf16_f32 v68, v86, v87
	v_cvt_pk_bf16_f32 v69, v88, v89
	v_cvt_pk_bf16_f32 v70, v90, v91
	v_cvt_pk_bf16_f32 v71, v92, v93
	v_cvt_pk_bf16_f32 v72, v94, v95
	v_cvt_pk_bf16_f32 v73, v96, v97
	v_cvt_pk_bf16_f32 v74, v98, v99
	v_cvt_pk_bf16_f32 v75, v100, v101
	v_cvt_pk_bf16_f32 v76, v102, v103
	v_cvt_pk_bf16_f32 v77, v104, v105
	v_cvt_pk_bf16_f32 v78, v106, v107
	v_cvt_pk_bf16_f32 v79, v108, v109
	v_cvt_pk_bf16_f32 v80, v110, v111
	v_cvt_pk_bf16_f32 v81, v112, v81
	v_fmac_f32_e32 v113, v212, v221
	v_permlane32_swap_b32_e32 v66, v68
	v_permlane32_swap_b32_e32 v67, v69
	v_permlane32_swap_b32_e32 v70, v72
	v_permlane32_swap_b32_e32 v71, v73
	v_permlane32_swap_b32_e32 v74, v76
	v_permlane32_swap_b32_e32 v75, v77
	v_permlane32_swap_b32_e32 v78, v80
	v_permlane32_swap_b32_e32 v79, v81
	ds_read_b64_tr_b16 v[82:83], v211 offset:0x4000
	ds_read_b64_tr_b16 v[84:85], v211 offset:0x4800
	ds_read_b64_tr_b16 v[86:87], v211 offset:0x5000
	ds_read_b64_tr_b16 v[88:89], v211 offset:0x5800
	ds_read_b64_tr_b16 v[90:91], v211 offset:0x6000
	ds_read_b64_tr_b16 v[92:93], v211 offset:0x6800
	ds_read_b64_tr_b16 v[94:95], v211 offset:0x7000
	ds_read_b64_tr_b16 v[96:97], v211 offset:0x7800
	s_waitcnt lgkmcnt(0)
	s_nop 0
	s_setprio 1
	v_mfma_f32_32x32x16_bf16 v[2:17], v[66:69], v[82:85], v[2:17]
	ds_read_b64_tr_b16 v[82:83], v211 offset:0x4200
	ds_read_b64_tr_b16 v[84:85], v211 offset:0x4a00
	v_mfma_f32_32x32x16_bf16 v[2:17], v[70:73], v[86:89], v[2:17]
	ds_read_b64_tr_b16 v[86:87], v211 offset:0x5200
	ds_read_b64_tr_b16 v[88:89], v211 offset:0x5a00
	v_mfma_f32_32x32x16_bf16 v[2:17], v[74:77], v[90:93], v[2:17]
	ds_read_b64_tr_b16 v[90:91], v211 offset:0x6200
	ds_read_b64_tr_b16 v[92:93], v211 offset:0x6a00
	v_mfma_f32_32x32x16_bf16 v[2:17], v[78:81], v[94:97], v[2:17]
	ds_read_b64_tr_b16 v[94:95], v211 offset:0x7200
	ds_read_b64_tr_b16 v[96:97], v211 offset:0x7a00
	s_waitcnt lgkmcnt(0)
	v_mfma_f32_32x32x16_bf16 v[18:33], v[66:69], v[82:85], v[18:33]
	ds_read_b64_tr_b16 v[82:83], v211 offset:0x4400
	ds_read_b64_tr_b16 v[84:85], v211 offset:0x4c00
	v_mfma_f32_32x32x16_bf16 v[18:33], v[70:73], v[86:89], v[18:33]
	ds_read_b64_tr_b16 v[86:87], v211 offset:0x5400
	ds_read_b64_tr_b16 v[88:89], v211 offset:0x5c00
	v_mfma_f32_32x32x16_bf16 v[18:33], v[74:77], v[90:93], v[18:33]
	ds_read_b64_tr_b16 v[90:91], v211 offset:0x6400
	ds_read_b64_tr_b16 v[92:93], v211 offset:0x6c00
	v_mfma_f32_32x32x16_bf16 v[18:33], v[78:81], v[94:97], v[18:33]
	ds_read_b64_tr_b16 v[94:95], v211 offset:0x7400
	ds_read_b64_tr_b16 v[96:97], v211 offset:0x7c00
	s_waitcnt lgkmcnt(0)
	v_mfma_f32_32x32x16_bf16 v[34:49], v[66:69], v[82:85], v[34:49]
	ds_read_b64_tr_b16 v[82:83], v211 offset:0x4600
	ds_read_b64_tr_b16 v[84:85], v211 offset:0x4e00
	v_mfma_f32_32x32x16_bf16 v[34:49], v[70:73], v[86:89], v[34:49]
	ds_read_b64_tr_b16 v[86:87], v211 offset:0x5600
	ds_read_b64_tr_b16 v[88:89], v211 offset:0x5e00
	v_mfma_f32_32x32x16_bf16 v[34:49], v[74:77], v[90:93], v[34:49]
	ds_read_b64_tr_b16 v[90:91], v211 offset:0x6600
	ds_read_b64_tr_b16 v[92:93], v211 offset:0x6e00
	v_mfma_f32_32x32x16_bf16 v[34:49], v[78:81], v[94:97], v[34:49]
	ds_read_b64_tr_b16 v[94:95], v211 offset:0x7600
	ds_read_b64_tr_b16 v[96:97], v211 offset:0x7e00
	s_waitcnt lgkmcnt(0)
	v_mfma_f32_32x32x16_bf16 v[50:65], v[66:69], v[82:85], v[50:65]
	v_mov_b32_e32 v212, v113
	v_mfma_f32_32x32x16_bf16 v[50:65], v[70:73], v[86:89], v[50:65]
	v_mfma_f32_32x32x16_bf16 v[50:65], v[74:77], v[90:93], v[50:65]
	v_mfma_f32_32x32x16_bf16 v[50:65], v[78:81], v[94:97], v[50:65]
	s_setprio 0

.LBB0_1129:
	s_andn2_b64 vcc, exec, s[0:1]
	s_cbranch_vccnz .LBB0_1125
	s_and_b32 s62, s61, 1
	v_add_u32_e32 v5, 0, v214
	s_cmp_eq_u32 s62, 0
	v_add_u32_e32 v12, 0x14800, v5
	v_add_u32_e32 v9, 0x14880, v5
	v_add_u32_e32 v13, 0x14820, v5
	v_add_u32_e32 v4, 0x148a0, v5
	v_add_u32_e32 v10, 0x14840, v5
	v_add_u32_e32 v7, 0x148c0, v5
	v_add_u32_e32 v11, 0x14860, v5
	v_add_u32_e32 v8, 0x148e0, v5
	s_mov_b64 s[0:1], -1
	s_cbranch_scc1 .LBB0_1135
	ds_read_b128 v[14:17], v229 offset:49152
	ds_read_b128 v[146:149], v12
	ds_read_b128 v[150:153], v13
	ds_read_b128 v[154:157], v10
	ds_read_b128 v[158:161], v11
	ds_read_b128 v[162:165], v9
	ds_read_b128 v[82:85], v229 offset:57344
	ds_read_b128 v[166:169], v4
	ds_read_b128 v[170:173], v7
	ds_read_b128 v[174:177], v8
	s_cmp_le_i32 s54, s52
	s_waitcnt lgkmcnt(0)
	s_setprio 1
	v_mfma_f32_32x32x16_bf16 v[146:161], v[14:17], v[178:181], v[146:161]
	ds_read_b128 v[14:17], v230 offset:49152
	s_waitcnt lgkmcnt(1)
	v_mfma_f32_32x32x16_bf16 v[162:177], v[82:85], v[178:181], v[162:177]
	s_waitcnt lgkmcnt(0)
	v_mfma_f32_32x32x16_bf16 v[146:161], v[14:17], v[182:185], v[146:161]
	ds_read_b128 v[14:17], v230 offset:57344
	s_waitcnt lgkmcnt(0)
	v_mfma_f32_32x32x16_bf16 v[162:177], v[14:17], v[182:185], v[162:177]
	ds_read_b128 v[14:17], v231 offset:49152
	s_waitcnt lgkmcnt(0)
	v_mfma_f32_32x32x16_bf16 v[146:161], v[14:17], v[186:189], v[146:161]
	ds_read_b128 v[14:17], v231 offset:57344
	s_waitcnt lgkmcnt(0)
	v_mfma_f32_32x32x16_bf16 v[162:177], v[14:17], v[186:189], v[162:177]
	ds_read_b128 v[14:17], v232 offset:49152
	s_waitcnt lgkmcnt(0)
	v_mfma_f32_32x32x16_bf16 v[146:161], v[14:17], v[190:193], v[146:161]
	ds_read_b128 v[14:17], v232 offset:57344
	s_waitcnt lgkmcnt(0)
	v_mfma_f32_32x32x16_bf16 v[162:177], v[14:17], v[190:193], v[162:177]
	ds_read_b128 v[14:17], v229 offset:49280
	s_waitcnt lgkmcnt(0)
	v_mfma_f32_32x32x16_bf16 v[146:161], v[14:17], v[194:197], v[146:161]
	ds_read_b128 v[14:17], v229 offset:57472
	s_waitcnt lgkmcnt(0)
	v_mfma_f32_32x32x16_bf16 v[162:177], v[14:17], v[194:197], v[162:177]
	ds_read_b128 v[14:17], v230 offset:49280
	s_waitcnt lgkmcnt(0)
	v_mfma_f32_32x32x16_bf16 v[146:161], v[14:17], v[198:201], v[146:161]
	ds_read_b128 v[14:17], v230 offset:57472
	s_waitcnt lgkmcnt(0)
	v_mfma_f32_32x32x16_bf16 v[162:177], v[14:17], v[198:201], v[162:177]
	ds_read_b128 v[14:17], v231 offset:49280
	s_waitcnt lgkmcnt(0)
	v_mfma_f32_32x32x16_bf16 v[146:161], v[14:17], v[202:205], v[146:161]
	ds_read_b128 v[14:17], v231 offset:57472
	s_waitcnt lgkmcnt(0)
	v_mfma_f32_32x32x16_bf16 v[162:177], v[14:17], v[202:205], v[162:177]
	ds_read_b128 v[14:17], v232 offset:49280
	s_waitcnt lgkmcnt(0)
	v_mfma_f32_32x32x16_bf16 v[146:161], v[14:17], v[206:209], v[146:161]
	ds_read_b128 v[14:17], v232 offset:57472
	s_waitcnt lgkmcnt(0)
	v_mfma_f32_32x32x16_bf16 v[162:177], v[14:17], v[206:209], v[162:177]
	s_setprio 0
	s_cbranch_scc1 .LBB0_1133
	v_add_u32_e32 v5, s45, v228
	v_cmp_gt_u32_e32 vcc, 2.0, v5
	v_add_u32_e32 v6, 0xbfffffe0, v5
	s_nop 4
	v_cndmask_b32_e32 v146, v218, v146, vcc
	v_cmp_lt_u32_e32 vcc, s12, v6
	v_add_u32_e32 v6, 0xbfffffff, v5
	s_nop 0
	v_cndmask_b32_e32 v162, v218, v162, vcc
	v_cmp_lt_u32_e32 vcc, s12, v6
	v_add_u32_e32 v6, 0xbfffffdf, v5
	s_nop 0
	v_cndmask_b32_e32 v147, v218, v147, vcc
	v_cmp_lt_u32_e32 vcc, s12, v6
	v_add_u32_e32 v6, 0xbffffffe, v5
	s_nop 0
	v_cndmask_b32_e32 v163, v218, v163, vcc
	v_cmp_lt_u32_e32 vcc, s12, v6
	v_add_u32_e32 v6, 0xbfffffde, v5
	s_nop 0
	v_cndmask_b32_e32 v148, v218, v148, vcc
	v_cmp_lt_u32_e32 vcc, s12, v6
	v_add_u32_e32 v6, 0xbffffffd, v5
	s_nop 0
	v_cndmask_b32_e32 v164, v218, v164, vcc
	v_cmp_lt_u32_e32 vcc, s12, v6
	v_add_u32_e32 v6, 0xbfffffdd, v5
	s_nop 0
	v_cndmask_b32_e32 v149, v218, v149, vcc
	v_cmp_lt_u32_e32 vcc, s12, v6
	v_add_u32_e32 v6, 0xbffffff8, v5
	s_nop 0
	v_cndmask_b32_e32 v165, v218, v165, vcc
	v_cmp_lt_u32_e32 vcc, s12, v6
	v_add_u32_e32 v6, 0xbfffffd8, v5
	s_nop 0
	v_cndmask_b32_e32 v150, v218, v150, vcc
	v_cmp_lt_u32_e32 vcc, s12, v6
	v_add_u32_e32 v6, 0xbffffff7, v5
	s_nop 0
	v_cndmask_b32_e32 v166, v218, v166, vcc
	v_cmp_lt_u32_e32 vcc, s12, v6
	v_add_u32_e32 v6, 0xbfffffd7, v5
	s_nop 0
	v_cndmask_b32_e32 v151, v218, v151, vcc
	v_cmp_lt_u32_e32 vcc, s12, v6
	v_add_u32_e32 v6, 0xbffffff6, v5
	s_nop 0
	v_cndmask_b32_e32 v167, v218, v167, vcc
	v_cmp_lt_u32_e32 vcc, s12, v6
	v_add_u32_e32 v6, 0xbfffffd6, v5
	s_nop 0
	v_cndmask_b32_e32 v152, v218, v152, vcc
	v_cmp_lt_u32_e32 vcc, s12, v6
	v_add_u32_e32 v6, 0xbffffff5, v5
	s_nop 0
	v_cndmask_b32_e32 v168, v218, v168, vcc
	v_cmp_lt_u32_e32 vcc, s12, v6
	v_add_u32_e32 v6, 0xbfffffd5, v5
	s_nop 0
	v_cndmask_b32_e32 v153, v218, v153, vcc
	v_cmp_lt_u32_e32 vcc, s12, v6
	v_add_u32_e32 v6, 0xbffffff0, v5
	s_nop 0
	v_cndmask_b32_e32 v169, v218, v169, vcc
	v_cmp_lt_u32_e32 vcc, s12, v6
	v_add_u32_e32 v6, 0xbfffffd0, v5
	s_nop 0
	v_cndmask_b32_e32 v154, v218, v154, vcc
	v_cmp_lt_u32_e32 vcc, s12, v6
	v_add_u32_e32 v6, 0xbfffffef, v5
	s_nop 0
	v_cndmask_b32_e32 v170, v218, v170, vcc
	v_cmp_lt_u32_e32 vcc, s12, v6
	v_add_u32_e32 v6, 0xbfffffcf, v5
	s_nop 0
	v_cndmask_b32_e32 v155, v218, v155, vcc
	v_cmp_lt_u32_e32 vcc, s12, v6
	v_add_u32_e32 v6, 0xbfffffee, v5
	s_nop 0
	v_cndmask_b32_e32 v171, v218, v171, vcc
	v_cmp_lt_u32_e32 vcc, s12, v6
	v_add_u32_e32 v6, 0xbfffffce, v5
	s_nop 0
	v_cndmask_b32_e32 v156, v218, v156, vcc
	v_cmp_lt_u32_e32 vcc, s12, v6
	v_add_u32_e32 v6, 0xbfffffed, v5
	s_nop 0
	v_cndmask_b32_e32 v172, v218, v172, vcc
	v_cmp_lt_u32_e32 vcc, s12, v6
	v_add_u32_e32 v6, 0xbfffffcd, v5
	s_nop 0
	v_cndmask_b32_e32 v157, v218, v157, vcc
	v_cmp_lt_u32_e32 vcc, s12, v6
	v_add_u32_e32 v6, 0xbfffffe8, v5
	s_nop 0
	v_cndmask_b32_e32 v173, v218, v173, vcc
	v_cmp_lt_u32_e32 vcc, s12, v6
	v_add_u32_e32 v6, 0xbfffffc8, v5
	s_nop 0
	v_cndmask_b32_e32 v158, v218, v158, vcc
	v_cmp_lt_u32_e32 vcc, s12, v6
	v_add_u32_e32 v6, 0xbfffffe7, v5
	s_nop 0
	v_cndmask_b32_e32 v174, v218, v174, vcc
	v_cmp_lt_u32_e32 vcc, s12, v6
	v_add_u32_e32 v6, 0xbfffffc7, v5
	s_nop 0
	v_cndmask_b32_e32 v159, v218, v159, vcc
	v_cmp_lt_u32_e32 vcc, s12, v6
	v_add_u32_e32 v6, 0xbfffffe6, v5
	s_nop 0
	v_cndmask_b32_e32 v175, v218, v175, vcc
	v_cmp_lt_u32_e32 vcc, s12, v6
	v_add_u32_e32 v6, 0xbfffffc6, v5
	s_nop 0
	v_cndmask_b32_e32 v160, v218, v160, vcc
	v_cmp_lt_u32_e32 vcc, s12, v6
	v_add_u32_e32 v6, 0xbfffffe5, v5
	v_add_u32_e32 v5, 0xbfffffc5, v5
	v_cndmask_b32_e32 v176, v218, v176, vcc
	v_cmp_lt_u32_e32 vcc, s12, v6
	s_nop 1
	v_cndmask_b32_e32 v161, v218, v161, vcc
	v_cmp_lt_u32_e32 vcc, s12, v5
	s_nop 1
	v_cndmask_b32_e32 v177, v218, v177, vcc

.LBB0_1135:
	s_and_b64 vcc, exec, s[0:1]
	s_cbranch_vccz .LBB0_1149
	ds_read_b128 v[14:17], v229 offset:32768
	ds_read_b128 v[82:85], v12
	ds_read_b128 v[86:89], v13
	ds_read_b128 v[90:93], v10
	ds_read_b128 v[94:97], v11
	ds_read_b128 v[98:101], v9
	ds_read_b128 v[10:13], v229 offset:40960
	ds_read_b128 v[102:105], v4
	ds_read_b128 v[106:109], v7
	ds_read_b128 v[110:113], v8
	ds_read_b128 v[4:7], v230 offset:32768
	s_waitcnt lgkmcnt(0)
	s_setprio 1
	v_mfma_f32_32x32x16_bf16 v[82:97], v[14:17], v[178:181], v[82:97]
	s_cmp_le_i32 s54, s52
	s_waitcnt lgkmcnt(0)
	v_mfma_f32_32x32x16_bf16 v[82:97], v[4:7], v[182:185], v[82:97]
	ds_read_b128 v[4:7], v230 offset:40960
	v_mfma_f32_32x32x16_bf16 v[98:113], v[10:13], v[178:181], v[98:113]
	s_waitcnt lgkmcnt(0)
	v_mfma_f32_32x32x16_bf16 v[98:113], v[4:7], v[182:185], v[98:113]
	ds_read_b128 v[4:7], v231 offset:32768
	s_waitcnt lgkmcnt(0)
	v_mfma_f32_32x32x16_bf16 v[82:97], v[4:7], v[186:189], v[82:97]
	ds_read_b128 v[4:7], v231 offset:40960
	s_waitcnt lgkmcnt(0)
	v_mfma_f32_32x32x16_bf16 v[98:113], v[4:7], v[186:189], v[98:113]
	ds_read_b128 v[4:7], v232 offset:32768
	s_waitcnt lgkmcnt(0)
	v_mfma_f32_32x32x16_bf16 v[82:97], v[4:7], v[190:193], v[82:97]
	ds_read_b128 v[4:7], v232 offset:40960
	s_waitcnt lgkmcnt(0)
	v_mfma_f32_32x32x16_bf16 v[98:113], v[4:7], v[190:193], v[98:113]
	ds_read_b128 v[4:7], v229 offset:32896
	s_waitcnt lgkmcnt(0)
	v_mfma_f32_32x32x16_bf16 v[82:97], v[4:7], v[194:197], v[82:97]
	ds_read_b128 v[4:7], v229 offset:41088
	s_waitcnt lgkmcnt(0)
	v_mfma_f32_32x32x16_bf16 v[98:113], v[4:7], v[194:197], v[98:113]
	ds_read_b128 v[4:7], v230 offset:32896
	s_waitcnt lgkmcnt(0)
	v_mfma_f32_32x32x16_bf16 v[82:97], v[4:7], v[198:201], v[82:97]
	ds_read_b128 v[4:7], v230 offset:41088
	s_waitcnt lgkmcnt(0)
	v_mfma_f32_32x32x16_bf16 v[98:113], v[4:7], v[198:201], v[98:113]
	ds_read_b128 v[4:7], v231 offset:32896
	s_waitcnt lgkmcnt(0)
	v_mfma_f32_32x32x16_bf16 v[82:97], v[4:7], v[202:205], v[82:97]
	ds_read_b128 v[4:7], v231 offset:41088
	s_waitcnt lgkmcnt(0)
	v_mfma_f32_32x32x16_bf16 v[98:113], v[4:7], v[202:205], v[98:113]
	ds_read_b128 v[4:7], v232 offset:32896
	s_waitcnt lgkmcnt(0)
	v_mfma_f32_32x32x16_bf16 v[82:97], v[4:7], v[206:209], v[82:97]
	ds_read_b128 v[4:7], v232 offset:41088
	s_waitcnt lgkmcnt(0)
	v_mfma_f32_32x32x16_bf16 v[98:113], v[4:7], v[206:209], v[98:113]
	s_setprio 0
	s_cbranch_scc1 .LBB0_1138
	v_add_u32_e32 v4, s45, v228
	v_cmp_gt_u32_e32 vcc, 2.0, v4
	v_add_u32_e32 v5, 0xbfffffe0, v4
	s_nop 4
	v_cndmask_b32_e32 v82, v218, v82, vcc
	v_cmp_lt_u32_e32 vcc, s12, v5
	v_add_u32_e32 v5, 0xbfffffff, v4
	s_nop 0
	v_cndmask_b32_e32 v98, v218, v98, vcc
	v_cmp_lt_u32_e32 vcc, s12, v5
	v_add_u32_e32 v5, 0xbfffffdf, v4
	s_nop 0
	v_cndmask_b32_e32 v83, v218, v83, vcc
	v_cmp_lt_u32_e32 vcc, s12, v5
	v_add_u32_e32 v5, 0xbffffffe, v4
	s_nop 0
	v_cndmask_b32_e32 v99, v218, v99, vcc
	v_cmp_lt_u32_e32 vcc, s12, v5
	v_add_u32_e32 v5, 0xbfffffde, v4
	s_nop 0
	v_cndmask_b32_e32 v84, v218, v84, vcc
	v_cmp_lt_u32_e32 vcc, s12, v5
	v_add_u32_e32 v5, 0xbffffffd, v4
	s_nop 0
	v_cndmask_b32_e32 v100, v218, v100, vcc
	v_cmp_lt_u32_e32 vcc, s12, v5
	v_add_u32_e32 v5, 0xbfffffdd, v4
	s_nop 0
	v_cndmask_b32_e32 v85, v218, v85, vcc
	v_cmp_lt_u32_e32 vcc, s12, v5
	v_add_u32_e32 v5, 0xbffffff8, v4
	s_nop 0
	v_cndmask_b32_e32 v101, v218, v101, vcc
	v_cmp_lt_u32_e32 vcc, s12, v5
	v_add_u32_e32 v5, 0xbfffffd8, v4
	s_nop 0
	v_cndmask_b32_e32 v86, v218, v86, vcc
	v_cmp_lt_u32_e32 vcc, s12, v5
	v_add_u32_e32 v5, 0xbffffff7, v4
	s_nop 0
	v_cndmask_b32_e32 v102, v218, v102, vcc
	v_cmp_lt_u32_e32 vcc, s12, v5
	v_add_u32_e32 v5, 0xbfffffd7, v4
	s_nop 0
	v_cndmask_b32_e32 v87, v218, v87, vcc
	v_cmp_lt_u32_e32 vcc, s12, v5
	v_add_u32_e32 v5, 0xbffffff6, v4
	s_nop 0
	v_cndmask_b32_e32 v103, v218, v103, vcc
	v_cmp_lt_u32_e32 vcc, s12, v5
	v_add_u32_e32 v5, 0xbfffffd6, v4
	s_nop 0
	v_cndmask_b32_e32 v88, v218, v88, vcc
	v_cmp_lt_u32_e32 vcc, s12, v5
	v_add_u32_e32 v5, 0xbffffff5, v4
	s_nop 0
	v_cndmask_b32_e32 v104, v218, v104, vcc
	v_cmp_lt_u32_e32 vcc, s12, v5
	v_add_u32_e32 v5, 0xbfffffd5, v4
	s_nop 0
	v_cndmask_b32_e32 v89, v218, v89, vcc
	v_cmp_lt_u32_e32 vcc, s12, v5
	v_add_u32_e32 v5, 0xbffffff0, v4
	s_nop 0
	v_cndmask_b32_e32 v105, v218, v105, vcc
	v_cmp_lt_u32_e32 vcc, s12, v5
	v_add_u32_e32 v5, 0xbfffffd0, v4
	s_nop 0
	v_cndmask_b32_e32 v90, v218, v90, vcc
	v_cmp_lt_u32_e32 vcc, s12, v5
	v_add_u32_e32 v5, 0xbfffffef, v4
	s_nop 0
	v_cndmask_b32_e32 v106, v218, v106, vcc
	v_cmp_lt_u32_e32 vcc, s12, v5
	v_add_u32_e32 v5, 0xbfffffcf, v4
	s_nop 0
	v_cndmask_b32_e32 v91, v218, v91, vcc
	v_cmp_lt_u32_e32 vcc, s12, v5
	v_add_u32_e32 v5, 0xbfffffee, v4
	s_nop 0
	v_cndmask_b32_e32 v107, v218, v107, vcc
	v_cmp_lt_u32_e32 vcc, s12, v5
	v_add_u32_e32 v5, 0xbfffffce, v4
	s_nop 0
	v_cndmask_b32_e32 v92, v218, v92, vcc
	v_cmp_lt_u32_e32 vcc, s12, v5
	v_add_u32_e32 v5, 0xbfffffed, v4
	s_nop 0
	v_cndmask_b32_e32 v108, v218, v108, vcc
	v_cmp_lt_u32_e32 vcc, s12, v5
	v_add_u32_e32 v5, 0xbfffffcd, v4
	s_nop 0
	v_cndmask_b32_e32 v93, v218, v93, vcc
	v_cmp_lt_u32_e32 vcc, s12, v5
	v_add_u32_e32 v5, 0xbfffffe8, v4
	s_nop 0
	v_cndmask_b32_e32 v109, v218, v109, vcc
	v_cmp_lt_u32_e32 vcc, s12, v5
	v_add_u32_e32 v5, 0xbfffffc8, v4
	s_nop 0
	v_cndmask_b32_e32 v94, v218, v94, vcc
	v_cmp_lt_u32_e32 vcc, s12, v5
	v_add_u32_e32 v5, 0xbfffffe7, v4
	s_nop 0
	v_cndmask_b32_e32 v110, v218, v110, vcc
	v_cmp_lt_u32_e32 vcc, s12, v5
	v_add_u32_e32 v5, 0xbfffffc7, v4
	s_nop 0
	v_cndmask_b32_e32 v95, v218, v95, vcc
	v_cmp_lt_u32_e32 vcc, s12, v5
	v_add_u32_e32 v5, 0xbfffffe6, v4
	s_nop 0
	v_cndmask_b32_e32 v111, v218, v111, vcc
	v_cmp_lt_u32_e32 vcc, s12, v5
	v_add_u32_e32 v5, 0xbfffffc6, v4
	s_nop 0
	v_cndmask_b32_e32 v96, v218, v96, vcc
	v_cmp_lt_u32_e32 vcc, s12, v5
	v_add_u32_e32 v5, 0xbfffffe5, v4
	v_add_u32_e32 v4, 0xbfffffc5, v4
	v_cndmask_b32_e32 v112, v218, v112, vcc
	v_cmp_lt_u32_e32 vcc, s12, v5
	s_nop 1
	v_cndmask_b32_e32 v97, v218, v97, vcc
	v_cmp_lt_u32_e32 vcc, s12, v4
	s_nop 1
	v_cndmask_b32_e32 v113, v218, v113, vcc

.LBB0_1147:
	v_add_f32_e32 v14, 0, v146
	v_add_f32_e32 v14, v147, v14
	v_add_f32_e32 v14, v148, v14
	v_add_f32_e32 v14, v149, v14
	v_add_f32_e32 v14, v150, v14
	v_add_f32_e32 v14, v151, v14
	v_add_f32_e32 v14, v152, v14
	v_add_f32_e32 v14, v153, v14
	v_add_f32_e32 v14, v154, v14
	v_add_f32_e32 v14, v155, v14
	v_add_f32_e32 v14, v156, v14
	v_add_f32_e32 v14, v157, v14
	v_exp_f32_e32 v16, v162
	v_add_f32_e32 v14, v158, v14
	v_exp_f32_e32 v17, v163
	v_add_f32_e32 v14, v159, v14
	v_exp_f32_e32 v162, v164
	v_add_f32_e32 v14, v160, v14
	v_exp_f32_e32 v163, v165
	v_add_f32_e32 v14, v161, v14
	v_exp_f32_e32 v164, v166
	v_add_f32_e32 v14, v16, v14
	v_exp_f32_e32 v165, v167
	v_add_f32_e32 v14, v17, v14
	v_exp_f32_e32 v166, v168
	v_add_f32_e32 v14, v162, v14
	v_exp_f32_e32 v167, v169
	v_add_f32_e32 v14, v163, v14
	v_exp_f32_e32 v168, v170
	v_add_f32_e32 v14, v164, v14
	v_exp_f32_e32 v169, v171
	v_add_f32_e32 v14, v165, v14
	v_exp_f32_e32 v170, v172
	v_add_f32_e32 v14, v166, v14
	v_exp_f32_e32 v171, v173
	v_add_f32_e32 v14, v167, v14
	v_exp_f32_e32 v172, v174
	v_add_f32_e32 v14, v168, v14
	v_exp_f32_e32 v173, v175
	v_add_f32_e32 v14, v169, v14
	v_exp_f32_e32 v174, v176
	v_add_f32_e32 v14, v170, v14
	v_exp_f32_e32 v175, v177
	v_add_f32_e32 v14, v171, v14
	v_add_f32_e32 v14, v172, v14
	v_add_f32_e32 v14, v173, v14
	v_add_f32_e32 v14, v174, v14
	v_add_f32_e32 v14, v175, v14
	v_mov_b32_e32 v176, v14
	s_nop 1
	v_permlane32_swap_b32_e32 v14, v176
	v_add_f32_e32 v14, v14, v176
	v_fmac_f32_e32 v14, v210, v15
	v_cvt_pk_bf16_f32 v146, v146, v147
	v_cvt_pk_bf16_f32 v147, v148, v149
	v_cvt_pk_bf16_f32 v148, v150, v151
	v_cvt_pk_bf16_f32 v149, v152, v153
	v_cvt_pk_bf16_f32 v150, v154, v155
	v_cvt_pk_bf16_f32 v151, v156, v157
	v_cvt_pk_bf16_f32 v152, v158, v159
	v_cvt_pk_bf16_f32 v153, v160, v161
	v_cvt_pk_bf16_f32 v154, v16, v17
	v_cvt_pk_bf16_f32 v155, v162, v163
	v_cvt_pk_bf16_f32 v156, v164, v165
	v_cvt_pk_bf16_f32 v157, v166, v167
	v_cvt_pk_bf16_f32 v158, v168, v169
	v_cvt_pk_bf16_f32 v159, v170, v171
	v_cvt_pk_bf16_f32 v160, v172, v173
	v_cvt_pk_bf16_f32 v161, v174, v175
	s_nop 0
	v_permlane32_swap_b32_e32 v146, v148
	v_permlane32_swap_b32_e32 v147, v149
	v_permlane32_swap_b32_e32 v150, v152
	v_permlane32_swap_b32_e32 v151, v153
	v_permlane32_swap_b32_e32 v154, v156
	v_permlane32_swap_b32_e32 v155, v157
	v_permlane32_swap_b32_e32 v158, v160
	v_permlane32_swap_b32_e32 v159, v161
	ds_read_b64_tr_b16 v[162:163], v224 offset:0x4000
	ds_read_b64_tr_b16 v[164:165], v224 offset:0x4800
	ds_read_b64_tr_b16 v[166:167], v224 offset:0x5000
	ds_read_b64_tr_b16 v[168:169], v224 offset:0x5800
	ds_read_b64_tr_b16 v[170:171], v224 offset:0x6000
	ds_read_b64_tr_b16 v[172:173], v224 offset:0x6800
	ds_read_b64_tr_b16 v[174:175], v224 offset:0x7000
	ds_read_b64_tr_b16 v[176:177], v224 offset:0x7800
	s_waitcnt lgkmcnt(0)
	s_nop 0
	s_setprio 1
	v_mfma_f32_32x32x16_bf16 v[82:97], v[146:149], v[162:165], v[82:97]
	ds_read_b64_tr_b16 v[162:163], v224 offset:0x4200
	ds_read_b64_tr_b16 v[164:165], v224 offset:0x4a00
	v_mfma_f32_32x32x16_bf16 v[82:97], v[150:153], v[166:169], v[82:97]
	ds_read_b64_tr_b16 v[166:167], v224 offset:0x5200
	ds_read_b64_tr_b16 v[168:169], v224 offset:0x5a00
	v_mfma_f32_32x32x16_bf16 v[82:97], v[154:157], v[170:173], v[82:97]
	ds_read_b64_tr_b16 v[170:171], v224 offset:0x6200
	ds_read_b64_tr_b16 v[172:173], v224 offset:0x6a00
	v_mfma_f32_32x32x16_bf16 v[82:97], v[158:161], v[174:177], v[82:97]
	ds_read_b64_tr_b16 v[174:175], v224 offset:0x7200
	ds_read_b64_tr_b16 v[176:177], v224 offset:0x7a00
	s_waitcnt lgkmcnt(0)
	v_mfma_f32_32x32x16_bf16 v[98:113], v[146:149], v[162:165], v[98:113]
	ds_read_b64_tr_b16 v[162:163], v224 offset:0x4400
	ds_read_b64_tr_b16 v[164:165], v224 offset:0x4c00
	v_mfma_f32_32x32x16_bf16 v[98:113], v[150:153], v[166:169], v[98:113]
	ds_read_b64_tr_b16 v[166:167], v224 offset:0x5400
	ds_read_b64_tr_b16 v[168:169], v224 offset:0x5c00
	v_mfma_f32_32x32x16_bf16 v[98:113], v[154:157], v[170:173], v[98:113]
	ds_read_b64_tr_b16 v[170:171], v224 offset:0x6400
	ds_read_b64_tr_b16 v[172:173], v224 offset:0x6c00
	v_mfma_f32_32x32x16_bf16 v[98:113], v[158:161], v[174:177], v[98:113]
	ds_read_b64_tr_b16 v[174:175], v224 offset:0x7400
	ds_read_b64_tr_b16 v[176:177], v224 offset:0x7c00
	s_waitcnt lgkmcnt(0)
	v_mfma_f32_32x32x16_bf16 v[114:129], v[146:149], v[162:165], v[114:129]
	ds_read_b64_tr_b16 v[162:163], v224 offset:0x4600
	ds_read_b64_tr_b16 v[164:165], v224 offset:0x4e00
	v_mfma_f32_32x32x16_bf16 v[114:129], v[150:153], v[166:169], v[114:129]
	ds_read_b64_tr_b16 v[166:167], v224 offset:0x5600
	ds_read_b64_tr_b16 v[168:169], v224 offset:0x5e00
	v_mfma_f32_32x32x16_bf16 v[114:129], v[154:157], v[170:173], v[114:129]
	ds_read_b64_tr_b16 v[170:171], v224 offset:0x6600
	ds_read_b64_tr_b16 v[172:173], v224 offset:0x6e00
	v_mfma_f32_32x32x16_bf16 v[114:129], v[158:161], v[174:177], v[114:129]
	ds_read_b64_tr_b16 v[174:175], v224 offset:0x7600
	ds_read_b64_tr_b16 v[176:177], v224 offset:0x7e00
	s_waitcnt lgkmcnt(0)
	v_mfma_f32_32x32x16_bf16 v[130:145], v[146:149], v[162:165], v[130:145]
	v_mfma_f32_32x32x16_bf16 v[130:145], v[150:153], v[166:169], v[130:145]
	v_mfma_f32_32x32x16_bf16 v[130:145], v[154:157], v[170:173], v[130:145]
	v_mfma_f32_32x32x16_bf16 v[130:145], v[158:161], v[174:177], v[130:145]
	s_setprio 0

.LBB0_1159:
	v_add_f32_e32 v8, 0, v82
	v_add_f32_e32 v8, v83, v8
	v_add_f32_e32 v8, v84, v8
	v_add_f32_e32 v8, v85, v8
	v_add_f32_e32 v8, v86, v8
	v_add_f32_e32 v8, v87, v8
	v_add_f32_e32 v8, v88, v8
	v_add_f32_e32 v8, v89, v8
	v_add_f32_e32 v8, v90, v8
	v_add_f32_e32 v8, v91, v8
	v_add_f32_e32 v8, v92, v8
	v_add_f32_e32 v8, v93, v8
	v_exp_f32_e32 v2, v98
	v_add_f32_e32 v8, v94, v8
	v_exp_f32_e32 v7, v99
	v_add_f32_e32 v8, v95, v8
	v_exp_f32_e32 v12, v100
	v_add_f32_e32 v8, v96, v8
	v_exp_f32_e32 v13, v101
	v_add_f32_e32 v8, v97, v8
	v_exp_f32_e32 v15, v102
	v_add_f32_e32 v8, v2, v8
	v_exp_f32_e32 v16, v103
	v_add_f32_e32 v8, v7, v8
	v_exp_f32_e32 v17, v104
	v_add_f32_e32 v8, v12, v8
	v_exp_f32_e32 v98, v105
	v_add_f32_e32 v8, v13, v8
	v_exp_f32_e32 v99, v106
	v_add_f32_e32 v8, v15, v8
	v_exp_f32_e32 v100, v107
	v_add_f32_e32 v8, v16, v8
	v_exp_f32_e32 v101, v108
	v_add_f32_e32 v8, v17, v8
	v_exp_f32_e32 v102, v109
	v_add_f32_e32 v8, v98, v8
	v_exp_f32_e32 v103, v110
	v_add_f32_e32 v8, v99, v8
	v_exp_f32_e32 v104, v111
	v_add_f32_e32 v8, v100, v8
	v_exp_f32_e32 v105, v112
	v_add_f32_e32 v8, v101, v8
	v_exp_f32_e32 v106, v113
	v_add_f32_e32 v8, v102, v8
	v_add_f32_e32 v8, v103, v8
	v_add_f32_e32 v8, v104, v8
	v_add_f32_e32 v8, v105, v8
	v_add_f32_e32 v8, v106, v8
	v_mov_b32_e32 v9, v8
	s_nop 1
	v_permlane32_swap_b32_e32 v8, v9
	v_add_f32_e32 v14, v8, v9
	v_cvt_pk_bf16_f32 v8, v82, v83
	v_cvt_pk_bf16_f32 v9, v84, v85
	v_cvt_pk_bf16_f32 v10, v86, v87
	v_cvt_pk_bf16_f32 v11, v88, v89
	v_cvt_pk_bf16_f32 v82, v90, v91
	v_cvt_pk_bf16_f32 v83, v92, v93
	v_cvt_pk_bf16_f32 v84, v94, v95
	v_cvt_pk_bf16_f32 v85, v96, v97
	v_cvt_pk_bf16_f32 v86, v2, v7
	v_cvt_pk_bf16_f32 v87, v12, v13
	v_cvt_pk_bf16_f32 v88, v15, v16
	v_cvt_pk_bf16_f32 v89, v17, v98
	v_fmac_f32_e32 v14, v210, v4
	v_permlane32_swap_b32_e32 v8, v10
	v_permlane32_swap_b32_e32 v9, v11
	v_permlane32_swap_b32_e32 v82, v84
	v_permlane32_swap_b32_e32 v83, v85
	v_permlane32_swap_b32_e32 v86, v88
	v_permlane32_swap_b32_e32 v87, v89
	v_cvt_pk_bf16_f32 v114, v99, v100
	v_cvt_pk_bf16_f32 v115, v101, v102
	v_cvt_pk_bf16_f32 v116, v103, v104
	v_cvt_pk_bf16_f32 v117, v105, v106
	s_nop 0
	v_permlane32_swap_b32_e32 v114, v116
	v_permlane32_swap_b32_e32 v115, v117
	ds_read_b64_tr_b16 v[90:91], v224 offset:0
	ds_read_b64_tr_b16 v[92:93], v224 offset:0x800
	ds_read_b64_tr_b16 v[94:95], v224 offset:0x1000
	ds_read_b64_tr_b16 v[96:97], v224 offset:0x1800
	ds_read_b64_tr_b16 v[98:99], v224 offset:0x2000
	ds_read_b64_tr_b16 v[100:101], v224 offset:0x2800
	ds_read_b64_tr_b16 v[102:103], v224 offset:0x3000
	ds_read_b64_tr_b16 v[104:105], v224 offset:0x3800
	s_waitcnt lgkmcnt(0)
	s_nop 0
	s_setprio 1
	v_mfma_f32_32x32x16_bf16 v[66:81], v[8:11], v[90:93], v[66:81]
	ds_read_b64_tr_b16 v[90:91], v224 offset:0x200
	ds_read_b64_tr_b16 v[92:93], v224 offset:0xa00
	v_mfma_f32_32x32x16_bf16 v[66:81], v[82:85], v[94:97], v[66:81]
	ds_read_b64_tr_b16 v[94:95], v224 offset:0x1200
	ds_read_b64_tr_b16 v[96:97], v224 offset:0x1a00
	v_mfma_f32_32x32x16_bf16 v[66:81], v[86:89], v[98:101], v[66:81]
	ds_read_b64_tr_b16 v[98:99], v224 offset:0x2200
	ds_read_b64_tr_b16 v[100:101], v224 offset:0x2a00
	v_mfma_f32_32x32x16_bf16 v[66:81], v[114:117], v[102:105], v[66:81]
	ds_read_b64_tr_b16 v[102:103], v224 offset:0x3200
	ds_read_b64_tr_b16 v[104:105], v224 offset:0x3a00
	s_waitcnt lgkmcnt(0)
	v_mfma_f32_32x32x16_bf16 v[50:65], v[8:11], v[90:93], v[50:65]
	ds_read_b64_tr_b16 v[90:91], v224 offset:0x400
	ds_read_b64_tr_b16 v[92:93], v224 offset:0xc00
	v_mfma_f32_32x32x16_bf16 v[50:65], v[82:85], v[94:97], v[50:65]
	ds_read_b64_tr_b16 v[94:95], v224 offset:0x1400
	ds_read_b64_tr_b16 v[96:97], v224 offset:0x1c00
	v_mfma_f32_32x32x16_bf16 v[50:65], v[86:89], v[98:101], v[50:65]
	ds_read_b64_tr_b16 v[98:99], v224 offset:0x2400
	ds_read_b64_tr_b16 v[100:101], v224 offset:0x2c00
	v_mfma_f32_32x32x16_bf16 v[50:65], v[114:117], v[102:105], v[50:65]
	ds_read_b64_tr_b16 v[102:103], v224 offset:0x3400
	ds_read_b64_tr_b16 v[104:105], v224 offset:0x3c00
	s_waitcnt lgkmcnt(0)
	v_mfma_f32_32x32x16_bf16 v[34:49], v[8:11], v[90:93], v[34:49]
	ds_read_b64_tr_b16 v[90:91], v224 offset:0x600
	ds_read_b64_tr_b16 v[92:93], v224 offset:0xe00
	v_mfma_f32_32x32x16_bf16 v[34:49], v[82:85], v[94:97], v[34:49]
	ds_read_b64_tr_b16 v[94:95], v224 offset:0x1600
	ds_read_b64_tr_b16 v[96:97], v224 offset:0x1e00
	v_mfma_f32_32x32x16_bf16 v[34:49], v[86:89], v[98:101], v[34:49]
	s_setprio 0
	ds_read_b64_tr_b16 v[98:99], v224 offset:0x2600
	ds_read_b64_tr_b16 v[100:101], v224 offset:0x2e00
	ds_read_b64_tr_b16 v[118:119], v224 offset:0x3600
	ds_read_b64_tr_b16 v[120:121], v224 offset:0x3e00
	s_waitcnt lgkmcnt(0)
	s_setprio 1
	v_mfma_f32_32x32x16_bf16 v[34:49], v[114:117], v[102:105], v[34:49]
	v_mfma_f32_32x32x16_bf16 v[18:33], v[8:11], v[90:93], v[18:33]
	v_mfma_f32_32x32x16_bf16 v[18:33], v[82:85], v[94:97], v[18:33]
	v_mfma_f32_32x32x16_bf16 v[18:33], v[86:89], v[98:101], v[18:33]
	s_setprio 0
	s_nop 0
	v_mov_b64_e32 v[96:97], v[80:81]
	s_nop 2
	v_mov_b64_e32 v[112:113], v[64:65]
	v_mov_b64_e32 v[94:95], v[78:79]
	v_mov_b64_e32 v[92:93], v[76:77]
	v_mov_b64_e32 v[90:91], v[74:75]
	v_mov_b64_e32 v[88:89], v[72:73]
	v_mov_b64_e32 v[86:87], v[70:71]
	v_mov_b64_e32 v[84:85], v[68:69]
	v_mov_b64_e32 v[82:83], v[66:67]
	v_mov_b64_e32 v[110:111], v[62:63]
	v_mov_b64_e32 v[108:109], v[60:61]
	v_mov_b64_e32 v[106:107], v[58:59]
	v_mov_b64_e32 v[104:105], v[56:57]
	v_mov_b64_e32 v[102:103], v[54:55]
	v_mov_b64_e32 v[100:101], v[52:53]
	v_mov_b64_e32 v[98:99], v[50:51]
	s_setprio 1
	v_mfma_f32_32x32x16_bf16 v[18:33], v[114:117], v[118:121], v[18:33]
	s_setprio 0

.LBB0_1201:
	s_or_b64 exec, exec, s[24:25]
	v_ashrrev_i32_e32 v19, 4, v18
	v_and_b32_e32 v12, 0xfffff0, v19
	v_lshlrev_b32_e32 v13, 1, v19
	v_and_or_b32 v12, v13, 8, v12
	v_lshrrev_b32_e32 v13, 1, v19
	v_and_b32_e32 v14, 3, v19
	v_bfe_u32 v10, v18, 5, 1
	s_ashr_i32 s16, s4, 1
	v_and_or_b32 v13, v13, 4, v14
	v_add_u32_e32 v14, 32, v19
	v_and_b32_e32 v204, 31, v18
	s_andn2_b32 s16, s16, 31
	v_lshlrev_b32_e32 v205, 2, v10
	v_and_b32_e32 v15, 0xfffff0, v14
	v_lshlrev_b32_e32 v16, 1, v14
	s_add_i32 s5, s16, 0x100000
	v_sub_u32_e32 v11, v204, v205
	v_lshlrev_b32_e32 v211, 4, v10
	v_lshlrev_b32_e32 v10, 3, v18
	v_and_or_b32 v15, v16, 8, v15
	v_add_u32_e32 v206, s5, v11
	v_and_b32_e32 v11, 0x78, v10
	v_lshrrev_b32_e32 v12, 1, v12
	v_bfe_u32 v10, v10, 5, 2
	v_lshrrev_b32_e32 v15, 1, v15
	v_or_b32_e32 v12, v12, v10
	v_lshlrev_b32_e32 v20, 1, v11
	v_or_b32_e32 v10, v15, v10
	v_lshlrev_b32_e32 v12, 9, v12
	v_lshlrev_b32_e32 v13, 6, v13
	v_and_b32_e32 v11, 48, v20
	v_lshlrev_b32_e32 v10, 9, v10
	v_or3_b32 v12, v12, v13, v11
	v_or3_b32 v10, v10, v13, v11
	s_lshl_b64 s[24:25], s[22:23], 9
	v_add_u32_e32 v213, 0, v12
	v_add_u32_e32 v214, 0, v10
	s_waitcnt lgkmcnt(0)
	s_barrier
	s_barrier
	ds_write_b128 v213, v[2:5]
	ds_write_b128 v214, v[6:9]
	s_add_u32 s30, s28, 0x20000
	s_addc_u32 s31, s29, 0
	v_lshl_or_b32 v198, v19, 10, v20
	v_lshl_or_b32 v200, v14, 10, v20
	global_load_dwordx4 v[2:5], v198, s[30:31]
	global_load_dwordx4 v[6:9], v200, s[30:31]
	s_add_u32 s30, s0, 0x20000
	s_addc_u32 s31, s1, 0
	global_load_dwordx4 v[10:13], v198, s[30:31]
	global_load_dwordx4 v[14:17], v200, s[30:31]
	s_cmp_gt_i32 s16, 0xfff000a0
	v_lshlrev_b32_e32 v29, 4, v204
	s_mov_b64 s[30:31], -1
	v_add_u32_e32 v223, s9, v211
	v_lshlrev_b32_e32 v21, 8, v204
	v_and_b32_e32 v24, 0x70, v29
	v_bitop3_b32 v22, v211, v29, s8 bitop3:0x78
	s_cbranch_scc0 .LBB0_1206
	v_lshlrev_b32_e32 v23, 8, v204
	v_bitop3_b32 v25, v211, v29, s8 bitop3:0x78
	v_add3_u32 v34, 0, v25, v23
	ds_read_b128 v[26:29], v34 offset:32768
	ds_read_b128 v[114:117], v223 offset:768
	ds_read_b128 v[118:121], v223 offset:800
	ds_read_b128 v[122:125], v223 offset:832
	ds_read_b128 v[126:129], v223 offset:864
	ds_read_b128 v[98:101], v223 offset:896
	ds_read_b128 v[30:33], v34 offset:40960
	ds_read_b128 v[102:105], v223 offset:928
	ds_read_b128 v[106:109], v223 offset:960
	ds_read_b128 v[110:113], v223 offset:992
	s_waitcnt lgkmcnt(5)
	s_setprio 1
	v_mfma_f32_32x32x16_bf16 v[114:129], v[26:29], v[162:165], v[114:129]
	v_bitop3_b32 v26, v211, v24, 32 bitop3:0x36
	v_add3_u32 v35, 0, v26, v23
	v_bitop3_b32 v27, v211, v24, 64 bitop3:0x36
	v_add3_u32 v36, 0, v27, v23
	s_cmpk_gt_u32 s5, 0xfe
	s_waitcnt lgkmcnt(0)
	v_mfma_f32_32x32x16_bf16 v[98:113], v[30:33], v[162:165], v[98:113]
	ds_read_b128 v[28:31], v35 offset:32768
	s_waitcnt lgkmcnt(0)
	v_mfma_f32_32x32x16_bf16 v[114:129], v[28:31], v[158:161], v[114:129]
	ds_read_b128 v[28:31], v35 offset:40960
	s_waitcnt lgkmcnt(0)
	v_mfma_f32_32x32x16_bf16 v[98:113], v[28:31], v[158:161], v[98:113]
	ds_read_b128 v[28:31], v36 offset:32768
	s_waitcnt lgkmcnt(0)
	v_mfma_f32_32x32x16_bf16 v[114:129], v[28:31], v[154:157], v[114:129]
	ds_read_b128 v[30:33], v36 offset:40960
	v_bitop3_b32 v28, v211, v24, s10 bitop3:0x36
	v_add3_u32 v29, 0, v28, v23
	s_waitcnt lgkmcnt(0)
	v_mfma_f32_32x32x16_bf16 v[98:113], v[30:33], v[154:157], v[98:113]
	ds_read_b128 v[30:33], v29 offset:32768
	s_waitcnt lgkmcnt(0)
	v_mfma_f32_32x32x16_bf16 v[114:129], v[30:33], v[150:153], v[114:129]
	ds_read_b128 v[30:33], v29 offset:40960
	s_waitcnt lgkmcnt(0)
	v_mfma_f32_32x32x16_bf16 v[98:113], v[30:33], v[150:153], v[98:113]
	ds_read_b128 v[30:33], v34 offset:32896
	s_waitcnt lgkmcnt(0)
	v_mfma_f32_32x32x16_bf16 v[114:129], v[30:33], v[146:149], v[114:129]
	ds_read_b128 v[30:33], v34 offset:41088
	s_waitcnt lgkmcnt(0)
	v_mfma_f32_32x32x16_bf16 v[98:113], v[30:33], v[146:149], v[98:113]
	ds_read_b128 v[30:33], v35 offset:32896
	s_waitcnt lgkmcnt(0)
	v_mfma_f32_32x32x16_bf16 v[114:129], v[30:33], v[142:145], v[114:129]
	ds_read_b128 v[30:33], v35 offset:41088
	s_waitcnt lgkmcnt(0)
	v_mfma_f32_32x32x16_bf16 v[98:113], v[30:33], v[142:145], v[98:113]
	ds_read_b128 v[30:33], v36 offset:32896
	s_waitcnt lgkmcnt(0)
	v_mfma_f32_32x32x16_bf16 v[114:129], v[30:33], v[138:141], v[114:129]
	ds_read_b128 v[30:33], v36 offset:41088
	s_waitcnt lgkmcnt(0)
	v_mfma_f32_32x32x16_bf16 v[98:113], v[30:33], v[138:141], v[98:113]
	ds_read_b128 v[30:33], v29 offset:32896
	s_waitcnt lgkmcnt(0)
	v_mfma_f32_32x32x16_bf16 v[114:129], v[30:33], v[134:137], v[114:129]
	ds_read_b128 v[30:33], v29 offset:41088
	s_waitcnt lgkmcnt(0)
	v_mfma_f32_32x32x16_bf16 v[98:113], v[30:33], v[134:137], v[98:113]
	s_setprio 0
	s_cbranch_scc1 .LBB0_1204
	v_add_u32_e32 v29, 0xbfffff40, v206
	v_cmp_lt_u32_e32 vcc, s11, v29
	v_add_u32_e32 v29, 0xbfffff20, v206
	s_nop 4
	v_cndmask_b32_e32 v114, v202, v114, vcc
	v_cmp_lt_u32_e32 vcc, s11, v29
	v_add_u32_e32 v29, 0xbfffff3f, v206
	s_nop 0
	v_cndmask_b32_e32 v98, v202, v98, vcc
	v_cmp_lt_u32_e32 vcc, s11, v29
	v_add_u32_e32 v29, 0xbfffff1f, v206
	s_nop 0
	v_cndmask_b32_e32 v115, v202, v115, vcc
	v_cmp_lt_u32_e32 vcc, s11, v29
	v_add_u32_e32 v29, 0xbfffff3e, v206
	s_nop 0
	v_cndmask_b32_e32 v99, v202, v99, vcc
	v_cmp_lt_u32_e32 vcc, s11, v29
	v_add_u32_e32 v29, 0xbfffff1e, v206
	s_nop 0
	v_cndmask_b32_e32 v116, v202, v116, vcc
	v_cmp_lt_u32_e32 vcc, s11, v29
	v_add_u32_e32 v29, 0xbfffff3d, v206
	s_nop 0
	v_cndmask_b32_e32 v100, v202, v100, vcc
	v_cmp_lt_u32_e32 vcc, s11, v29
	v_add_u32_e32 v29, 0xbfffff1d, v206
	s_nop 0
	v_cndmask_b32_e32 v117, v202, v117, vcc
	v_cmp_lt_u32_e32 vcc, s11, v29
	v_add_u32_e32 v29, 0xbfffff38, v206
	s_nop 0
	v_cndmask_b32_e32 v101, v202, v101, vcc
	v_cmp_lt_u32_e32 vcc, s11, v29
	v_add_u32_e32 v29, 0xbfffff18, v206
	s_nop 0
	v_cndmask_b32_e32 v118, v202, v118, vcc
	v_cmp_lt_u32_e32 vcc, s11, v29
	v_add_u32_e32 v29, 0xbfffff37, v206
	s_nop 0
	v_cndmask_b32_e32 v102, v202, v102, vcc
	v_cmp_lt_u32_e32 vcc, s11, v29
	v_add_u32_e32 v29, 0xbfffff17, v206
	s_nop 0
	v_cndmask_b32_e32 v119, v202, v119, vcc
	v_cmp_lt_u32_e32 vcc, s11, v29
	v_add_u32_e32 v29, 0xbfffff36, v206
	s_nop 0
	v_cndmask_b32_e32 v103, v202, v103, vcc
	v_cmp_lt_u32_e32 vcc, s11, v29
	v_add_u32_e32 v29, 0xbfffff16, v206
	s_nop 0
	v_cndmask_b32_e32 v120, v202, v120, vcc
	v_cmp_lt_u32_e32 vcc, s11, v29
	v_add_u32_e32 v29, 0xbfffff35, v206
	s_nop 0
	v_cndmask_b32_e32 v104, v202, v104, vcc
	v_cmp_lt_u32_e32 vcc, s11, v29
	v_add_u32_e32 v29, 0xbfffff15, v206
	s_nop 0
	v_cndmask_b32_e32 v121, v202, v121, vcc
	v_cmp_lt_u32_e32 vcc, s11, v29
	v_add_u32_e32 v29, 0xbfffff30, v206
	s_nop 0
	v_cndmask_b32_e32 v105, v202, v105, vcc
	v_cmp_lt_u32_e32 vcc, s11, v29
	v_add_u32_e32 v29, 0xbfffff10, v206
	s_nop 0
	v_cndmask_b32_e32 v122, v202, v122, vcc
	v_cmp_lt_u32_e32 vcc, s11, v29
	v_add_u32_e32 v29, 0xbfffff2f, v206
	s_nop 0
	v_cndmask_b32_e32 v106, v202, v106, vcc
	v_cmp_lt_u32_e32 vcc, s11, v29
	v_add_u32_e32 v29, 0xbfffff0f, v206
	s_nop 0
	v_cndmask_b32_e32 v123, v202, v123, vcc
	v_cmp_lt_u32_e32 vcc, s11, v29
	v_add_u32_e32 v29, 0xbfffff2e, v206
	s_nop 0
	v_cndmask_b32_e32 v107, v202, v107, vcc
	v_cmp_lt_u32_e32 vcc, s11, v29
	v_add_u32_e32 v29, 0xbfffff0e, v206
	s_nop 0
	v_cndmask_b32_e32 v124, v202, v124, vcc
	v_cmp_lt_u32_e32 vcc, s11, v29
	v_add_u32_e32 v29, 0xbfffff2d, v206
	s_nop 0
	v_cndmask_b32_e32 v108, v202, v108, vcc
	v_cmp_lt_u32_e32 vcc, s11, v29
	v_add_u32_e32 v29, 0xbfffff0d, v206
	s_nop 0
	v_cndmask_b32_e32 v125, v202, v125, vcc
	v_cmp_lt_u32_e32 vcc, s11, v29
	v_add_u32_e32 v29, 0xbfffff28, v206
	s_nop 0
	v_cndmask_b32_e32 v109, v202, v109, vcc
	v_cmp_lt_u32_e32 vcc, s11, v29
	v_add_u32_e32 v29, 0xbfffff08, v206
	s_nop 0
	v_cndmask_b32_e32 v126, v202, v126, vcc
	v_cmp_lt_u32_e32 vcc, s11, v29
	v_add_u32_e32 v29, 0xbfffff27, v206
	s_nop 0
	v_cndmask_b32_e32 v110, v202, v110, vcc
	v_cmp_lt_u32_e32 vcc, s11, v29
	v_add_u32_e32 v29, 0xbfffff07, v206
	s_nop 0
	v_cndmask_b32_e32 v127, v202, v127, vcc
	v_cmp_lt_u32_e32 vcc, s11, v29
	v_add_u32_e32 v29, 0xbfffff26, v206
	s_nop 0
	v_cndmask_b32_e32 v111, v202, v111, vcc
	v_cmp_lt_u32_e32 vcc, s11, v29
	v_add_u32_e32 v29, 0xbfffff06, v206
	s_nop 0
	v_cndmask_b32_e32 v128, v202, v128, vcc
	v_cmp_lt_u32_e32 vcc, s11, v29
	v_add_u32_e32 v29, 0xbfffff25, v206
	s_nop 0
	v_cndmask_b32_e32 v112, v202, v112, vcc
	v_cmp_lt_u32_e32 vcc, s11, v29
	v_add_u32_e32 v29, 0xbfffff05, v206
	s_nop 0
	v_cndmask_b32_e32 v129, v202, v129, vcc
	v_cmp_lt_u32_e32 vcc, s11, v29
	s_nop 1
	v_cndmask_b32_e32 v113, v202, v113, vcc

.LBB0_1208:
	v_lshlrev_b32_e32 v19, 8, v19
	v_and_b32_e32 v21, 0x70, v18
	s_waitcnt vmcnt(0)
	v_bitop3_b32 v19, v20, v19, v21 bitop3:0xde
	v_mov_b32_e32 v201, v199
	v_add_u32_e32 v207, 0, v19
	s_waitcnt vmcnt(3)
	ds_write_b128 v213, v[2:5] offset:16384
	s_waitcnt vmcnt(2)
	ds_write_b128 v214, v[6:9] offset:16384
	s_waitcnt vmcnt(1)
	ds_write_b128 v207, v[10:13] offset:49152
	s_waitcnt vmcnt(0)
	ds_write_b128 v207, v[14:17] offset:57344
	s_waitcnt lgkmcnt(0)
	s_barrier
	v_add_u32_e32 v6, 0, v25
	v_add_u32_e32 v7, 0, v26
	v_add_u32_e32 v8, 0, v27
	v_add_u32_e32 v9, 0, v28
	s_add_u32 s30, s28, 0x10000
	s_addc_u32 s31, s29, 0
	v_lshl_add_u64 v[2:3], s[30:31], 0, v[198:199]
	v_lshl_add_u64 v[4:5], s[30:31], 0, v[200:201]
	s_add_u32 s30, s0, 0x10000
	s_addc_u32 s31, s1, 0
	global_load_dwordx4 v[182:185], v[2:3], off
	global_load_dwordx4 v[186:189], v[4:5], off
	v_lshl_add_u64 v[2:3], s[30:31], 0, v[198:199]
	v_lshl_add_u64 v[4:5], s[30:31], 0, v[200:201]
	global_load_dwordx4 v[194:197], v[2:3], off
	global_load_dwordx4 v[190:193], v[4:5], off
	s_cmp_gt_i32 s16, 0xfff00060
	s_cselect_b64 s[30:31], -1, 0
	s_cmp_lt_i32 s16, 0xfff00061
	v_add_u32_e32 v221, v6, v23
	v_add_u32_e32 v220, v7, v23
	v_add_u32_e32 v219, v8, v23
	v_add_u32_e32 v218, v9, v23
	s_cbranch_scc1 .LBB0_1210
	ds_read_b128 v[2:5], v221 offset:49152
	ds_read_b128 v[82:85], v223 offset:512
	ds_read_b128 v[86:89], v223 offset:544
	ds_read_b128 v[90:93], v223 offset:576
	ds_read_b128 v[94:97], v223 offset:608
	ds_read_b128 v[66:69], v223 offset:640
	ds_read_b128 v[6:9], v221 offset:57344
	ds_read_b128 v[70:73], v223 offset:672
	ds_read_b128 v[74:77], v223 offset:704
	ds_read_b128 v[78:81], v223 offset:736
	s_waitcnt lgkmcnt(5)
	s_setprio 1
	v_mfma_f32_32x32x16_bf16 v[82:97], v[2:5], v[162:165], v[82:97]
	ds_read_b128 v[2:5], v220 offset:49152
	s_waitcnt lgkmcnt(1)
	v_mfma_f32_32x32x16_bf16 v[66:81], v[6:9], v[162:165], v[66:81]
	s_waitcnt lgkmcnt(0)
	v_mfma_f32_32x32x16_bf16 v[82:97], v[2:5], v[158:161], v[82:97]
	ds_read_b128 v[2:5], v220 offset:57344
	s_waitcnt lgkmcnt(0)
	v_mfma_f32_32x32x16_bf16 v[66:81], v[2:5], v[158:161], v[66:81]
	ds_read_b128 v[2:5], v219 offset:49152
	s_waitcnt lgkmcnt(0)
	v_mfma_f32_32x32x16_bf16 v[82:97], v[2:5], v[154:157], v[82:97]
	ds_read_b128 v[2:5], v219 offset:57344
	s_waitcnt lgkmcnt(0)
	v_mfma_f32_32x32x16_bf16 v[66:81], v[2:5], v[154:157], v[66:81]
	ds_read_b128 v[2:5], v218 offset:49152
	s_waitcnt lgkmcnt(0)
	v_mfma_f32_32x32x16_bf16 v[82:97], v[2:5], v[150:153], v[82:97]
	ds_read_b128 v[2:5], v218 offset:57344
	s_waitcnt lgkmcnt(0)
	v_mfma_f32_32x32x16_bf16 v[66:81], v[2:5], v[150:153], v[66:81]
	ds_read_b128 v[2:5], v221 offset:49280
	s_waitcnt lgkmcnt(0)
	v_mfma_f32_32x32x16_bf16 v[82:97], v[2:5], v[146:149], v[82:97]
	ds_read_b128 v[2:5], v221 offset:57472
	s_waitcnt lgkmcnt(0)
	v_mfma_f32_32x32x16_bf16 v[66:81], v[2:5], v[146:149], v[66:81]
	ds_read_b128 v[2:5], v220 offset:49280
	s_waitcnt lgkmcnt(0)
	v_mfma_f32_32x32x16_bf16 v[82:97], v[2:5], v[142:145], v[82:97]
	ds_read_b128 v[2:5], v220 offset:57472
	s_waitcnt lgkmcnt(0)
	v_mfma_f32_32x32x16_bf16 v[66:81], v[2:5], v[142:145], v[66:81]
	ds_read_b128 v[2:5], v219 offset:49280
	s_waitcnt lgkmcnt(0)
	v_mfma_f32_32x32x16_bf16 v[82:97], v[2:5], v[138:141], v[82:97]
	ds_read_b128 v[2:5], v219 offset:57472
	s_waitcnt lgkmcnt(0)
	v_mfma_f32_32x32x16_bf16 v[66:81], v[2:5], v[138:141], v[66:81]
	ds_read_b128 v[2:5], v218 offset:49280
	s_waitcnt lgkmcnt(0)
	v_mfma_f32_32x32x16_bf16 v[82:97], v[2:5], v[134:137], v[82:97]
	ds_read_b128 v[2:5], v218 offset:57472
	s_waitcnt lgkmcnt(0)
	v_mfma_f32_32x32x16_bf16 v[66:81], v[2:5], v[134:137], v[66:81]
	s_setprio 0
	s_branch .LBB0_1211

.LBB0_1213:
.LBB0_1214:
	v_and_b32_e32 v215, 63, v18
	v_lshlrev_b32_e32 v3, 4, v215
	v_lshlrev_b32_e32 v2, 3, v215
	v_and_b32_e32 v3, 0xc0, v3
	v_lshlrev_b32_e32 v4, 1, v215
	v_and_or_b32 v3, v2, 24, v3
	v_and_b32_e32 v4, 32, v4
	v_and_b32_e32 v2, 0x100, v2
	s_cmp_lg_u32 0, -1
	v_or3_b32 v2, v3, v4, v2
	s_cselect_b32 s5, 0, 0
	v_add_u32_e32 v210, s5, v2
	s_and_b64 vcc, exec, s[40:41]
	s_cbranch_vccnz .LBB0_1217
	ds_read_b64_tr_b16 v[2:3], v210 offset:0
	ds_read_b64_tr_b16 v[4:5], v210 offset:0x800
	ds_read_b64_tr_b16 v[18:19], v210 offset:0x1000
	ds_read_b64_tr_b16 v[20:21], v210 offset:0x1800
	ds_read_b64_tr_b16 v[22:23], v210 offset:0x2000
	ds_read_b64_tr_b16 v[24:25], v210 offset:0x2800
	ds_read_b64_tr_b16 v[26:27], v210 offset:0x3000
	ds_read_b64_tr_b16 v[28:29], v210 offset:0x3800
	s_waitcnt lgkmcnt(0)
	s_nop 0
	s_setprio 1
	v_mfma_f32_32x32x16_bf16 v[2:17], v[166:169], v[2:5], 0
	v_mfma_f32_32x32x16_bf16 v[2:17], v[170:173], v[18:21], v[2:17]
	s_setprio 0
	ds_read_b64_tr_b16 v[18:19], v210 offset:0x200
	ds_read_b64_tr_b16 v[20:21], v210 offset:0xa00
	ds_read_b64_tr_b16 v[34:35], v210 offset:0x1200
	ds_read_b64_tr_b16 v[36:37], v210 offset:0x1a00
	ds_read_b64_tr_b16 v[38:39], v210 offset:0x2200
	ds_read_b64_tr_b16 v[40:41], v210 offset:0x2a00
	ds_read_b64_tr_b16 v[42:43], v210 offset:0x3200
	s_setprio 1
	v_mfma_f32_32x32x16_bf16 v[2:17], v[174:177], v[22:25], v[2:17]
	ds_read_b64_tr_b16 v[44:45], v210 offset:0x3a00
	s_waitcnt lgkmcnt(0)
	v_mfma_f32_32x32x16_bf16 v[2:17], v[178:181], v[26:29], v[2:17]
	v_mfma_f32_32x32x16_bf16 v[18:33], v[166:169], v[18:21], 0
	v_mfma_f32_32x32x16_bf16 v[18:33], v[170:173], v[34:37], v[18:33]
	s_setprio 0
	ds_read_b64_tr_b16 v[34:35], v210 offset:0x400
	ds_read_b64_tr_b16 v[36:37], v210 offset:0xc00
	ds_read_b64_tr_b16 v[50:51], v210 offset:0x1400
	ds_read_b64_tr_b16 v[52:53], v210 offset:0x1c00
	ds_read_b64_tr_b16 v[54:55], v210 offset:0x2400
	ds_read_b64_tr_b16 v[56:57], v210 offset:0x2c00
	ds_read_b64_tr_b16 v[58:59], v210 offset:0x3400
	s_setprio 1
	v_mfma_f32_32x32x16_bf16 v[18:33], v[174:177], v[38:41], v[18:33]
	ds_read_b64_tr_b16 v[60:61], v210 offset:0x3c00
	s_waitcnt lgkmcnt(0)
	v_mfma_f32_32x32x16_bf16 v[18:33], v[178:181], v[42:45], v[18:33]
	v_mfma_f32_32x32x16_bf16 v[34:49], v[166:169], v[34:37], 0
	v_mfma_f32_32x32x16_bf16 v[34:49], v[170:173], v[50:53], v[34:49]
	s_setprio 0
	ds_read_b64_tr_b16 v[50:51], v210 offset:0x600
	ds_read_b64_tr_b16 v[52:53], v210 offset:0xe00
	ds_read_b64_tr_b16 v[228:229], v210 offset:0x1600
	ds_read_b64_tr_b16 v[230:231], v210 offset:0x1e00
	ds_read_b64_tr_b16 v[232:233], v210 offset:0x2600
	ds_read_b64_tr_b16 v[234:235], v210 offset:0x2e00
	ds_read_b64_tr_b16 v[236:237], v210 offset:0x3600
	s_setprio 1
	v_mfma_f32_32x32x16_bf16 v[34:49], v[174:177], v[54:57], v[34:49]
	ds_read_b64_tr_b16 v[238:239], v210 offset:0x3e00
	s_waitcnt lgkmcnt(0)
	v_mfma_f32_32x32x16_bf16 v[34:49], v[178:181], v[58:61], v[34:49]
	v_mfma_f32_32x32x16_bf16 v[50:65], v[166:169], v[50:53], 0
	v_mfma_f32_32x32x16_bf16 v[50:65], v[170:173], v[228:231], v[50:65]
	v_mfma_f32_32x32x16_bf16 v[50:65], v[174:177], v[232:235], v[50:65]
	v_mfma_f32_32x32x16_bf16 v[50:65], v[178:181], v[236:239], v[50:65]
	s_setprio 0
	s_andn2_b64 vcc, exec, s[30:31]
	s_mov_b64 s[30:31], 0
	s_cbranch_vccz .LBB0_1218

.LBB0_1229:
	s_waitcnt lgkmcnt(0)
	s_barrier
	v_lshl_add_u64 v[182:183], s[28:29], 0, v[198:199]
	v_lshl_add_u64 v[184:185], s[28:29], 0, v[200:201]
	global_load_dwordx4 v[186:189], v[182:183], off
	global_load_dwordx4 v[190:193], v[184:185], off
	v_lshl_add_u64 v[182:183], s[0:1], 0, v[198:199]
	v_lshl_add_u64 v[184:185], s[0:1], 0, v[200:201]
	global_load_dwordx4 v[194:197], v[182:183], off
	s_nop 0
	global_load_dwordx4 v[182:185], v[184:185], off
	s_cmp_gt_i32 s16, 0xfff00020
	s_cselect_b64 s[0:1], -1, 0
	s_cmp_lt_i32 s16, 0xfff00021
	s_cbranch_scc1 .LBB0_1231
	ds_read_b128 v[102:105], v221 offset:32768
	ds_read_b128 v[114:117], v223 offset:256
	ds_read_b128 v[118:121], v223 offset:288
	ds_read_b128 v[122:125], v223 offset:320
	ds_read_b128 v[126:129], v223 offset:352
	ds_read_b128 v[98:101], v223 offset:384
	ds_read_b128 v[228:231], v221 offset:40960
	s_waitcnt lgkmcnt(2)
	s_setprio 1
	v_mfma_f32_32x32x16_bf16 v[114:129], v[102:105], v[162:165], v[114:129]
	ds_read_b128 v[102:105], v223 offset:416
	ds_read_b128 v[106:109], v223 offset:448
	ds_read_b128 v[110:113], v223 offset:480
	s_waitcnt lgkmcnt(0)
	v_mfma_f32_32x32x16_bf16 v[98:113], v[228:231], v[162:165], v[98:113]
	ds_read_b128 v[228:231], v220 offset:32768
	s_waitcnt lgkmcnt(0)
	v_mfma_f32_32x32x16_bf16 v[114:129], v[228:231], v[158:161], v[114:129]
	ds_read_b128 v[228:231], v220 offset:40960
	s_waitcnt lgkmcnt(0)
	v_mfma_f32_32x32x16_bf16 v[98:113], v[228:231], v[158:161], v[98:113]
	ds_read_b128 v[228:231], v219 offset:32768
	s_waitcnt lgkmcnt(0)
	v_mfma_f32_32x32x16_bf16 v[114:129], v[228:231], v[154:157], v[114:129]
	ds_read_b128 v[228:231], v219 offset:40960
	s_waitcnt lgkmcnt(0)
	v_mfma_f32_32x32x16_bf16 v[98:113], v[228:231], v[154:157], v[98:113]
	ds_read_b128 v[228:231], v218 offset:32768
	s_waitcnt lgkmcnt(0)
	v_mfma_f32_32x32x16_bf16 v[114:129], v[228:231], v[150:153], v[114:129]
	ds_read_b128 v[228:231], v218 offset:40960
	s_waitcnt lgkmcnt(0)
	v_mfma_f32_32x32x16_bf16 v[98:113], v[228:231], v[150:153], v[98:113]
	ds_read_b128 v[228:231], v221 offset:32896
	s_waitcnt lgkmcnt(0)
	v_mfma_f32_32x32x16_bf16 v[114:129], v[228:231], v[146:149], v[114:129]
	ds_read_b128 v[228:231], v221 offset:41088
	s_waitcnt lgkmcnt(0)
	v_mfma_f32_32x32x16_bf16 v[98:113], v[228:231], v[146:149], v[98:113]
	ds_read_b128 v[228:231], v220 offset:32896
	s_waitcnt lgkmcnt(0)
	v_mfma_f32_32x32x16_bf16 v[114:129], v[228:231], v[142:145], v[114:129]
	ds_read_b128 v[228:231], v220 offset:41088
	s_waitcnt lgkmcnt(0)
	v_mfma_f32_32x32x16_bf16 v[98:113], v[228:231], v[142:145], v[98:113]
	ds_read_b128 v[228:231], v219 offset:32896
	s_waitcnt lgkmcnt(0)
	v_mfma_f32_32x32x16_bf16 v[114:129], v[228:231], v[138:141], v[114:129]
	ds_read_b128 v[228:231], v219 offset:41088
	s_waitcnt lgkmcnt(0)
	v_mfma_f32_32x32x16_bf16 v[98:113], v[228:231], v[138:141], v[98:113]
	ds_read_b128 v[228:231], v218 offset:32896
	s_waitcnt lgkmcnt(0)
	v_mfma_f32_32x32x16_bf16 v[114:129], v[228:231], v[134:137], v[114:129]
	ds_read_b128 v[228:231], v218 offset:41088
	s_waitcnt lgkmcnt(0)
	v_mfma_f32_32x32x16_bf16 v[98:113], v[228:231], v[134:137], v[98:113]
	s_setprio 0

.LBB0_1233:
	s_and_b64 vcc, exec, s[42:43]
	s_cbranch_vccnz .LBB0_1235
	ds_read_b64_tr_b16 v[228:229], v210 offset:0x4000
	ds_read_b64_tr_b16 v[230:231], v210 offset:0x4800
	ds_read_b64_tr_b16 v[232:233], v210 offset:0x5000
	ds_read_b64_tr_b16 v[234:235], v210 offset:0x5800
	ds_read_b64_tr_b16 v[236:237], v210 offset:0x6000
	ds_read_b64_tr_b16 v[238:239], v210 offset:0x6800
	ds_read_b64_tr_b16 v[240:241], v210 offset:0x7000
	ds_read_b64_tr_b16 v[242:243], v210 offset:0x7800
	s_waitcnt lgkmcnt(0)
	s_nop 0
	s_setprio 1
	v_mfma_f32_32x32x16_bf16 v[2:17], v[166:169], v[228:231], v[2:17]
	ds_read_b64_tr_b16 v[228:229], v210 offset:0x4200
	ds_read_b64_tr_b16 v[230:231], v210 offset:0x4a00
	v_mfma_f32_32x32x16_bf16 v[2:17], v[170:173], v[232:235], v[2:17]
	ds_read_b64_tr_b16 v[232:233], v210 offset:0x5200
	ds_read_b64_tr_b16 v[234:235], v210 offset:0x5a00
	v_mfma_f32_32x32x16_bf16 v[2:17], v[174:177], v[236:239], v[2:17]
	ds_read_b64_tr_b16 v[236:237], v210 offset:0x6200
	ds_read_b64_tr_b16 v[238:239], v210 offset:0x6a00
	v_mfma_f32_32x32x16_bf16 v[2:17], v[178:181], v[240:243], v[2:17]
	ds_read_b64_tr_b16 v[240:241], v210 offset:0x7200
	ds_read_b64_tr_b16 v[242:243], v210 offset:0x7a00
	s_waitcnt lgkmcnt(0)
	v_mfma_f32_32x32x16_bf16 v[18:33], v[166:169], v[228:231], v[18:33]
	ds_read_b64_tr_b16 v[228:229], v210 offset:0x4400
	ds_read_b64_tr_b16 v[230:231], v210 offset:0x4c00
	v_mfma_f32_32x32x16_bf16 v[18:33], v[170:173], v[232:235], v[18:33]
	ds_read_b64_tr_b16 v[232:233], v210 offset:0x5400
	ds_read_b64_tr_b16 v[234:235], v210 offset:0x5c00
	v_mfma_f32_32x32x16_bf16 v[18:33], v[174:177], v[236:239], v[18:33]
	ds_read_b64_tr_b16 v[236:237], v210 offset:0x6400
	ds_read_b64_tr_b16 v[238:239], v210 offset:0x6c00
	v_mfma_f32_32x32x16_bf16 v[18:33], v[178:181], v[240:243], v[18:33]
	ds_read_b64_tr_b16 v[240:241], v210 offset:0x7400
	ds_read_b64_tr_b16 v[242:243], v210 offset:0x7c00
	s_waitcnt lgkmcnt(0)
	v_mfma_f32_32x32x16_bf16 v[34:49], v[166:169], v[228:231], v[34:49]
	ds_read_b64_tr_b16 v[228:229], v210 offset:0x4600
	ds_read_b64_tr_b16 v[230:231], v210 offset:0x4e00
	v_mfma_f32_32x32x16_bf16 v[34:49], v[170:173], v[232:235], v[34:49]
	ds_read_b64_tr_b16 v[232:233], v210 offset:0x5600
	ds_read_b64_tr_b16 v[234:235], v210 offset:0x5e00
	v_mfma_f32_32x32x16_bf16 v[34:49], v[174:177], v[236:239], v[34:49]
	ds_read_b64_tr_b16 v[236:237], v210 offset:0x6600
	ds_read_b64_tr_b16 v[238:239], v210 offset:0x6e00
	v_mfma_f32_32x32x16_bf16 v[34:49], v[178:181], v[240:243], v[34:49]
	ds_read_b64_tr_b16 v[240:241], v210 offset:0x7600
	ds_read_b64_tr_b16 v[242:243], v210 offset:0x7e00
	s_waitcnt lgkmcnt(0)
	v_mfma_f32_32x32x16_bf16 v[50:65], v[166:169], v[228:231], v[50:65]
	v_mfma_f32_32x32x16_bf16 v[50:65], v[170:173], v[232:235], v[50:65]
	v_mfma_f32_32x32x16_bf16 v[50:65], v[174:177], v[236:239], v[50:65]
	v_mfma_f32_32x32x16_bf16 v[50:65], v[178:181], v[240:243], v[50:65]
	s_setprio 0

.LBB0_1246:
	s_waitcnt lgkmcnt(0)
	s_barrier
	s_cmp_gt_i32 s16, 0xffefffe0
	s_cselect_b64 s[0:1], -1, 0
	s_cmp_lt_i32 s16, 0xffefffe1
	s_cbranch_scc1 .LBB0_1248
	v_add_u32_e32 v66, 0, v211
	v_add_u32_e32 v78, 0x10800, v66
	ds_read_b128 v[70:73], v221 offset:49152
	ds_read_b128 v[82:85], v78
	ds_read_b128 v[86:89], v78 offset:32
	ds_read_b128 v[90:93], v78 offset:64
	ds_read_b128 v[94:97], v78 offset:96
	ds_read_b128 v[166:169], v221 offset:57344
	ds_read_b128 v[66:69], v78 offset:128
	s_waitcnt lgkmcnt(2)
	s_setprio 1
	v_mfma_f32_32x32x16_bf16 v[82:97], v[70:73], v[162:165], v[82:97]
	ds_read_b128 v[70:73], v78 offset:160
	ds_read_b128 v[74:77], v78 offset:192
	ds_read_b128 v[78:81], v78 offset:224
	s_waitcnt lgkmcnt(0)
	v_mfma_f32_32x32x16_bf16 v[66:81], v[166:169], v[162:165], v[66:81]
	ds_read_b128 v[162:165], v220 offset:49152
	s_waitcnt lgkmcnt(0)
	v_mfma_f32_32x32x16_bf16 v[82:97], v[162:165], v[158:161], v[82:97]
	ds_read_b128 v[162:165], v220 offset:57344
	s_waitcnt lgkmcnt(0)
	v_mfma_f32_32x32x16_bf16 v[66:81], v[162:165], v[158:161], v[66:81]
	ds_read_b128 v[158:161], v219 offset:49152
	s_waitcnt lgkmcnt(0)
	v_mfma_f32_32x32x16_bf16 v[82:97], v[158:161], v[154:157], v[82:97]
	ds_read_b128 v[158:161], v219 offset:57344
	s_waitcnt lgkmcnt(0)
	v_mfma_f32_32x32x16_bf16 v[66:81], v[158:161], v[154:157], v[66:81]
	ds_read_b128 v[154:157], v218 offset:49152
	s_waitcnt lgkmcnt(0)
	v_mfma_f32_32x32x16_bf16 v[82:97], v[154:157], v[150:153], v[82:97]
	ds_read_b128 v[154:157], v218 offset:57344
	s_waitcnt lgkmcnt(0)
	v_mfma_f32_32x32x16_bf16 v[66:81], v[154:157], v[150:153], v[66:81]
	ds_read_b128 v[150:153], v221 offset:49280
	s_waitcnt lgkmcnt(0)
	v_mfma_f32_32x32x16_bf16 v[82:97], v[150:153], v[146:149], v[82:97]
	ds_read_b128 v[150:153], v221 offset:57472
	s_waitcnt lgkmcnt(0)
	v_mfma_f32_32x32x16_bf16 v[66:81], v[150:153], v[146:149], v[66:81]
	ds_read_b128 v[146:149], v220 offset:49280
	s_waitcnt lgkmcnt(0)
	v_mfma_f32_32x32x16_bf16 v[82:97], v[146:149], v[142:145], v[82:97]
	ds_read_b128 v[146:149], v220 offset:57472
	s_waitcnt lgkmcnt(0)
	v_mfma_f32_32x32x16_bf16 v[66:81], v[146:149], v[142:145], v[66:81]
	ds_read_b128 v[142:145], v219 offset:49280
	s_waitcnt lgkmcnt(0)
	v_mfma_f32_32x32x16_bf16 v[82:97], v[142:145], v[138:141], v[82:97]
	ds_read_b128 v[142:145], v219 offset:57472
	s_waitcnt lgkmcnt(0)
	v_mfma_f32_32x32x16_bf16 v[66:81], v[142:145], v[138:141], v[66:81]
	ds_read_b128 v[138:141], v218 offset:49280
	s_waitcnt lgkmcnt(0)
	v_mfma_f32_32x32x16_bf16 v[82:97], v[138:141], v[134:137], v[82:97]
	ds_read_b128 v[138:141], v218 offset:57472
	s_waitcnt lgkmcnt(0)
	v_mfma_f32_32x32x16_bf16 v[66:81], v[138:141], v[134:137], v[66:81]
	s_setprio 0
.LBB0_1248:
	v_lshl_add_u64 v[134:135], s[26:27], 0, v[198:199]
	v_lshl_add_u64 v[138:139], s[26:27], 0, v[200:201]
	global_load_dwordx4 v[134:137], v[134:135], off
	s_nop 0
	global_load_dwordx4 v[138:141], v[138:139], off
	s_and_b64 vcc, exec, s[42:43]
	s_cbranch_vccnz .LBB0_1250
	v_exp_f32_e32 v142, v98
	v_add_f32_e32 v98, 0, v114
	v_add_f32_e32 v98, v115, v98
	v_add_f32_e32 v98, v116, v98
	v_add_f32_e32 v98, v117, v98
	v_add_f32_e32 v98, v118, v98
	v_add_f32_e32 v98, v119, v98
	v_add_f32_e32 v98, v120, v98
	v_add_f32_e32 v98, v121, v98
	v_add_f32_e32 v98, v122, v98
	v_add_f32_e32 v98, v123, v98
	v_add_f32_e32 v98, v124, v98
	v_add_f32_e32 v98, v125, v98
	v_add_f32_e32 v98, v126, v98
	v_exp_f32_e32 v143, v99
	v_add_f32_e32 v98, v127, v98
	v_exp_f32_e32 v144, v100
	v_add_f32_e32 v98, v128, v98
	v_exp_f32_e32 v145, v101
	v_add_f32_e32 v98, v129, v98
	v_exp_f32_e32 v146, v102
	v_add_f32_e32 v98, v142, v98
	v_exp_f32_e32 v147, v103
	v_add_f32_e32 v98, v143, v98
	v_exp_f32_e32 v148, v104
	v_add_f32_e32 v98, v144, v98
	v_exp_f32_e32 v149, v105
	v_add_f32_e32 v98, v145, v98
	v_exp_f32_e32 v150, v106
	v_add_f32_e32 v98, v146, v98
	v_exp_f32_e32 v151, v107
	v_add_f32_e32 v98, v147, v98
	v_exp_f32_e32 v152, v108
	v_add_f32_e32 v98, v148, v98
	v_exp_f32_e32 v153, v109
	v_add_f32_e32 v98, v149, v98
	v_exp_f32_e32 v154, v110
	v_add_f32_e32 v98, v150, v98
	v_exp_f32_e32 v155, v111
	v_add_f32_e32 v98, v151, v98
	v_exp_f32_e32 v156, v112
	v_add_f32_e32 v98, v152, v98
	v_exp_f32_e32 v113, v113
	v_add_f32_e32 v98, v153, v98
	v_add_f32_e32 v98, v154, v98
	v_add_f32_e32 v98, v155, v98
	v_add_f32_e32 v98, v156, v98
	v_add_f32_e32 v98, v113, v98
	v_mov_b32_e32 v99, v98
	s_nop 1
	v_permlane32_swap_b32_e32 v98, v99
	v_add_f32_e32 v157, v98, v99
	v_cvt_pk_bf16_f32 v98, v114, v115
	v_cvt_pk_bf16_f32 v99, v116, v117
	v_cvt_pk_bf16_f32 v100, v118, v119
	v_cvt_pk_bf16_f32 v101, v120, v121
	v_cvt_pk_bf16_f32 v102, v122, v123
	v_cvt_pk_bf16_f32 v103, v124, v125
	v_cvt_pk_bf16_f32 v104, v126, v127
	v_cvt_pk_bf16_f32 v105, v128, v129
	v_cvt_pk_bf16_f32 v106, v142, v143
	v_cvt_pk_bf16_f32 v107, v144, v145
	v_cvt_pk_bf16_f32 v108, v146, v147
	v_cvt_pk_bf16_f32 v109, v148, v149
	v_cvt_pk_bf16_f32 v110, v150, v151
	v_cvt_pk_bf16_f32 v111, v152, v153
	v_cvt_pk_bf16_f32 v112, v154, v155
	v_cvt_pk_bf16_f32 v113, v156, v113
	v_fmac_f32_e32 v157, v212, v217
	v_permlane32_swap_b32_e32 v98, v100
	v_permlane32_swap_b32_e32 v99, v101
	v_permlane32_swap_b32_e32 v102, v104
	v_permlane32_swap_b32_e32 v103, v105
	v_permlane32_swap_b32_e32 v106, v108
	v_permlane32_swap_b32_e32 v107, v109
	v_permlane32_swap_b32_e32 v110, v112
	v_permlane32_swap_b32_e32 v111, v113
	ds_read_b64_tr_b16 v[114:115], v210 offset:0
	ds_read_b64_tr_b16 v[116:117], v210 offset:0x800
	ds_read_b64_tr_b16 v[118:119], v210 offset:0x1000
	ds_read_b64_tr_b16 v[120:121], v210 offset:0x1800
	ds_read_b64_tr_b16 v[122:123], v210 offset:0x2000
	ds_read_b64_tr_b16 v[124:125], v210 offset:0x2800
	ds_read_b64_tr_b16 v[126:127], v210 offset:0x3000
	ds_read_b64_tr_b16 v[128:129], v210 offset:0x3800
	s_waitcnt lgkmcnt(0)
	s_nop 0
	s_setprio 1
	v_mfma_f32_32x32x16_bf16 v[2:17], v[98:101], v[114:117], v[2:17]
	ds_read_b64_tr_b16 v[114:115], v210 offset:0x200
	ds_read_b64_tr_b16 v[116:117], v210 offset:0xa00
	v_mfma_f32_32x32x16_bf16 v[2:17], v[102:105], v[118:121], v[2:17]
	ds_read_b64_tr_b16 v[118:119], v210 offset:0x1200
	ds_read_b64_tr_b16 v[120:121], v210 offset:0x1a00
	v_mfma_f32_32x32x16_bf16 v[2:17], v[106:109], v[122:125], v[2:17]
	ds_read_b64_tr_b16 v[122:123], v210 offset:0x2200
	ds_read_b64_tr_b16 v[124:125], v210 offset:0x2a00
	v_mfma_f32_32x32x16_bf16 v[2:17], v[110:113], v[126:129], v[2:17]
	ds_read_b64_tr_b16 v[126:127], v210 offset:0x3200
	ds_read_b64_tr_b16 v[128:129], v210 offset:0x3a00
	s_waitcnt lgkmcnt(0)
	v_mfma_f32_32x32x16_bf16 v[18:33], v[98:101], v[114:117], v[18:33]
	ds_read_b64_tr_b16 v[114:115], v210 offset:0x400
	ds_read_b64_tr_b16 v[116:117], v210 offset:0xc00
	v_mfma_f32_32x32x16_bf16 v[18:33], v[102:105], v[118:121], v[18:33]
	ds_read_b64_tr_b16 v[118:119], v210 offset:0x1400
	ds_read_b64_tr_b16 v[120:121], v210 offset:0x1c00
	v_mfma_f32_32x32x16_bf16 v[18:33], v[106:109], v[122:125], v[18:33]
	ds_read_b64_tr_b16 v[122:123], v210 offset:0x2400
	ds_read_b64_tr_b16 v[124:125], v210 offset:0x2c00
	v_mfma_f32_32x32x16_bf16 v[18:33], v[110:113], v[126:129], v[18:33]
	ds_read_b64_tr_b16 v[126:127], v210 offset:0x3400
	ds_read_b64_tr_b16 v[128:129], v210 offset:0x3c00
	s_waitcnt lgkmcnt(0)
	v_mfma_f32_32x32x16_bf16 v[34:49], v[98:101], v[114:117], v[34:49]
	ds_read_b64_tr_b16 v[114:115], v210 offset:0x600
	ds_read_b64_tr_b16 v[116:117], v210 offset:0xe00
	v_mfma_f32_32x32x16_bf16 v[34:49], v[102:105], v[118:121], v[34:49]
	ds_read_b64_tr_b16 v[118:119], v210 offset:0x1600
	ds_read_b64_tr_b16 v[120:121], v210 offset:0x1e00
	v_mfma_f32_32x32x16_bf16 v[34:49], v[106:109], v[122:125], v[34:49]
	ds_read_b64_tr_b16 v[122:123], v210 offset:0x2600
	ds_read_b64_tr_b16 v[124:125], v210 offset:0x2e00
	v_mfma_f32_32x32x16_bf16 v[34:49], v[110:113], v[126:129], v[34:49]
	ds_read_b64_tr_b16 v[126:127], v210 offset:0x3600
	ds_read_b64_tr_b16 v[128:129], v210 offset:0x3e00
	s_waitcnt lgkmcnt(0)
	v_mfma_f32_32x32x16_bf16 v[50:65], v[98:101], v[114:117], v[50:65]
	v_mov_b32_e32 v212, v157
	v_mfma_f32_32x32x16_bf16 v[50:65], v[102:105], v[118:121], v[50:65]
	v_mfma_f32_32x32x16_bf16 v[50:65], v[106:109], v[122:125], v[50:65]
	v_mfma_f32_32x32x16_bf16 v[50:65], v[110:113], v[126:129], v[50:65]
	s_setprio 0

.LBB0_1261:
	v_exp_f32_e32 v98, v66
	v_add_f32_e32 v66, 0, v82
	v_add_f32_e32 v66, v83, v66
	v_add_f32_e32 v66, v84, v66
	v_add_f32_e32 v66, v85, v66
	v_add_f32_e32 v66, v86, v66
	v_add_f32_e32 v66, v87, v66
	v_add_f32_e32 v66, v88, v66
	v_add_f32_e32 v66, v89, v66
	v_add_f32_e32 v66, v90, v66
	v_add_f32_e32 v66, v91, v66
	v_add_f32_e32 v66, v92, v66
	v_add_f32_e32 v66, v93, v66
	v_add_f32_e32 v66, v94, v66
	v_exp_f32_e32 v99, v67
	v_add_f32_e32 v66, v95, v66
	v_exp_f32_e32 v100, v68
	v_add_f32_e32 v66, v96, v66
	v_exp_f32_e32 v101, v69
	v_add_f32_e32 v66, v97, v66
	v_exp_f32_e32 v102, v70
	v_add_f32_e32 v66, v98, v66
	v_exp_f32_e32 v103, v71
	v_add_f32_e32 v66, v99, v66
	v_exp_f32_e32 v104, v72
	v_add_f32_e32 v66, v100, v66
	v_exp_f32_e32 v105, v73
	v_add_f32_e32 v66, v101, v66
	v_exp_f32_e32 v106, v74
	v_add_f32_e32 v66, v102, v66
	v_exp_f32_e32 v107, v75
	v_add_f32_e32 v66, v103, v66
	v_exp_f32_e32 v108, v76
	v_add_f32_e32 v66, v104, v66
	v_exp_f32_e32 v109, v77
	v_add_f32_e32 v66, v105, v66
	v_exp_f32_e32 v110, v78
	v_add_f32_e32 v66, v106, v66
	v_exp_f32_e32 v111, v79
	v_add_f32_e32 v66, v107, v66
	v_exp_f32_e32 v112, v80
	v_add_f32_e32 v66, v108, v66
	v_exp_f32_e32 v81, v81
	v_add_f32_e32 v66, v109, v66
	v_add_f32_e32 v66, v110, v66
	v_add_f32_e32 v66, v111, v66
	v_add_f32_e32 v66, v112, v66
	v_add_f32_e32 v66, v81, v66
	v_mov_b32_e32 v67, v66
	s_nop 1
	v_permlane32_swap_b32_e32 v66, v67
	v_add_f32_e32 v113, v66, v67
	v_cvt_pk_bf16_f32 v66, v82, v83
	v_cvt_pk_bf16_f32 v67, v84, v85
	v_cvt_pk_bf16_f32 v68, v86, v87
	v_cvt_pk_bf16_f32 v69, v88, v89
	v_cvt_pk_bf16_f32 v70, v90, v91
	v_cvt_pk_bf16_f32 v71, v92, v93
	v_cvt_pk_bf16_f32 v72, v94, v95
	v_cvt_pk_bf16_f32 v73, v96, v97
	v_cvt_pk_bf16_f32 v74, v98, v99
	v_cvt_pk_bf16_f32 v75, v100, v101
	v_cvt_pk_bf16_f32 v76, v102, v103
	v_cvt_pk_bf16_f32 v77, v104, v105
	v_cvt_pk_bf16_f32 v78, v106, v107
	v_cvt_pk_bf16_f32 v79, v108, v109
	v_cvt_pk_bf16_f32 v80, v110, v111
	v_cvt_pk_bf16_f32 v81, v112, v81
	v_fmac_f32_e32 v113, v212, v222
	v_permlane32_swap_b32_e32 v66, v68
	v_permlane32_swap_b32_e32 v67, v69
	v_permlane32_swap_b32_e32 v70, v72
	v_permlane32_swap_b32_e32 v71, v73
	v_permlane32_swap_b32_e32 v74, v76
	v_permlane32_swap_b32_e32 v75, v77
	v_permlane32_swap_b32_e32 v78, v80
	v_permlane32_swap_b32_e32 v79, v81
	ds_read_b64_tr_b16 v[82:83], v210 offset:0x4000
	ds_read_b64_tr_b16 v[84:85], v210 offset:0x4800
	ds_read_b64_tr_b16 v[86:87], v210 offset:0x5000
	ds_read_b64_tr_b16 v[88:89], v210 offset:0x5800
	ds_read_b64_tr_b16 v[90:91], v210 offset:0x6000
	ds_read_b64_tr_b16 v[92:93], v210 offset:0x6800
	ds_read_b64_tr_b16 v[94:95], v210 offset:0x7000
	ds_read_b64_tr_b16 v[96:97], v210 offset:0x7800
	s_waitcnt lgkmcnt(0)
	s_nop 0
	s_setprio 1
	v_mfma_f32_32x32x16_bf16 v[2:17], v[66:69], v[82:85], v[2:17]
	ds_read_b64_tr_b16 v[82:83], v210 offset:0x4200
	ds_read_b64_tr_b16 v[84:85], v210 offset:0x4a00
	v_mfma_f32_32x32x16_bf16 v[2:17], v[70:73], v[86:89], v[2:17]
	ds_read_b64_tr_b16 v[86:87], v210 offset:0x5200
	ds_read_b64_tr_b16 v[88:89], v210 offset:0x5a00
	v_mfma_f32_32x32x16_bf16 v[2:17], v[74:77], v[90:93], v[2:17]
	ds_read_b64_tr_b16 v[90:91], v210 offset:0x6200
	ds_read_b64_tr_b16 v[92:93], v210 offset:0x6a00
	v_mfma_f32_32x32x16_bf16 v[2:17], v[78:81], v[94:97], v[2:17]
	ds_read_b64_tr_b16 v[94:95], v210 offset:0x7200
	ds_read_b64_tr_b16 v[96:97], v210 offset:0x7a00
	s_waitcnt lgkmcnt(0)
	v_mfma_f32_32x32x16_bf16 v[18:33], v[66:69], v[82:85], v[18:33]
	ds_read_b64_tr_b16 v[82:83], v210 offset:0x4400
	ds_read_b64_tr_b16 v[84:85], v210 offset:0x4c00
	v_mfma_f32_32x32x16_bf16 v[18:33], v[70:73], v[86:89], v[18:33]
	ds_read_b64_tr_b16 v[86:87], v210 offset:0x5400
	ds_read_b64_tr_b16 v[88:89], v210 offset:0x5c00
	v_mfma_f32_32x32x16_bf16 v[18:33], v[74:77], v[90:93], v[18:33]
	ds_read_b64_tr_b16 v[90:91], v210 offset:0x6400
	ds_read_b64_tr_b16 v[92:93], v210 offset:0x6c00
	v_mfma_f32_32x32x16_bf16 v[18:33], v[78:81], v[94:97], v[18:33]
	ds_read_b64_tr_b16 v[94:95], v210 offset:0x7400
	ds_read_b64_tr_b16 v[96:97], v210 offset:0x7c00
	s_waitcnt lgkmcnt(0)
	v_mfma_f32_32x32x16_bf16 v[34:49], v[66:69], v[82:85], v[34:49]
	ds_read_b64_tr_b16 v[82:83], v210 offset:0x4600
	ds_read_b64_tr_b16 v[84:85], v210 offset:0x4e00
	v_mfma_f32_32x32x16_bf16 v[34:49], v[70:73], v[86:89], v[34:49]
	ds_read_b64_tr_b16 v[86:87], v210 offset:0x5600
	ds_read_b64_tr_b16 v[88:89], v210 offset:0x5e00
	v_mfma_f32_32x32x16_bf16 v[34:49], v[74:77], v[90:93], v[34:49]
	ds_read_b64_tr_b16 v[90:91], v210 offset:0x6600
	ds_read_b64_tr_b16 v[92:93], v210 offset:0x6e00
	v_mfma_f32_32x32x16_bf16 v[34:49], v[78:81], v[94:97], v[34:49]
	ds_read_b64_tr_b16 v[94:95], v210 offset:0x7600
	ds_read_b64_tr_b16 v[96:97], v210 offset:0x7e00
	s_waitcnt lgkmcnt(0)
	v_mfma_f32_32x32x16_bf16 v[50:65], v[66:69], v[82:85], v[50:65]
	v_mov_b32_e32 v212, v113
	v_mfma_f32_32x32x16_bf16 v[50:65], v[70:73], v[86:89], v[50:65]
	v_mfma_f32_32x32x16_bf16 v[50:65], v[74:77], v[90:93], v[50:65]
	v_mfma_f32_32x32x16_bf16 v[50:65], v[78:81], v[94:97], v[50:65]
	s_setprio 0

.LBB0_1431:
	s_ashr_i32 s6, s4, 6
	v_lshrrev_b32_e32 v2, 5, v211
	s_lshl_b32 s59, s6, 5
	v_lshlrev_b32_e32 v212, 2, v2
	s_add_i32 s4, s59, s15
	v_sub_u32_e32 v4, v199, v212
	v_lshlrev_b32_e32 v204, 4, v2
	s_add_i32 s20, 0, 0x10800
	s_add_i32 s21, s9, -1
	v_add_u32_e32 v217, s4, v4
	v_add_u32_e32 v221, s20, v204
	s_lshl_b32 s20, s21, 6
	s_add_i32 s55, s4, 31
	s_cmp_gt_i32 s20, s55
	s_cbranch_scc1 .LBB0_1436
	v_lshl_add_u32 v2, s21, 8, v221
	v_lshlrev_b32_e32 v13, 4, v199
	s_movk_i32 s21, 0x70
	v_lshlrev_b32_e32 v12, 8, v199
	v_bitop3_b32 v4, v204, v13, s21 bitop3:0x78
	v_add3_u32 v14, 0, v4, v12
	ds_read_b128 v[4:7], v14 offset:32768
	ds_read_b128 v[116:119], v2
	ds_read_b128 v[120:123], v2 offset:32
	ds_read_b128 v[124:127], v2 offset:64
	ds_read_b128 v[128:131], v2 offset:96
	ds_read_b128 v[100:103], v2 offset:128
	ds_read_b128 v[8:11], v14 offset:40960
	ds_read_b128 v[104:107], v2 offset:160
	ds_read_b128 v[108:111], v2 offset:192
	ds_read_b128 v[112:115], v2 offset:224
	v_and_b32_e32 v2, 0x70, v13
	s_waitcnt lgkmcnt(5)
	s_setprio 1
	v_mfma_f32_32x32x16_bf16 v[116:131], v[4:7], v[160:163], v[116:131]
	v_bitop3_b32 v4, v204, v2, 32 bitop3:0x36
	v_add3_u32 v13, 0, v4, v12
	ds_read_b128 v[4:7], v13 offset:32768
	s_movk_i32 s21, 0x60
	s_waitcnt lgkmcnt(0)
	v_mfma_f32_32x32x16_bf16 v[116:131], v[4:7], v[156:159], v[116:131]
	ds_read_b128 v[4:7], v13 offset:40960
	v_mfma_f32_32x32x16_bf16 v[100:115], v[8:11], v[160:163], v[100:115]
	v_bitop3_b32 v8, v204, v2, 64 bitop3:0x36
	v_add3_u32 v8, 0, v8, v12
	v_bitop3_b32 v2, v204, v2, s21 bitop3:0x36
	v_add3_u32 v2, 0, v2, v12
	s_or_b32 s21, s20, 63
	s_cmp_le_i32 s21, s4
	s_waitcnt lgkmcnt(0)
	v_mfma_f32_32x32x16_bf16 v[100:115], v[4:7], v[156:159], v[100:115]
	ds_read_b128 v[4:7], v8 offset:32768
	s_waitcnt lgkmcnt(0)
	v_mfma_f32_32x32x16_bf16 v[116:131], v[4:7], v[152:155], v[116:131]
	ds_read_b128 v[4:7], v8 offset:40960
	s_waitcnt lgkmcnt(0)
	v_mfma_f32_32x32x16_bf16 v[100:115], v[4:7], v[152:155], v[100:115]
	ds_read_b128 v[4:7], v2 offset:32768
	s_waitcnt lgkmcnt(0)
	v_mfma_f32_32x32x16_bf16 v[116:131], v[4:7], v[148:151], v[116:131]
	ds_read_b128 v[4:7], v2 offset:40960
	s_waitcnt lgkmcnt(0)
	v_mfma_f32_32x32x16_bf16 v[100:115], v[4:7], v[148:151], v[100:115]
	ds_read_b128 v[4:7], v14 offset:32896
	s_waitcnt lgkmcnt(0)
	v_mfma_f32_32x32x16_bf16 v[116:131], v[4:7], v[144:147], v[116:131]
	ds_read_b128 v[4:7], v14 offset:41088
	s_waitcnt lgkmcnt(0)
	v_mfma_f32_32x32x16_bf16 v[100:115], v[4:7], v[144:147], v[100:115]
	ds_read_b128 v[4:7], v13 offset:32896
	s_waitcnt lgkmcnt(0)
	v_mfma_f32_32x32x16_bf16 v[116:131], v[4:7], v[140:143], v[116:131]
	ds_read_b128 v[4:7], v13 offset:41088
	s_waitcnt lgkmcnt(0)
	v_mfma_f32_32x32x16_bf16 v[100:115], v[4:7], v[140:143], v[100:115]
	ds_read_b128 v[4:7], v8 offset:32896
	s_waitcnt lgkmcnt(0)
	v_mfma_f32_32x32x16_bf16 v[116:131], v[4:7], v[136:139], v[116:131]
	ds_read_b128 v[4:7], v8 offset:41088
	s_waitcnt lgkmcnt(0)
	v_mfma_f32_32x32x16_bf16 v[100:115], v[4:7], v[136:139], v[100:115]
	ds_read_b128 v[4:7], v2 offset:32896
	s_waitcnt lgkmcnt(0)
	v_mfma_f32_32x32x16_bf16 v[116:131], v[4:7], v[132:135], v[116:131]
	ds_read_b128 v[4:7], v2 offset:41088
	s_waitcnt lgkmcnt(0)
	v_mfma_f32_32x32x16_bf16 v[100:115], v[4:7], v[132:135], v[100:115]
	s_setprio 0
	s_cbranch_scc1 .LBB0_1434
	v_subrev_u32_e32 v2, s20, v217
	v_cmp_gt_u32_e32 vcc, 2.0, v2
	v_add_u32_e32 v4, 0xbfffffe0, v2
	s_nop 4
	v_cndmask_b32_e32 v116, v209, v116, vcc
	v_cmp_lt_u32_e32 vcc, s54, v4
	v_add_u32_e32 v4, 0xbfffffff, v2
	s_nop 0
	v_cndmask_b32_e32 v100, v209, v100, vcc
	v_cmp_lt_u32_e32 vcc, s54, v4
	v_add_u32_e32 v4, 0xbfffffdf, v2
	s_nop 0
	v_cndmask_b32_e32 v117, v209, v117, vcc
	v_cmp_lt_u32_e32 vcc, s54, v4
	v_add_u32_e32 v4, 0xbffffffe, v2
	s_nop 0
	v_cndmask_b32_e32 v101, v209, v101, vcc
	v_cmp_lt_u32_e32 vcc, s54, v4
	v_add_u32_e32 v4, 0xbfffffde, v2
	s_nop 0
	v_cndmask_b32_e32 v118, v209, v118, vcc
	v_cmp_lt_u32_e32 vcc, s54, v4
	v_add_u32_e32 v4, 0xbffffffd, v2
	s_nop 0
	v_cndmask_b32_e32 v102, v209, v102, vcc
	v_cmp_lt_u32_e32 vcc, s54, v4
	v_add_u32_e32 v4, 0xbfffffdd, v2
	s_nop 0
	v_cndmask_b32_e32 v119, v209, v119, vcc
	v_cmp_lt_u32_e32 vcc, s54, v4
	v_add_u32_e32 v4, 0xbffffff8, v2
	s_nop 0
	v_cndmask_b32_e32 v103, v209, v103, vcc
	v_cmp_lt_u32_e32 vcc, s54, v4
	v_add_u32_e32 v4, 0xbfffffd8, v2
	s_nop 0
	v_cndmask_b32_e32 v120, v209, v120, vcc
	v_cmp_lt_u32_e32 vcc, s54, v4
	v_add_u32_e32 v4, 0xbffffff7, v2
	s_nop 0
	v_cndmask_b32_e32 v104, v209, v104, vcc
	v_cmp_lt_u32_e32 vcc, s54, v4
	v_add_u32_e32 v4, 0xbfffffd7, v2
	s_nop 0
	v_cndmask_b32_e32 v121, v209, v121, vcc
	v_cmp_lt_u32_e32 vcc, s54, v4
	v_add_u32_e32 v4, 0xbffffff6, v2
	s_nop 0
	v_cndmask_b32_e32 v105, v209, v105, vcc
	v_cmp_lt_u32_e32 vcc, s54, v4
	v_add_u32_e32 v4, 0xbfffffd6, v2
	s_nop 0
	v_cndmask_b32_e32 v122, v209, v122, vcc
	v_cmp_lt_u32_e32 vcc, s54, v4
	v_add_u32_e32 v4, 0xbffffff5, v2
	s_nop 0
	v_cndmask_b32_e32 v106, v209, v106, vcc
	v_cmp_lt_u32_e32 vcc, s54, v4
	v_add_u32_e32 v4, 0xbfffffd5, v2
	s_nop 0
	v_cndmask_b32_e32 v123, v209, v123, vcc
	v_cmp_lt_u32_e32 vcc, s54, v4
	v_add_u32_e32 v4, 0xbffffff0, v2
	s_nop 0
	v_cndmask_b32_e32 v107, v209, v107, vcc
	v_cmp_lt_u32_e32 vcc, s54, v4
	v_add_u32_e32 v4, 0xbfffffd0, v2
	s_nop 0
	v_cndmask_b32_e32 v124, v209, v124, vcc
	v_cmp_lt_u32_e32 vcc, s54, v4
	v_add_u32_e32 v4, 0xbfffffef, v2
	s_nop 0
	v_cndmask_b32_e32 v108, v209, v108, vcc
	v_cmp_lt_u32_e32 vcc, s54, v4
	v_add_u32_e32 v4, 0xbfffffcf, v2
	s_nop 0
	v_cndmask_b32_e32 v125, v209, v125, vcc
	v_cmp_lt_u32_e32 vcc, s54, v4
	v_add_u32_e32 v4, 0xbfffffee, v2
	s_nop 0
	v_cndmask_b32_e32 v109, v209, v109, vcc
	v_cmp_lt_u32_e32 vcc, s54, v4
	v_add_u32_e32 v4, 0xbfffffce, v2
	s_nop 0
	v_cndmask_b32_e32 v126, v209, v126, vcc
	v_cmp_lt_u32_e32 vcc, s54, v4
	v_add_u32_e32 v4, 0xbfffffed, v2
	s_nop 0
	v_cndmask_b32_e32 v110, v209, v110, vcc
	v_cmp_lt_u32_e32 vcc, s54, v4
	v_add_u32_e32 v4, 0xbfffffcd, v2
	s_nop 0
	v_cndmask_b32_e32 v127, v209, v127, vcc
	v_cmp_lt_u32_e32 vcc, s54, v4
	v_add_u32_e32 v4, 0xbfffffe8, v2
	s_nop 0
	v_cndmask_b32_e32 v111, v209, v111, vcc
	v_cmp_lt_u32_e32 vcc, s54, v4
	v_add_u32_e32 v4, 0xbfffffc8, v2
	s_nop 0
	v_cndmask_b32_e32 v128, v209, v128, vcc
	v_cmp_lt_u32_e32 vcc, s54, v4
	v_add_u32_e32 v4, 0xbfffffe7, v2
	s_nop 0
	v_cndmask_b32_e32 v112, v209, v112, vcc
	v_cmp_lt_u32_e32 vcc, s54, v4
	v_add_u32_e32 v4, 0xbfffffc7, v2
	s_nop 0
	v_cndmask_b32_e32 v129, v209, v129, vcc
	v_cmp_lt_u32_e32 vcc, s54, v4
	v_add_u32_e32 v4, 0xbfffffe6, v2
	s_nop 0
	v_cndmask_b32_e32 v113, v209, v113, vcc
	v_cmp_lt_u32_e32 vcc, s54, v4
	v_add_u32_e32 v4, 0xbfffffc6, v2
	s_nop 0
	v_cndmask_b32_e32 v130, v209, v130, vcc
	v_cmp_lt_u32_e32 vcc, s54, v4
	v_add_u32_e32 v4, 0xbfffffe5, v2
	v_add_u32_e32 v2, 0xbfffffc5, v2
	v_cndmask_b32_e32 v114, v209, v114, vcc
	v_cmp_lt_u32_e32 vcc, s54, v4
	s_nop 1
	v_cndmask_b32_e32 v131, v209, v131, vcc
	v_cmp_lt_u32_e32 vcc, s54, v2
	s_nop 1
	v_cndmask_b32_e32 v115, v209, v115, vcc

.LBB0_1444:
	s_add_i32 s20, s41, 64
	s_ashr_i32 s0, s20, 31
	s_mul_i32 s0, s0, s92
	s_mul_hi_u32 s1, s20, s92
	s_add_i32 s1, s1, s0
	s_mul_i32 s0, s20, s92
	s_lshl_b64 s[0:1], s[0:1], 1
	s_add_u32 s48, s30, s0
	s_addc_u32 s49, s31, s1
	s_add_u32 s0, s28, s0
	s_addc_u32 s1, s29, s1
	s_waitcnt vmcnt(3)
	v_lshl_add_u64 v[180:181], s[48:49], 0, v[2:3]
	s_waitcnt vmcnt(2)
	v_lshl_add_u64 v[184:185], s[48:49], 0, v[206:207]
	s_waitcnt vmcnt(1)
	v_lshl_add_u64 v[188:189], s[0:1], 0, v[2:3]
	s_waitcnt vmcnt(0)
	v_lshl_add_u64 v[192:193], s[0:1], 0, v[206:207]
	global_load_dwordx4 v[180:183], v[180:181], off
	s_nop 0
	global_load_dwordx4 v[184:187], v[184:185], off
	s_nop 0
	global_load_dwordx4 v[188:191], v[188:189], off
	s_nop 0
	global_load_dwordx4 v[192:195], v[192:193], off
	s_add_i32 s21, s41, 0x80
	s_cmp_le_i32 s21, s55
	s_cselect_b64 s[0:1], -1, 0
	s_cmp_gt_i32 s21, s55
	v_add_u32_e32 v196, 0, v225
	s_cbranch_scc1 .LBB0_1446
	v_add_u32_e32 v68, 0x10600, v196
	v_add_u32_e32 v69, 0x10680, v196
	v_add_u32_e32 v72, 0x10620, v196
	ds_read_b128 v[84:87], v68
	ds_read_b128 v[68:71], v69
	ds_read_b128 v[88:91], v72
	ds_read_b128 v[76:79], v227 offset:49152
	v_add_u32_e32 v72, 0x10640, v196
	ds_read_b128 v[92:95], v72
	ds_read_b128 v[232:235], v227 offset:57344
	v_add_u32_e32 v72, 0x10660, v196
	ds_read_b128 v[96:99], v72
	v_add_u32_e32 v72, 0x106a0, v196
	v_add_u32_e32 v80, 0x106c0, v196
	ds_read_b128 v[72:75], v72
	s_waitcnt lgkmcnt(1)
	s_setprio 1
	v_mfma_f32_32x32x16_bf16 v[84:99], v[76:79], v[160:163], v[84:99]
	ds_read_b128 v[76:79], v80
	v_add_u32_e32 v80, 0x106e0, v196
	ds_read_b128 v[80:83], v80
	s_waitcnt lgkmcnt(0)
	v_mfma_f32_32x32x16_bf16 v[68:83], v[232:235], v[160:163], v[68:83]
	ds_read_b128 v[232:235], v228 offset:49152
	s_waitcnt lgkmcnt(0)
	v_mfma_f32_32x32x16_bf16 v[84:99], v[232:235], v[156:159], v[84:99]
	ds_read_b128 v[232:235], v228 offset:57344
	s_waitcnt lgkmcnt(0)
	v_mfma_f32_32x32x16_bf16 v[68:83], v[232:235], v[156:159], v[68:83]
	ds_read_b128 v[232:235], v229 offset:49152
	s_waitcnt lgkmcnt(0)
	v_mfma_f32_32x32x16_bf16 v[84:99], v[232:235], v[152:155], v[84:99]
	ds_read_b128 v[232:235], v229 offset:57344
	s_waitcnt lgkmcnt(0)
	v_mfma_f32_32x32x16_bf16 v[68:83], v[232:235], v[152:155], v[68:83]
	ds_read_b128 v[232:235], v230 offset:49152
	s_waitcnt lgkmcnt(0)
	v_mfma_f32_32x32x16_bf16 v[84:99], v[232:235], v[148:151], v[84:99]
	ds_read_b128 v[232:235], v230 offset:57344
	s_waitcnt lgkmcnt(0)
	v_mfma_f32_32x32x16_bf16 v[68:83], v[232:235], v[148:151], v[68:83]
	ds_read_b128 v[232:235], v227 offset:49280
	s_waitcnt lgkmcnt(0)
	v_mfma_f32_32x32x16_bf16 v[84:99], v[232:235], v[144:147], v[84:99]
	ds_read_b128 v[232:235], v227 offset:57472
	s_waitcnt lgkmcnt(0)
	v_mfma_f32_32x32x16_bf16 v[68:83], v[232:235], v[144:147], v[68:83]
	ds_read_b128 v[232:235], v228 offset:49280
	s_waitcnt lgkmcnt(0)
	v_mfma_f32_32x32x16_bf16 v[84:99], v[232:235], v[140:143], v[84:99]
	ds_read_b128 v[232:235], v228 offset:57472
	s_waitcnt lgkmcnt(0)
	v_mfma_f32_32x32x16_bf16 v[68:83], v[232:235], v[140:143], v[68:83]
	ds_read_b128 v[232:235], v229 offset:49280
	s_waitcnt lgkmcnt(0)
	v_mfma_f32_32x32x16_bf16 v[84:99], v[232:235], v[136:139], v[84:99]
	ds_read_b128 v[232:235], v229 offset:57472
	s_waitcnt lgkmcnt(0)
	v_mfma_f32_32x32x16_bf16 v[68:83], v[232:235], v[136:139], v[68:83]
	ds_read_b128 v[232:235], v230 offset:49280
	s_waitcnt lgkmcnt(0)
	v_mfma_f32_32x32x16_bf16 v[84:99], v[232:235], v[132:135], v[84:99]
	ds_read_b128 v[232:235], v230 offset:57472
	s_waitcnt lgkmcnt(0)
	v_mfma_f32_32x32x16_bf16 v[68:83], v[232:235], v[132:135], v[68:83]
	s_setprio 0

.LBB0_1448:
	s_and_b64 vcc, exec, s[48:49]
	s_cbranch_vccnz .LBB0_1450
	ds_read_b64_tr_b16 v[232:233], v216 offset:0
	ds_read_b64_tr_b16 v[234:235], v216 offset:0x800
	ds_read_b64_tr_b16 v[236:237], v216 offset:0x1000
	ds_read_b64_tr_b16 v[238:239], v216 offset:0x1800
	ds_read_b64_tr_b16 v[240:241], v216 offset:0x2000
	ds_read_b64_tr_b16 v[242:243], v216 offset:0x2800
	ds_read_b64_tr_b16 v[244:245], v216 offset:0x3000
	ds_read_b64_tr_b16 v[246:247], v216 offset:0x3800
	s_waitcnt lgkmcnt(0)
	s_waitcnt vmcnt(7)
	s_setprio 1
	v_mfma_f32_32x32x16_bf16 v[4:19], v[164:167], v[232:235], v[4:19]
	ds_read_b64_tr_b16 v[232:233], v216 offset:0x200
	ds_read_b64_tr_b16 v[234:235], v216 offset:0xa00
	s_waitcnt vmcnt(6)
	v_mfma_f32_32x32x16_bf16 v[4:19], v[168:171], v[236:239], v[4:19]
	ds_read_b64_tr_b16 v[236:237], v216 offset:0x1200
	ds_read_b64_tr_b16 v[238:239], v216 offset:0x1a00
	s_waitcnt vmcnt(5)
	v_mfma_f32_32x32x16_bf16 v[4:19], v[172:175], v[240:243], v[4:19]
	ds_read_b64_tr_b16 v[240:241], v216 offset:0x2200
	ds_read_b64_tr_b16 v[242:243], v216 offset:0x2a00
	s_waitcnt vmcnt(4)
	v_mfma_f32_32x32x16_bf16 v[4:19], v[176:179], v[244:247], v[4:19]
	ds_read_b64_tr_b16 v[244:245], v216 offset:0x3200
	ds_read_b64_tr_b16 v[246:247], v216 offset:0x3a00
	s_waitcnt lgkmcnt(0)
	v_mfma_f32_32x32x16_bf16 v[52:67], v[164:167], v[232:235], v[52:67]
	ds_read_b64_tr_b16 v[232:233], v216 offset:0x400
	ds_read_b64_tr_b16 v[234:235], v216 offset:0xc00
	v_mfma_f32_32x32x16_bf16 v[52:67], v[168:171], v[236:239], v[52:67]
	ds_read_b64_tr_b16 v[236:237], v216 offset:0x1400
	ds_read_b64_tr_b16 v[238:239], v216 offset:0x1c00
	v_mfma_f32_32x32x16_bf16 v[52:67], v[172:175], v[240:243], v[52:67]
	ds_read_b64_tr_b16 v[240:241], v216 offset:0x2400
	ds_read_b64_tr_b16 v[242:243], v216 offset:0x2c00
	v_mfma_f32_32x32x16_bf16 v[52:67], v[176:179], v[244:247], v[52:67]
	ds_read_b64_tr_b16 v[244:245], v216 offset:0x3400
	ds_read_b64_tr_b16 v[246:247], v216 offset:0x3c00
	s_waitcnt lgkmcnt(0)
	v_mfma_f32_32x32x16_bf16 v[36:51], v[164:167], v[232:235], v[36:51]
	ds_read_b64_tr_b16 v[232:233], v216 offset:0x600
	ds_read_b64_tr_b16 v[234:235], v216 offset:0xe00
	v_mfma_f32_32x32x16_bf16 v[36:51], v[168:171], v[236:239], v[36:51]
	ds_read_b64_tr_b16 v[236:237], v216 offset:0x1600
	ds_read_b64_tr_b16 v[238:239], v216 offset:0x1e00
	v_mfma_f32_32x32x16_bf16 v[36:51], v[172:175], v[240:243], v[36:51]
	ds_read_b64_tr_b16 v[240:241], v216 offset:0x2600
	ds_read_b64_tr_b16 v[242:243], v216 offset:0x2e00
	v_mfma_f32_32x32x16_bf16 v[36:51], v[176:179], v[244:247], v[36:51]
	ds_read_b64_tr_b16 v[244:245], v216 offset:0x3600
	ds_read_b64_tr_b16 v[246:247], v216 offset:0x3e00
	s_waitcnt lgkmcnt(0)
	v_mfma_f32_32x32x16_bf16 v[20:35], v[164:167], v[232:235], v[20:35]
	v_mfma_f32_32x32x16_bf16 v[20:35], v[168:171], v[236:239], v[20:35]
	v_mfma_f32_32x32x16_bf16 v[20:35], v[172:175], v[240:243], v[20:35]
	v_mfma_f32_32x32x16_bf16 v[20:35], v[176:179], v[244:247], v[20:35]
	s_setprio 0

.LBB0_1463:
	s_cmp_le_i32 s20, s55
	s_cselect_b64 s[84:85], -1, 0
	s_cmp_gt_i32 s20, s55
	s_cbranch_scc1 .LBB0_1465
	v_add_u32_e32 v100, 0x10500, v196
	v_add_u32_e32 v101, 0x10580, v196
	v_add_u32_e32 v104, 0x10520, v196
	ds_read_b128 v[116:119], v100
	ds_read_b128 v[100:103], v101
	ds_read_b128 v[120:123], v104
	ds_read_b128 v[108:111], v227 offset:32768
	v_add_u32_e32 v104, 0x10540, v196
	ds_read_b128 v[124:127], v104
	ds_read_b128 v[232:235], v227 offset:40960
	v_add_u32_e32 v104, 0x10560, v196
	ds_read_b128 v[128:131], v104
	v_add_u32_e32 v104, 0x105a0, v196
	v_add_u32_e32 v112, 0x105c0, v196
	ds_read_b128 v[104:107], v104
	s_waitcnt lgkmcnt(1)
	s_setprio 1
	v_mfma_f32_32x32x16_bf16 v[116:131], v[108:111], v[160:163], v[116:131]
	ds_read_b128 v[108:111], v112
	v_add_u32_e32 v112, 0x105e0, v196
	ds_read_b128 v[112:115], v112
	s_waitcnt lgkmcnt(0)
	v_mfma_f32_32x32x16_bf16 v[100:115], v[232:235], v[160:163], v[100:115]
	ds_read_b128 v[232:235], v228 offset:32768
	s_waitcnt lgkmcnt(0)
	v_mfma_f32_32x32x16_bf16 v[116:131], v[232:235], v[156:159], v[116:131]
	ds_read_b128 v[232:235], v228 offset:40960
	s_waitcnt lgkmcnt(0)
	v_mfma_f32_32x32x16_bf16 v[100:115], v[232:235], v[156:159], v[100:115]
	ds_read_b128 v[232:235], v229 offset:32768
	s_waitcnt lgkmcnt(0)
	v_mfma_f32_32x32x16_bf16 v[116:131], v[232:235], v[152:155], v[116:131]
	ds_read_b128 v[232:235], v229 offset:40960
	s_waitcnt lgkmcnt(0)
	v_mfma_f32_32x32x16_bf16 v[100:115], v[232:235], v[152:155], v[100:115]
	ds_read_b128 v[232:235], v230 offset:32768
	s_waitcnt lgkmcnt(0)
	v_mfma_f32_32x32x16_bf16 v[116:131], v[232:235], v[148:151], v[116:131]
	ds_read_b128 v[232:235], v230 offset:40960
	s_waitcnt lgkmcnt(0)
	v_mfma_f32_32x32x16_bf16 v[100:115], v[232:235], v[148:151], v[100:115]
	ds_read_b128 v[232:235], v227 offset:32896
	s_waitcnt lgkmcnt(0)
	v_mfma_f32_32x32x16_bf16 v[116:131], v[232:235], v[144:147], v[116:131]
	ds_read_b128 v[232:235], v227 offset:41088
	s_waitcnt lgkmcnt(0)
	v_mfma_f32_32x32x16_bf16 v[100:115], v[232:235], v[144:147], v[100:115]
	ds_read_b128 v[232:235], v228 offset:32896
	s_waitcnt lgkmcnt(0)
	v_mfma_f32_32x32x16_bf16 v[116:131], v[232:235], v[140:143], v[116:131]
	ds_read_b128 v[232:235], v228 offset:41088
	s_waitcnt lgkmcnt(0)
	v_mfma_f32_32x32x16_bf16 v[100:115], v[232:235], v[140:143], v[100:115]
	ds_read_b128 v[232:235], v229 offset:32896
	s_waitcnt lgkmcnt(0)
	v_mfma_f32_32x32x16_bf16 v[116:131], v[232:235], v[136:139], v[116:131]
	ds_read_b128 v[232:235], v229 offset:41088
	s_waitcnt lgkmcnt(0)
	v_mfma_f32_32x32x16_bf16 v[100:115], v[232:235], v[136:139], v[100:115]
	ds_read_b128 v[232:235], v230 offset:32896
	s_waitcnt lgkmcnt(0)
	v_mfma_f32_32x32x16_bf16 v[116:131], v[232:235], v[132:135], v[116:131]
	ds_read_b128 v[232:235], v230 offset:41088
	s_waitcnt lgkmcnt(0)
	v_mfma_f32_32x32x16_bf16 v[100:115], v[232:235], v[132:135], v[100:115]
	s_setprio 0

.LBB0_1467:
	s_and_b64 vcc, exec, s[48:49]
	s_cbranch_vccnz .LBB0_1469
	ds_read_b64_tr_b16 v[232:233], v216 offset:0x4000
	ds_read_b64_tr_b16 v[234:235], v216 offset:0x4800
	ds_read_b64_tr_b16 v[236:237], v216 offset:0x5000
	ds_read_b64_tr_b16 v[238:239], v216 offset:0x5800
	ds_read_b64_tr_b16 v[240:241], v216 offset:0x6000
	ds_read_b64_tr_b16 v[242:243], v216 offset:0x6800
	ds_read_b64_tr_b16 v[244:245], v216 offset:0x7000
	ds_read_b64_tr_b16 v[246:247], v216 offset:0x7800
	s_waitcnt lgkmcnt(0)
	s_nop 0
	s_setprio 1
	v_mfma_f32_32x32x16_bf16 v[4:19], v[164:167], v[232:235], v[4:19]
	ds_read_b64_tr_b16 v[232:233], v216 offset:0x4200
	ds_read_b64_tr_b16 v[234:235], v216 offset:0x4a00
	v_mfma_f32_32x32x16_bf16 v[4:19], v[168:171], v[236:239], v[4:19]
	ds_read_b64_tr_b16 v[236:237], v216 offset:0x5200
	ds_read_b64_tr_b16 v[238:239], v216 offset:0x5a00
	v_mfma_f32_32x32x16_bf16 v[4:19], v[172:175], v[240:243], v[4:19]
	ds_read_b64_tr_b16 v[240:241], v216 offset:0x6200
	ds_read_b64_tr_b16 v[242:243], v216 offset:0x6a00
	v_mfma_f32_32x32x16_bf16 v[4:19], v[176:179], v[244:247], v[4:19]
	ds_read_b64_tr_b16 v[244:245], v216 offset:0x7200
	ds_read_b64_tr_b16 v[246:247], v216 offset:0x7a00
	s_waitcnt lgkmcnt(0)
	v_mfma_f32_32x32x16_bf16 v[52:67], v[164:167], v[232:235], v[52:67]
	ds_read_b64_tr_b16 v[232:233], v216 offset:0x4400
	ds_read_b64_tr_b16 v[234:235], v216 offset:0x4c00
	v_mfma_f32_32x32x16_bf16 v[52:67], v[168:171], v[236:239], v[52:67]
	ds_read_b64_tr_b16 v[236:237], v216 offset:0x5400
	ds_read_b64_tr_b16 v[238:239], v216 offset:0x5c00
	v_mfma_f32_32x32x16_bf16 v[52:67], v[172:175], v[240:243], v[52:67]
	ds_read_b64_tr_b16 v[240:241], v216 offset:0x6400
	ds_read_b64_tr_b16 v[242:243], v216 offset:0x6c00
	v_mfma_f32_32x32x16_bf16 v[52:67], v[176:179], v[244:247], v[52:67]
	ds_read_b64_tr_b16 v[244:245], v216 offset:0x7400
	ds_read_b64_tr_b16 v[246:247], v216 offset:0x7c00
	s_waitcnt lgkmcnt(0)
	v_mfma_f32_32x32x16_bf16 v[36:51], v[164:167], v[232:235], v[36:51]
	ds_read_b64_tr_b16 v[232:233], v216 offset:0x4600
	ds_read_b64_tr_b16 v[234:235], v216 offset:0x4e00
	v_mfma_f32_32x32x16_bf16 v[36:51], v[168:171], v[236:239], v[36:51]
	ds_read_b64_tr_b16 v[236:237], v216 offset:0x5600
	ds_read_b64_tr_b16 v[238:239], v216 offset:0x5e00
	v_mfma_f32_32x32x16_bf16 v[36:51], v[172:175], v[240:243], v[36:51]
	ds_read_b64_tr_b16 v[240:241], v216 offset:0x6600
	ds_read_b64_tr_b16 v[242:243], v216 offset:0x6e00
	v_mfma_f32_32x32x16_bf16 v[36:51], v[176:179], v[244:247], v[36:51]
	ds_read_b64_tr_b16 v[244:245], v216 offset:0x7600
	ds_read_b64_tr_b16 v[246:247], v216 offset:0x7e00
	s_waitcnt lgkmcnt(0)
	v_mfma_f32_32x32x16_bf16 v[20:35], v[164:167], v[232:235], v[20:35]
	v_mfma_f32_32x32x16_bf16 v[20:35], v[168:171], v[236:239], v[20:35]
	v_mfma_f32_32x32x16_bf16 v[20:35], v[172:175], v[240:243], v[20:35]
	v_mfma_f32_32x32x16_bf16 v[20:35], v[176:179], v[244:247], v[20:35]
	s_setprio 0

.LBB0_1494:
	s_and_b32 s5, s96, 1
	s_cmp_eq_u32 s5, 0
	s_cselect_b64 s[42:43], -1, 0
	s_cmp_eq_u32 s5, 1
	s_cselect_b64 s[20:21], -1, 0
	s_and_b64 vcc, exec, s[20:21]
	s_cbranch_vccnz .LBB0_1498
	s_sub_i32 s5, s9, s96
	s_lshl_b32 s6, s5, 6
	s_cmp_le_i32 s6, s55
	s_cselect_b64 s[0:1], -1, 0
	s_cmp_gt_i32 s6, s55
	s_cbranch_scc1 .LBB0_1497
	v_lshl_add_u32 v2, s5, 8, v221
	s_waitcnt vmcnt(2)
	v_lshlrev_b32_e32 v169, 4, v199
	s_movk_i32 s5, 0x70
	v_lshlrev_b32_e32 v168, 8, v199
	v_bitop3_b32 v68, v204, v169, s5 bitop3:0x78
	v_add3_u32 v170, 0, v68, v168
	ds_read_b128 v[72:75], v170 offset:49152
	ds_read_b128 v[84:87], v2
	ds_read_b128 v[88:91], v2 offset:32
	ds_read_b128 v[92:95], v2 offset:64
	ds_read_b128 v[96:99], v2 offset:96
	ds_read_b128 v[68:71], v2 offset:128
	ds_read_b128 v[164:167], v170 offset:57344
	s_waitcnt lgkmcnt(2)
	s_setprio 1
	v_mfma_f32_32x32x16_bf16 v[84:99], v[72:75], v[160:163], v[84:99]
	ds_read_b128 v[72:75], v2 offset:160
	ds_read_b128 v[76:79], v2 offset:192
	ds_read_b128 v[80:83], v2 offset:224
	v_and_b32_e32 v2, 0x70, v169
	v_bitop3_b32 v169, v204, v2, 32 bitop3:0x36
	v_add3_u32 v169, 0, v169, v168
	s_movk_i32 s5, 0x60
	s_waitcnt lgkmcnt(0)
	v_mfma_f32_32x32x16_bf16 v[68:83], v[164:167], v[160:163], v[68:83]
	ds_read_b128 v[160:163], v169 offset:49152
	v_bitop3_b32 v164, v204, v2, 64 bitop3:0x36
	v_add3_u32 v164, 0, v164, v168
	v_bitop3_b32 v2, v204, v2, s5 bitop3:0x36
	v_add3_u32 v2, 0, v2, v168
	s_waitcnt lgkmcnt(0)
	v_mfma_f32_32x32x16_bf16 v[84:99], v[160:163], v[156:159], v[84:99]
	ds_read_b128 v[160:163], v169 offset:57344
	s_waitcnt lgkmcnt(0)
	v_mfma_f32_32x32x16_bf16 v[68:83], v[160:163], v[156:159], v[68:83]
	ds_read_b128 v[156:159], v164 offset:49152
	s_waitcnt lgkmcnt(0)
	v_mfma_f32_32x32x16_bf16 v[84:99], v[156:159], v[152:155], v[84:99]
	ds_read_b128 v[156:159], v164 offset:57344
	s_waitcnt lgkmcnt(0)
	v_mfma_f32_32x32x16_bf16 v[68:83], v[156:159], v[152:155], v[68:83]
	ds_read_b128 v[152:155], v2 offset:49152
	s_waitcnt lgkmcnt(0)
	v_mfma_f32_32x32x16_bf16 v[84:99], v[152:155], v[148:151], v[84:99]
	ds_read_b128 v[152:155], v2 offset:57344
	s_waitcnt lgkmcnt(0)
	v_mfma_f32_32x32x16_bf16 v[68:83], v[152:155], v[148:151], v[68:83]
	ds_read_b128 v[148:151], v170 offset:49280
	s_waitcnt lgkmcnt(0)
	v_mfma_f32_32x32x16_bf16 v[84:99], v[148:151], v[144:147], v[84:99]
	ds_read_b128 v[148:151], v170 offset:57472
	s_waitcnt lgkmcnt(0)
	v_mfma_f32_32x32x16_bf16 v[68:83], v[148:151], v[144:147], v[68:83]
	ds_read_b128 v[144:147], v169 offset:49280
	s_waitcnt lgkmcnt(0)
	v_mfma_f32_32x32x16_bf16 v[84:99], v[144:147], v[140:143], v[84:99]
	ds_read_b128 v[144:147], v169 offset:57472
	s_waitcnt lgkmcnt(0)
	v_mfma_f32_32x32x16_bf16 v[68:83], v[144:147], v[140:143], v[68:83]
	ds_read_b128 v[140:143], v164 offset:49280
	s_waitcnt lgkmcnt(0)
	v_mfma_f32_32x32x16_bf16 v[84:99], v[140:143], v[136:139], v[84:99]
	ds_read_b128 v[140:143], v164 offset:57472
	s_waitcnt lgkmcnt(0)
	v_mfma_f32_32x32x16_bf16 v[68:83], v[140:143], v[136:139], v[68:83]
	ds_read_b128 v[136:139], v2 offset:49280
	s_waitcnt lgkmcnt(0)
	v_mfma_f32_32x32x16_bf16 v[84:99], v[136:139], v[132:135], v[84:99]
	ds_read_b128 v[136:139], v2 offset:57472
	s_waitcnt lgkmcnt(0)
	v_mfma_f32_32x32x16_bf16 v[68:83], v[136:139], v[132:135], v[68:83]
	s_setprio 0
.LBB0_1497:
.LBB0_1498:
	s_add_i32 s5, s17, 0xff
	s_ashr_i32 s6, s5, 31
	s_lshr_b32 s6, s6, 26
	s_add_i32 s5, s5, s6
	s_ashr_i32 s5, s5, 6
	s_add_i32 s5, s5, 1
	s_lshr_b32 s6, s16, 6
	s_min_i32 s5, s5, s6
	s_lshl_b32 s5, s5, 6
	s_sub_i32 s5, s5, 64
	v_mad_u64_u32 v[132:133], s[20:21], v205, s40, v[200:201]
	s_ashr_i32 s6, s5, 31
	s_mul_i32 s6, s6, s40
	s_mul_hi_u32 s20, s5, s40
	s_add_i32 s21, s20, s6
	s_mul_i32 s20, s5, s40
	s_lshl_b64 s[20:21], s[20:21], 1
	s_add_u32 s44, s36, s20
	s_addc_u32 s45, s37, s21
	s_lshl_b32 s5, s40, 5
	s_add_u32 s20, s80, s20
	v_lshlrev_b32_e32 v2, 1, v132
	v_add_lshl_u32 v132, v132, s5, 1
	s_addc_u32 s21, s81, s21
	global_load_dwordx4 v[164:167], v2, s[44:45]
	global_load_dwordx4 v[168:171], v132, s[44:45]
	global_load_dwordx4 v[172:175], v2, s[20:21]
	global_load_dwordx4 v[176:179], v132, s[20:21]
	s_add_i32 s5, s78, -1
	v_mov_b32_e32 v2, s5
	v_bitop3_b32 v2, s59, v2, v199 bitop3:0xc8
	v_mad_u64_u32 v[132:133], s[20:21], v2, s95, 0
	v_lshl_add_u64 v[132:133], v[132:133], 1, s[26:27]
	v_mov_b32_e32 v205, v3
	v_lshl_add_u64 v[132:133], v[132:133], 0, v[204:205]
	global_load_dwordx4 v[160:163], v[132:133], off
	global_load_dwordx4 v[156:159], v[132:133], off offset:32
	global_load_dwordx4 v[152:155], v[132:133], off offset:64
	global_load_dwordx4 v[148:151], v[132:133], off offset:96
	global_load_dwordx4 v[144:147], v[132:133], off offset:128
	global_load_dwordx4 v[140:143], v[132:133], off offset:160
	global_load_dwordx4 v[136:139], v[132:133], off offset:192
	s_nop 0
	global_load_dwordx4 v[132:135], v[132:133], off offset:224
	s_andn2_b64 vcc, exec, s[84:85]
	s_cbranch_vccnz .LBB0_1500
	v_exp_f32_e32 v2, v100
	v_add_f32_e32 v100, 0, v116
	v_add_f32_e32 v100, v117, v100
	v_add_f32_e32 v100, v118, v100
	v_add_f32_e32 v100, v119, v100
	v_add_f32_e32 v100, v120, v100
	v_add_f32_e32 v100, v121, v100
	v_add_f32_e32 v100, v122, v100
	v_add_f32_e32 v100, v123, v100
	v_add_f32_e32 v100, v124, v100
	v_add_f32_e32 v100, v125, v100
	v_add_f32_e32 v100, v126, v100
	v_add_f32_e32 v100, v127, v100
	v_add_f32_e32 v100, v128, v100
	s_waitcnt vmcnt(15)
	v_exp_f32_e32 v180, v101
	v_add_f32_e32 v100, v129, v100
	v_exp_f32_e32 v181, v102
	v_add_f32_e32 v100, v130, v100
	v_exp_f32_e32 v182, v103
	v_add_f32_e32 v100, v131, v100
	v_exp_f32_e32 v183, v104
	v_add_f32_e32 v100, v2, v100
	s_waitcnt vmcnt(14)
	v_exp_f32_e32 v184, v105
	v_add_f32_e32 v100, v180, v100
	v_exp_f32_e32 v185, v106
	v_add_f32_e32 v100, v181, v100
	v_exp_f32_e32 v186, v107
	v_add_f32_e32 v100, v182, v100
	v_exp_f32_e32 v187, v108
	v_add_f32_e32 v100, v183, v100
	s_waitcnt vmcnt(13)
	v_exp_f32_e32 v188, v109
	v_add_f32_e32 v100, v184, v100
	v_exp_f32_e32 v189, v110
	v_add_f32_e32 v100, v185, v100
	v_exp_f32_e32 v190, v111
	v_add_f32_e32 v100, v186, v100
	v_exp_f32_e32 v191, v112
	v_add_f32_e32 v100, v187, v100
	s_waitcnt vmcnt(12)
	v_exp_f32_e32 v192, v113
	v_add_f32_e32 v100, v188, v100
	v_exp_f32_e32 v193, v114
	v_add_f32_e32 v100, v189, v100
	v_exp_f32_e32 v115, v115
	v_add_f32_e32 v100, v190, v100
	v_add_f32_e32 v100, v191, v100
	v_add_f32_e32 v100, v192, v100
	v_add_f32_e32 v100, v193, v100
	v_add_f32_e32 v100, v115, v100
	v_mov_b32_e32 v101, v100
	s_nop 1
	v_permlane32_swap_b32_e32 v100, v101
	v_add_f32_e32 v194, v100, v101
	v_cvt_pk_bf16_f32 v100, v116, v117
	v_cvt_pk_bf16_f32 v101, v118, v119
	v_cvt_pk_bf16_f32 v102, v120, v121
	v_cvt_pk_bf16_f32 v103, v122, v123
	v_cvt_pk_bf16_f32 v104, v124, v125
	v_cvt_pk_bf16_f32 v105, v126, v127
	v_cvt_pk_bf16_f32 v106, v128, v129
	v_cvt_pk_bf16_f32 v107, v130, v131
	v_cvt_pk_bf16_f32 v108, v2, v180
	v_cvt_pk_bf16_f32 v109, v181, v182
	v_cvt_pk_bf16_f32 v110, v183, v184
	v_cvt_pk_bf16_f32 v111, v185, v186
	v_cvt_pk_bf16_f32 v112, v187, v188
	v_cvt_pk_bf16_f32 v113, v189, v190
	v_cvt_pk_bf16_f32 v114, v191, v192
	v_cvt_pk_bf16_f32 v115, v193, v115
	v_fmac_f32_e32 v194, v219, v224
	v_permlane32_swap_b32_e32 v100, v102
	v_permlane32_swap_b32_e32 v101, v103
	v_permlane32_swap_b32_e32 v104, v106
	v_permlane32_swap_b32_e32 v105, v107
	v_permlane32_swap_b32_e32 v108, v110
	v_permlane32_swap_b32_e32 v109, v111
	v_permlane32_swap_b32_e32 v112, v114
	v_permlane32_swap_b32_e32 v113, v115
	ds_read_b64_tr_b16 v[116:117], v216 offset:0
	ds_read_b64_tr_b16 v[118:119], v216 offset:0x800
	ds_read_b64_tr_b16 v[120:121], v216 offset:0x1000
	ds_read_b64_tr_b16 v[122:123], v216 offset:0x1800
	ds_read_b64_tr_b16 v[124:125], v216 offset:0x2000
	ds_read_b64_tr_b16 v[126:127], v216 offset:0x2800
	ds_read_b64_tr_b16 v[128:129], v216 offset:0x3000
	ds_read_b64_tr_b16 v[130:131], v216 offset:0x3800
	s_waitcnt lgkmcnt(0)
	s_nop 0
	s_setprio 1
	v_mfma_f32_32x32x16_bf16 v[4:19], v[100:103], v[116:119], v[4:19]
	ds_read_b64_tr_b16 v[116:117], v216 offset:0x200
	ds_read_b64_tr_b16 v[118:119], v216 offset:0xa00
	v_mfma_f32_32x32x16_bf16 v[4:19], v[104:107], v[120:123], v[4:19]
	ds_read_b64_tr_b16 v[120:121], v216 offset:0x1200
	ds_read_b64_tr_b16 v[122:123], v216 offset:0x1a00
	v_mfma_f32_32x32x16_bf16 v[4:19], v[108:111], v[124:127], v[4:19]
	ds_read_b64_tr_b16 v[124:125], v216 offset:0x2200
	ds_read_b64_tr_b16 v[126:127], v216 offset:0x2a00
	v_mfma_f32_32x32x16_bf16 v[4:19], v[112:115], v[128:131], v[4:19]
	ds_read_b64_tr_b16 v[128:129], v216 offset:0x3200
	ds_read_b64_tr_b16 v[130:131], v216 offset:0x3a00
	s_waitcnt lgkmcnt(0)
	v_mfma_f32_32x32x16_bf16 v[52:67], v[100:103], v[116:119], v[52:67]
	ds_read_b64_tr_b16 v[116:117], v216 offset:0x400
	ds_read_b64_tr_b16 v[118:119], v216 offset:0xc00
	v_mfma_f32_32x32x16_bf16 v[52:67], v[104:107], v[120:123], v[52:67]
	ds_read_b64_tr_b16 v[120:121], v216 offset:0x1400
	ds_read_b64_tr_b16 v[122:123], v216 offset:0x1c00
	v_mfma_f32_32x32x16_bf16 v[52:67], v[108:111], v[124:127], v[52:67]
	ds_read_b64_tr_b16 v[124:125], v216 offset:0x2400
	ds_read_b64_tr_b16 v[126:127], v216 offset:0x2c00
	v_mfma_f32_32x32x16_bf16 v[52:67], v[112:115], v[128:131], v[52:67]
	ds_read_b64_tr_b16 v[128:129], v216 offset:0x3400
	ds_read_b64_tr_b16 v[130:131], v216 offset:0x3c00
	s_waitcnt lgkmcnt(0)
	v_mfma_f32_32x32x16_bf16 v[36:51], v[100:103], v[116:119], v[36:51]
	ds_read_b64_tr_b16 v[116:117], v216 offset:0x600
	ds_read_b64_tr_b16 v[118:119], v216 offset:0xe00
	v_mfma_f32_32x32x16_bf16 v[36:51], v[104:107], v[120:123], v[36:51]
	ds_read_b64_tr_b16 v[120:121], v216 offset:0x1600
	ds_read_b64_tr_b16 v[122:123], v216 offset:0x1e00
	v_mfma_f32_32x32x16_bf16 v[36:51], v[108:111], v[124:127], v[36:51]
	ds_read_b64_tr_b16 v[124:125], v216 offset:0x2600
	ds_read_b64_tr_b16 v[126:127], v216 offset:0x2e00
	v_mfma_f32_32x32x16_bf16 v[36:51], v[112:115], v[128:131], v[36:51]
	ds_read_b64_tr_b16 v[128:129], v216 offset:0x3600
	ds_read_b64_tr_b16 v[130:131], v216 offset:0x3e00
	s_waitcnt lgkmcnt(0)
	v_mfma_f32_32x32x16_bf16 v[20:35], v[100:103], v[116:119], v[20:35]
	v_mov_b32_e32 v219, v194
	v_mfma_f32_32x32x16_bf16 v[20:35], v[104:107], v[120:123], v[20:35]
	v_mfma_f32_32x32x16_bf16 v[20:35], v[108:111], v[124:127], v[20:35]
	v_mfma_f32_32x32x16_bf16 v[20:35], v[112:115], v[128:131], v[20:35]
	s_setprio 0

.LBB0_1512:
	v_exp_f32_e32 v2, v68
	v_add_f32_e32 v68, 0, v84
	v_add_f32_e32 v68, v85, v68
	v_add_f32_e32 v68, v86, v68
	v_add_f32_e32 v68, v87, v68
	v_add_f32_e32 v68, v88, v68
	v_add_f32_e32 v68, v89, v68
	v_add_f32_e32 v68, v90, v68
	v_add_f32_e32 v68, v91, v68
	v_add_f32_e32 v68, v92, v68
	v_add_f32_e32 v68, v93, v68
	v_add_f32_e32 v68, v94, v68
	v_add_f32_e32 v68, v95, v68
	v_add_f32_e32 v68, v96, v68
	v_exp_f32_e32 v100, v69
	v_add_f32_e32 v68, v97, v68
	v_exp_f32_e32 v101, v70
	v_add_f32_e32 v68, v98, v68
	v_exp_f32_e32 v102, v71
	v_add_f32_e32 v68, v99, v68
	v_exp_f32_e32 v103, v72
	v_add_f32_e32 v68, v2, v68
	v_exp_f32_e32 v104, v73
	v_add_f32_e32 v68, v100, v68
	v_exp_f32_e32 v105, v74
	v_add_f32_e32 v68, v101, v68
	v_exp_f32_e32 v106, v75
	v_add_f32_e32 v68, v102, v68
	v_exp_f32_e32 v107, v76
	v_add_f32_e32 v68, v103, v68
	v_exp_f32_e32 v108, v77
	v_add_f32_e32 v68, v104, v68
	v_exp_f32_e32 v109, v78
	v_add_f32_e32 v68, v105, v68
	v_exp_f32_e32 v110, v79
	v_add_f32_e32 v68, v106, v68
	v_exp_f32_e32 v111, v80
	v_add_f32_e32 v68, v107, v68
	v_exp_f32_e32 v112, v81
	v_add_f32_e32 v68, v108, v68
	v_exp_f32_e32 v113, v82
	v_add_f32_e32 v68, v109, v68
	v_exp_f32_e32 v83, v83
	v_add_f32_e32 v68, v110, v68
	v_add_f32_e32 v68, v111, v68
	v_add_f32_e32 v68, v112, v68
	v_add_f32_e32 v68, v113, v68
	v_add_f32_e32 v68, v83, v68
	v_mov_b32_e32 v69, v68
	s_nop 1
	v_permlane32_swap_b32_e32 v68, v69
	v_add_f32_e32 v114, v68, v69
	v_cvt_pk_bf16_f32 v68, v84, v85
	v_cvt_pk_bf16_f32 v69, v86, v87
	v_cvt_pk_bf16_f32 v70, v88, v89
	v_cvt_pk_bf16_f32 v71, v90, v91
	v_cvt_pk_bf16_f32 v72, v92, v93
	v_cvt_pk_bf16_f32 v73, v94, v95
	v_cvt_pk_bf16_f32 v74, v96, v97
	v_cvt_pk_bf16_f32 v75, v98, v99
	v_cvt_pk_bf16_f32 v76, v2, v100
	v_cvt_pk_bf16_f32 v77, v101, v102
	v_cvt_pk_bf16_f32 v78, v103, v104
	v_cvt_pk_bf16_f32 v79, v105, v106
	v_cvt_pk_bf16_f32 v80, v107, v108
	v_cvt_pk_bf16_f32 v81, v109, v110
	v_cvt_pk_bf16_f32 v82, v111, v112
	v_cvt_pk_bf16_f32 v83, v113, v83
	v_fmac_f32_e32 v114, v219, v220
	v_permlane32_swap_b32_e32 v68, v70
	v_permlane32_swap_b32_e32 v69, v71
	v_permlane32_swap_b32_e32 v72, v74
	v_permlane32_swap_b32_e32 v73, v75
	v_permlane32_swap_b32_e32 v76, v78
	v_permlane32_swap_b32_e32 v77, v79
	v_permlane32_swap_b32_e32 v80, v82
	v_permlane32_swap_b32_e32 v81, v83
	ds_read_b64_tr_b16 v[84:85], v216 offset:0x4000
	ds_read_b64_tr_b16 v[86:87], v216 offset:0x4800
	ds_read_b64_tr_b16 v[88:89], v216 offset:0x5000
	ds_read_b64_tr_b16 v[90:91], v216 offset:0x5800
	ds_read_b64_tr_b16 v[92:93], v216 offset:0x6000
	ds_read_b64_tr_b16 v[94:95], v216 offset:0x6800
	ds_read_b64_tr_b16 v[96:97], v216 offset:0x7000
	ds_read_b64_tr_b16 v[98:99], v216 offset:0x7800
	s_waitcnt lgkmcnt(0)
	s_nop 0
	s_setprio 1
	v_mfma_f32_32x32x16_bf16 v[4:19], v[68:71], v[84:87], v[4:19]
	ds_read_b64_tr_b16 v[84:85], v216 offset:0x4200
	ds_read_b64_tr_b16 v[86:87], v216 offset:0x4a00
	v_mfma_f32_32x32x16_bf16 v[4:19], v[72:75], v[88:91], v[4:19]
	ds_read_b64_tr_b16 v[88:89], v216 offset:0x5200
	ds_read_b64_tr_b16 v[90:91], v216 offset:0x5a00
	v_mfma_f32_32x32x16_bf16 v[4:19], v[76:79], v[92:95], v[4:19]
	ds_read_b64_tr_b16 v[92:93], v216 offset:0x6200
	ds_read_b64_tr_b16 v[94:95], v216 offset:0x6a00
	v_mfma_f32_32x32x16_bf16 v[4:19], v[80:83], v[96:99], v[4:19]
	ds_read_b64_tr_b16 v[96:97], v216 offset:0x7200
	ds_read_b64_tr_b16 v[98:99], v216 offset:0x7a00
	s_waitcnt lgkmcnt(0)
	v_mfma_f32_32x32x16_bf16 v[52:67], v[68:71], v[84:87], v[52:67]
	ds_read_b64_tr_b16 v[84:85], v216 offset:0x4400
	ds_read_b64_tr_b16 v[86:87], v216 offset:0x4c00
	v_mfma_f32_32x32x16_bf16 v[52:67], v[72:75], v[88:91], v[52:67]
	ds_read_b64_tr_b16 v[88:89], v216 offset:0x5400
	ds_read_b64_tr_b16 v[90:91], v216 offset:0x5c00
	v_mfma_f32_32x32x16_bf16 v[52:67], v[76:79], v[92:95], v[52:67]
	ds_read_b64_tr_b16 v[92:93], v216 offset:0x6400
	ds_read_b64_tr_b16 v[94:95], v216 offset:0x6c00
	v_mfma_f32_32x32x16_bf16 v[52:67], v[80:83], v[96:99], v[52:67]
	ds_read_b64_tr_b16 v[96:97], v216 offset:0x7400
	ds_read_b64_tr_b16 v[98:99], v216 offset:0x7c00
	s_waitcnt lgkmcnt(0)
	v_mfma_f32_32x32x16_bf16 v[36:51], v[68:71], v[84:87], v[36:51]
	ds_read_b64_tr_b16 v[84:85], v216 offset:0x4600
	ds_read_b64_tr_b16 v[86:87], v216 offset:0x4e00
	v_mfma_f32_32x32x16_bf16 v[36:51], v[72:75], v[88:91], v[36:51]
	ds_read_b64_tr_b16 v[88:89], v216 offset:0x5600
	ds_read_b64_tr_b16 v[90:91], v216 offset:0x5e00
	v_mfma_f32_32x32x16_bf16 v[36:51], v[76:79], v[92:95], v[36:51]
	ds_read_b64_tr_b16 v[92:93], v216 offset:0x6600
	ds_read_b64_tr_b16 v[94:95], v216 offset:0x6e00
	v_mfma_f32_32x32x16_bf16 v[36:51], v[80:83], v[96:99], v[36:51]
	ds_read_b64_tr_b16 v[96:97], v216 offset:0x7600
	ds_read_b64_tr_b16 v[98:99], v216 offset:0x7e00
	s_waitcnt lgkmcnt(0)
	v_mfma_f32_32x32x16_bf16 v[20:35], v[68:71], v[84:87], v[20:35]
	v_mov_b32_e32 v219, v114
	v_mfma_f32_32x32x16_bf16 v[20:35], v[72:75], v[88:91], v[20:35]
	v_mfma_f32_32x32x16_bf16 v[20:35], v[76:79], v[92:95], v[20:35]
	v_mfma_f32_32x32x16_bf16 v[20:35], v[80:83], v[96:99], v[20:35]
	s_setprio 0
